# attention softmax max tree: 11 ops (6 self-max canonicalisations) -> 3 v_max3 + 1 v_max per query block, MFMA distances re-padded
# speedup vs baseline: 1.0040x; 1.0040x over previous
.LBB0_266:
	ds_read_b128 v[48:51], v161 offset:20480
	v_lshl_add_u64 v[34:35], s[26:27], 0, v[162:163]
	s_mov_b32 s0, 0x12708000
	v_add_co_u32_e32 v38, vcc, s0, v34
	s_mov_b32 s0, 0x1270c000
	s_nop 0
	v_addc_co_u32_e32 v39, vcc, 0, v35, vcc
	global_load_dwordx4 v[64:67], v[38:39], off
	global_load_dwordx4 v[60:63], v[38:39], off offset:1024
	ds_read_b128 v[156:159], v161 offset:21504
	s_waitcnt vmcnt(9) lgkmcnt(1)
	v_mfma_f32_16x16x32_bf16 v[38:41], v[24:27], v[48:51], 0
	v_add_co_u32_e32 v34, vcc, s0, v34
	v_lshl_add_u64 v[52:53], s[24:25], 0, v[162:163]
	s_nop 0
	v_addc_co_u32_e32 v35, vcc, 0, v35, vcc
	s_waitcnt vmcnt(8) lgkmcnt(0)
	v_mfma_f32_16x16x32_bf16 v[152:155], v[16:19], v[156:159], v[38:41]
	global_load_dwordx4 v[68:71], v[34:35], off
	global_load_dwordx4 v[56:59], v[34:35], off offset:1024
	s_nop 0
	global_load_dwordx4 v[40:43], v[52:53], off offset:-2048
	global_load_dwordx4 v[44:47], v[52:53], off offset:-1024
	s_nop 2
	s_waitcnt vmcnt(11)
	v_mfma_f32_16x16x32_bf16 v[172:175], v[28:31], v[48:51], 0
	global_load_dwordx4 v[48:51], v[52:53], off
	s_nop 0
	global_load_dwordx4 v[52:55], v[52:53], off offset:1024
	s_waitcnt vmcnt(12)
	v_mfma_f32_16x16x32_bf16 v[156:159], v[20:23], v[156:159], v[172:175]
	s_nop 4
	v_max3_f32 v32, v152, v153, v154
	s_nop 1
	v_max3_f32 v35, v155, v156, v157
	v_max3_f32 v32, v32, v158, v159
	v_max_f32_e32 v32, v32, v35
	v_add_f32_e32 v34, 0x41000000, v171
	v_cmp_gt_f32_e32 vcc, v32, v34
	s_cbranch_vccz .LBB0_268
	v_mov_b32_e32 v34, v32
	s_nop 1
	v_permlane16_swap_b32 v32, v34
	s_nop 0
	v_max_f32_e32 v34, v34, v34
	v_max_f32_e32 v32, v32, v32
	v_max_f32_e32 v32, v32, v34
	v_mov_b32_e32 v34, v32
	s_nop 1
	v_permlane32_swap_b32 v32, v34
	s_nop 0
	v_max3_f32 v34, v171, v32, v34
	v_sub_f32_e32 v32, v171, v34
	v_exp_f32_e32 v32, v32
	v_mov_b32_e32 v171, v34
	v_pk_mul_f32 v[146:147], v[146:147], v[32:33] op_sel_hi:[1,0]
	v_pk_mul_f32 v[144:145], v[144:145], v[32:33] op_sel_hi:[1,0]
	v_pk_mul_f32 v[142:143], v[142:143], v[32:33] op_sel_hi:[1,0]
	v_pk_mul_f32 v[140:141], v[140:141], v[32:33] op_sel_hi:[1,0]
	v_pk_mul_f32 v[138:139], v[138:139], v[32:33] op_sel_hi:[1,0]
	v_pk_mul_f32 v[136:137], v[136:137], v[32:33] op_sel_hi:[1,0]
	v_pk_mul_f32 v[134:135], v[134:135], v[32:33] op_sel_hi:[1,0]
	v_pk_mul_f32 v[132:133], v[132:133], v[32:33] op_sel_hi:[1,0]
	v_pk_mul_f32 v[150:151], v[150:151], v[32:33] op_sel_hi:[1,0]
	v_pk_mul_f32 v[148:149], v[148:149], v[32:33] op_sel_hi:[1,0]
.LBB0_268:
	v_sub_f32_e32 v35, v154, v171
	v_sub_f32_e32 v37, v155, v171
	v_sub_f32_e32 v38, v156, v171
	v_sub_f32_e32 v39, v157, v171
	v_exp_f32_e32 v35, v35
	v_exp_f32_e32 v37, v37
	v_exp_f32_e32 v38, v38
	v_exp_f32_e32 v39, v39
	v_sub_f32_e32 v32, v152, v171
	v_sub_f32_e32 v152, v158, v171
	v_sub_f32_e32 v34, v153, v171
	v_exp_f32_e32 v155, v152
	v_sub_f32_e32 v152, v159, v171
	v_exp_f32_e32 v32, v32
	v_exp_f32_e32 v34, v34
	v_exp_f32_e32 v156, v152
	v_cvt_pk_bf16_f32 v153, v35, v37
	v_cvt_pk_bf16_f32 v154, v38, v39
	v_mov_b32_e32 v37, v36
	v_mov_b32_e32 v38, v36
	v_mov_b32_e32 v39, v36
	v_cvt_pk_bf16_f32 v152, v32, v34
	v_cvt_pk_bf16_f32 v155, v155, v156
	s_waitcnt vmcnt(11)
	s_nop 0
	v_mfma_f32_16x16x32_bf16 v[144:147], v[0:3], v[152:155], v[144:147]
	s_waitcnt vmcnt(10)
	v_mfma_f32_16x16x32_bf16 v[140:143], v[4:7], v[152:155], v[140:143]
	s_waitcnt vmcnt(9)
	v_mfma_f32_16x16x32_bf16 v[136:139], v[8:11], v[152:155], v[136:139]
	s_waitcnt vmcnt(8)
	v_mfma_f32_16x16x32_bf16 v[132:135], v[12:15], v[152:155], v[132:135]
	v_mfma_f32_16x16x32_bf16 v[148:151], v[36:39], v[152:155], v[148:151]
	ds_read_b128 v[152:155], v161 offset:22528
	ds_read_b128 v[172:175], v161 offset:23552
	s_waitcnt lgkmcnt(1)
	v_mfma_f32_16x16x32_bf16 v[156:159], v[24:27], v[152:155], 0
	v_mfma_f32_16x16x32_bf16 v[152:155], v[28:31], v[152:155], 0
	s_waitcnt lgkmcnt(0)
	v_mfma_f32_16x16x32_bf16 v[156:159], v[16:19], v[172:175], v[156:159]
	v_mfma_f32_16x16x32_bf16 v[152:155], v[20:23], v[172:175], v[152:155]
	s_nop 6
	v_max3_f32 v32, v156, v157, v158
	v_max3_f32 v35, v159, v152, v153
	v_max3_f32 v32, v32, v154, v155
	v_max_f32_e32 v32, v32, v35
	v_add_f32_e32 v34, 0x41000000, v170
	v_cmp_gt_f32_e32 vcc, v32, v34
	s_cbranch_vccz .LBB0_270
	v_mov_b32_e32 v34, v32
	s_nop 1
	v_permlane16_swap_b32 v32, v34
	s_nop 0
	v_max_f32_e32 v34, v34, v34
	v_max_f32_e32 v32, v32, v32
	v_max_f32_e32 v32, v32, v34
	v_mov_b32_e32 v34, v32
	s_nop 1
	v_permlane32_swap_b32 v32, v34
	s_nop 0
	v_max3_f32 v34, v170, v32, v34
	v_sub_f32_e32 v32, v170, v34
	v_exp_f32_e32 v32, v32
	v_mov_b32_e32 v170, v34
	v_pk_mul_f32 v[126:127], v[126:127], v[32:33] op_sel_hi:[1,0]
	v_pk_mul_f32 v[124:125], v[124:125], v[32:33] op_sel_hi:[1,0]
	v_pk_mul_f32 v[122:123], v[122:123], v[32:33] op_sel_hi:[1,0]
	v_pk_mul_f32 v[120:121], v[120:121], v[32:33] op_sel_hi:[1,0]
	v_pk_mul_f32 v[118:119], v[118:119], v[32:33] op_sel_hi:[1,0]
	v_pk_mul_f32 v[116:117], v[116:117], v[32:33] op_sel_hi:[1,0]
	v_pk_mul_f32 v[114:115], v[114:115], v[32:33] op_sel_hi:[1,0]
	v_pk_mul_f32 v[112:113], v[112:113], v[32:33] op_sel_hi:[1,0]
	v_pk_mul_f32 v[130:131], v[130:131], v[32:33] op_sel_hi:[1,0]
	v_pk_mul_f32 v[128:129], v[128:129], v[32:33] op_sel_hi:[1,0]
.LBB0_270:
	v_sub_f32_e32 v152, v152, v170
	v_sub_f32_e32 v34, v157, v170
	v_exp_f32_e32 v157, v152
	v_sub_f32_e32 v152, v153, v170
	v_sub_f32_e32 v35, v158, v170
	v_exp_f32_e32 v158, v152
	v_sub_f32_e32 v152, v154, v170
	v_sub_f32_e32 v32, v156, v170
	v_sub_f32_e32 v156, v159, v170
	v_exp_f32_e32 v159, v152
	v_sub_f32_e32 v152, v155, v170
	v_exp_f32_e32 v32, v32
	v_exp_f32_e32 v34, v34
	v_exp_f32_e32 v35, v35
	v_exp_f32_e32 v156, v156
	v_exp_f32_e32 v155, v152
	v_cvt_pk_bf16_f32 v152, v32, v34
	v_cvt_pk_bf16_f32 v154, v157, v158
	v_cvt_pk_bf16_f32 v153, v35, v156
	v_cvt_pk_bf16_f32 v155, v159, v155
	s_nop 1
	v_mfma_f32_16x16x32_bf16 v[124:127], v[0:3], v[152:155], v[124:127]
	v_mfma_f32_16x16x32_bf16 v[120:123], v[4:7], v[152:155], v[120:123]
	v_mfma_f32_16x16x32_bf16 v[116:119], v[8:11], v[152:155], v[116:119]
	v_mfma_f32_16x16x32_bf16 v[112:115], v[12:15], v[152:155], v[112:115]
	v_mfma_f32_16x16x32_bf16 v[128:131], v[36:39], v[152:155], v[128:131]
	ds_read_b128 v[152:155], v161 offset:24576
	ds_read_b128 v[172:175], v161 offset:25600
	s_waitcnt lgkmcnt(1)
	v_mfma_f32_16x16x32_bf16 v[156:159], v[24:27], v[152:155], 0
	v_mfma_f32_16x16x32_bf16 v[152:155], v[28:31], v[152:155], 0
	s_waitcnt lgkmcnt(0)
	v_mfma_f32_16x16x32_bf16 v[156:159], v[16:19], v[172:175], v[156:159]
	v_mfma_f32_16x16x32_bf16 v[152:155], v[20:23], v[172:175], v[152:155]
	s_nop 6
	v_max3_f32 v32, v156, v157, v158
	v_max3_f32 v35, v159, v152, v153
	v_max3_f32 v32, v32, v154, v155
	v_max_f32_e32 v32, v32, v35
	v_add_f32_e32 v34, 0x41000000, v169
	v_cmp_gt_f32_e32 vcc, v32, v34
	s_cbranch_vccz .LBB0_272
	v_mov_b32_e32 v34, v32
	s_nop 1
	v_permlane16_swap_b32 v32, v34
	s_nop 0
	v_max_f32_e32 v34, v34, v34
	v_max_f32_e32 v32, v32, v32
	v_max_f32_e32 v32, v32, v34
	v_mov_b32_e32 v34, v32
	s_nop 1
	v_permlane32_swap_b32 v32, v34
	s_nop 0
	v_max3_f32 v34, v169, v32, v34
	v_sub_f32_e32 v32, v169, v34
	v_exp_f32_e32 v32, v32
	v_mov_b32_e32 v169, v34
	v_pk_mul_f32 v[106:107], v[106:107], v[32:33] op_sel_hi:[1,0]
	v_pk_mul_f32 v[104:105], v[104:105], v[32:33] op_sel_hi:[1,0]
	v_pk_mul_f32 v[102:103], v[102:103], v[32:33] op_sel_hi:[1,0]
	v_pk_mul_f32 v[100:101], v[100:101], v[32:33] op_sel_hi:[1,0]
	v_pk_mul_f32 v[98:99], v[98:99], v[32:33] op_sel_hi:[1,0]
	v_pk_mul_f32 v[96:97], v[96:97], v[32:33] op_sel_hi:[1,0]
	v_pk_mul_f32 v[94:95], v[94:95], v[32:33] op_sel_hi:[1,0]
	v_pk_mul_f32 v[92:93], v[92:93], v[32:33] op_sel_hi:[1,0]
	v_pk_mul_f32 v[110:111], v[110:111], v[32:33] op_sel_hi:[1,0]
	v_pk_mul_f32 v[108:109], v[108:109], v[32:33] op_sel_hi:[1,0]
.LBB0_272:
	v_sub_f32_e32 v35, v158, v169
	v_sub_f32_e32 v37, v159, v169
	v_sub_f32_e32 v38, v152, v169
	v_sub_f32_e32 v39, v153, v169
	v_exp_f32_e32 v35, v35
	v_exp_f32_e32 v37, v37
	v_exp_f32_e32 v38, v38
	v_exp_f32_e32 v39, v39
	v_sub_f32_e32 v152, v154, v169
	v_sub_f32_e32 v32, v156, v169
	v_sub_f32_e32 v34, v157, v169
	v_exp_f32_e32 v156, v152
	v_sub_f32_e32 v152, v155, v169
	v_exp_f32_e32 v32, v32
	v_exp_f32_e32 v34, v34
	v_exp_f32_e32 v155, v152
	v_cvt_pk_bf16_f32 v153, v35, v37
	v_cvt_pk_bf16_f32 v154, v38, v39
	v_mov_b32_e32 v37, v36
	v_mov_b32_e32 v38, v36
	v_mov_b32_e32 v39, v36
	v_cvt_pk_bf16_f32 v152, v32, v34
	v_cvt_pk_bf16_f32 v155, v156, v155
	s_nop 1
	v_mfma_f32_16x16x32_bf16 v[104:107], v[0:3], v[152:155], v[104:107]
	v_mfma_f32_16x16x32_bf16 v[100:103], v[4:7], v[152:155], v[100:103]
	v_mfma_f32_16x16x32_bf16 v[96:99], v[8:11], v[152:155], v[96:99]
	v_mfma_f32_16x16x32_bf16 v[92:95], v[12:15], v[152:155], v[92:95]
	v_mfma_f32_16x16x32_bf16 v[108:111], v[36:39], v[152:155], v[108:111]
	ds_read_b128 v[152:155], v161 offset:26624
	s_waitcnt lgkmcnt(0)
	v_mfma_f32_16x16x32_bf16 v[24:27], v[24:27], v[152:155], 0
	v_mfma_f32_16x16x32_bf16 v[28:31], v[28:31], v[152:155], 0
	ds_read_b128 v[152:155], v161 offset:27648
	s_waitcnt lgkmcnt(0)
	v_mfma_f32_16x16x32_bf16 v[16:19], v[16:19], v[152:155], v[24:27]
	v_mfma_f32_16x16x32_bf16 v[20:23], v[20:23], v[152:155], v[28:31]
	s_nop 6
	v_max3_f32 v24, v16, v17, v18
	v_max3_f32 v26, v19, v20, v21
	v_max3_f32 v24, v24, v22, v23
	v_max_f32_e32 v24, v24, v26
	v_add_f32_e32 v25, 0x41000000, v168
	v_cmp_gt_f32_e32 vcc, v24, v25
	s_cbranch_vccz .LBB0_274
	v_mov_b32_e32 v25, v24
	s_nop 1
	v_permlane16_swap_b32 v24, v25
	s_nop 0
	v_max_f32_e32 v25, v25, v25
	v_max_f32_e32 v24, v24, v24
	v_max_f32_e32 v24, v24, v25
	v_mov_b32_e32 v25, v24
	s_nop 1
	v_permlane32_swap_b32 v25, v24
	s_nop 0
	v_max3_f32 v25, v168, v25, v24
	v_sub_f32_e32 v24, v168, v25
	v_exp_f32_e32 v24, v24
	v_mov_b32_e32 v168, v25
	v_pk_mul_f32 v[86:87], v[86:87], v[24:25] op_sel_hi:[1,0]
	v_pk_mul_f32 v[84:85], v[84:85], v[24:25] op_sel_hi:[1,0]
	v_pk_mul_f32 v[82:83], v[82:83], v[24:25] op_sel_hi:[1,0]
	v_pk_mul_f32 v[80:81], v[80:81], v[24:25] op_sel_hi:[1,0]
	v_pk_mul_f32 v[78:79], v[78:79], v[24:25] op_sel_hi:[1,0]
	v_pk_mul_f32 v[76:77], v[76:77], v[24:25] op_sel_hi:[1,0]
	v_pk_mul_f32 v[74:75], v[74:75], v[24:25] op_sel_hi:[1,0]
	v_pk_mul_f32 v[72:73], v[72:73], v[24:25] op_sel_hi:[1,0]
	v_pk_mul_f32 v[90:91], v[90:91], v[24:25] op_sel_hi:[1,0]
	v_pk_mul_f32 v[88:89], v[88:89], v[24:25] op_sel_hi:[1,0]
.LBB0_274:
	v_sub_f32_e32 v16, v16, v168
	v_sub_f32_e32 v17, v17, v168
	v_sub_f32_e32 v18, v18, v168
	v_sub_f32_e32 v19, v19, v168
	v_sub_f32_e32 v20, v20, v168
	v_sub_f32_e32 v21, v21, v168
	v_sub_f32_e32 v22, v22, v168
	v_sub_f32_e32 v23, v23, v168
	v_exp_f32_e32 v16, v16
	v_exp_f32_e32 v17, v17
	v_exp_f32_e32 v18, v18
	v_exp_f32_e32 v19, v19
	v_exp_f32_e32 v20, v20
	v_exp_f32_e32 v21, v21
	v_exp_f32_e32 v22, v22
	v_exp_f32_e32 v23, v23
	v_cvt_pk_bf16_f32 v16, v16, v17
	v_cvt_pk_bf16_f32 v17, v18, v19
	v_cvt_pk_bf16_f32 v18, v20, v21
	v_cvt_pk_bf16_f32 v19, v22, v23
	s_add_i32 s31, s35, -2
	s_nop 0
	v_mfma_f32_16x16x32_bf16 v[84:87], v[0:3], v[16:19], v[84:87]
	v_mfma_f32_16x16x32_bf16 v[80:83], v[4:7], v[16:19], v[80:83]
	v_mfma_f32_16x16x32_bf16 v[76:79], v[8:11], v[16:19], v[76:79]
	v_mfma_f32_16x16x32_bf16 v[72:75], v[12:15], v[16:19], v[72:75]
	v_mfma_f32_16x16x32_bf16 v[88:91], v[36:39], v[16:19], v[88:91]
	s_cmp_lt_u32 s31, 6
	s_cselect_b32 s0, s35, 0
	s_add_i32 s40, s0, s42
	ds_read_b128 v[8:11], v161 offset:20480
	s_lshl_b32 s0, s40, 1
	s_lshl_b64 s[46:47], s[0:1], 14
	v_lshl_add_u64 v[4:5], v[164:165], 0, s[46:47]
	global_load_dwordx4 v[24:27], v[4:5], off
	global_load_dwordx4 v[16:19], v[4:5], off offset:1024
	ds_read_b128 v[156:159], v161 offset:21504
	s_waitcnt vmcnt(9) lgkmcnt(1)
	v_mfma_f32_16x16x32_bf16 v[0:3], v[64:67], v[8:11], 0
	s_mov_b32 s41, s1
	v_add_co_u32_e32 v4, vcc, s72, v4
	s_lshl_b64 s[40:41], s[40:41], 15
	s_nop 0
	v_addc_co_u32_e32 v5, vcc, 0, v5, vcc
	v_lshl_add_u64 v[12:13], v[166:167], 0, s[40:41]
	s_waitcnt vmcnt(8) lgkmcnt(0)
	v_mfma_f32_16x16x32_bf16 v[152:155], v[60:63], v[156:159], v[0:3]
	global_load_dwordx4 v[28:31], v[4:5], off
	global_load_dwordx4 v[20:23], v[4:5], off offset:1024
	s_nop 0
	global_load_dwordx4 v[0:3], v[12:13], off
	global_load_dwordx4 v[4:7], v[12:13], off offset:1024
	s_nop 2
	s_waitcnt vmcnt(11)
	v_mfma_f32_16x16x32_bf16 v[172:175], v[68:71], v[8:11], 0
	global_load_dwordx4 v[8:11], v[12:13], off offset:2048
	s_nop 0
	global_load_dwordx4 v[12:15], v[12:13], off offset:3072
	s_waitcnt vmcnt(12)
	v_mfma_f32_16x16x32_bf16 v[156:159], v[56:59], v[156:159], v[172:175]
	s_nop 4
	v_max3_f32 v32, v152, v153, v154
	s_nop 1
	v_max3_f32 v35, v155, v156, v157
	v_max3_f32 v32, v32, v158, v159
	v_max_f32_e32 v32, v32, v35
	v_add_f32_e32 v34, 0x41000000, v171
	v_cmp_gt_f32_e32 vcc, v32, v34
	s_cbranch_vccz .LBB0_276
	v_mov_b32_e32 v34, v32
	s_nop 1
	v_permlane16_swap_b32 v32, v34
	s_nop 0
	v_max_f32_e32 v34, v34, v34
	v_max_f32_e32 v32, v32, v32
	v_max_f32_e32 v32, v32, v34
	v_mov_b32_e32 v34, v32
	s_nop 1
	v_permlane32_swap_b32 v32, v34
	s_nop 0
	v_max3_f32 v34, v171, v32, v34
	v_sub_f32_e32 v32, v171, v34
	v_exp_f32_e32 v32, v32
	v_mov_b32_e32 v171, v34
	v_pk_mul_f32 v[146:147], v[146:147], v[32:33] op_sel_hi:[1,0]
	v_pk_mul_f32 v[144:145], v[144:145], v[32:33] op_sel_hi:[1,0]
	v_pk_mul_f32 v[142:143], v[142:143], v[32:33] op_sel_hi:[1,0]
	v_pk_mul_f32 v[140:141], v[140:141], v[32:33] op_sel_hi:[1,0]
	v_pk_mul_f32 v[138:139], v[138:139], v[32:33] op_sel_hi:[1,0]
	v_pk_mul_f32 v[136:137], v[136:137], v[32:33] op_sel_hi:[1,0]
	v_pk_mul_f32 v[134:135], v[134:135], v[32:33] op_sel_hi:[1,0]
	v_pk_mul_f32 v[132:133], v[132:133], v[32:33] op_sel_hi:[1,0]
	v_pk_mul_f32 v[150:151], v[150:151], v[32:33] op_sel_hi:[1,0]
	v_pk_mul_f32 v[148:149], v[148:149], v[32:33] op_sel_hi:[1,0]
.LBB0_276:
	v_sub_f32_e32 v35, v154, v171
	v_sub_f32_e32 v37, v155, v171
	v_sub_f32_e32 v38, v156, v171
	v_sub_f32_e32 v39, v157, v171
	v_exp_f32_e32 v35, v35
	v_exp_f32_e32 v37, v37
	v_exp_f32_e32 v38, v38
	v_exp_f32_e32 v39, v39
	v_sub_f32_e32 v32, v152, v171
	v_sub_f32_e32 v152, v158, v171
	v_sub_f32_e32 v34, v153, v171
	v_exp_f32_e32 v155, v152
	v_sub_f32_e32 v152, v159, v171
	v_exp_f32_e32 v32, v32
	v_exp_f32_e32 v34, v34
	v_exp_f32_e32 v156, v152
	v_cvt_pk_bf16_f32 v153, v35, v37
	v_cvt_pk_bf16_f32 v154, v38, v39
	v_mov_b32_e32 v37, v36
	v_mov_b32_e32 v38, v36
	v_mov_b32_e32 v39, v36
	v_cvt_pk_bf16_f32 v152, v32, v34
	v_cvt_pk_bf16_f32 v155, v155, v156
	s_waitcnt vmcnt(11)
	s_nop 0
	v_mfma_f32_16x16x32_bf16 v[144:147], v[40:43], v[152:155], v[144:147]
	s_waitcnt vmcnt(10)
	v_mfma_f32_16x16x32_bf16 v[140:143], v[44:47], v[152:155], v[140:143]
	s_waitcnt vmcnt(9)
	v_mfma_f32_16x16x32_bf16 v[136:139], v[48:51], v[152:155], v[136:139]
	s_waitcnt vmcnt(8)
	v_mfma_f32_16x16x32_bf16 v[132:135], v[52:55], v[152:155], v[132:135]
	v_mfma_f32_16x16x32_bf16 v[148:151], v[36:39], v[152:155], v[148:151]
	ds_read_b128 v[152:155], v161 offset:22528
	ds_read_b128 v[172:175], v161 offset:23552
	s_waitcnt lgkmcnt(1)
	v_mfma_f32_16x16x32_bf16 v[156:159], v[64:67], v[152:155], 0
	v_mfma_f32_16x16x32_bf16 v[152:155], v[68:71], v[152:155], 0
	s_waitcnt lgkmcnt(0)
	v_mfma_f32_16x16x32_bf16 v[156:159], v[60:63], v[172:175], v[156:159]
	v_mfma_f32_16x16x32_bf16 v[152:155], v[56:59], v[172:175], v[152:155]
	s_nop 6
	v_max3_f32 v32, v156, v157, v158
	v_max3_f32 v35, v159, v152, v153
	v_max3_f32 v32, v32, v154, v155
	v_max_f32_e32 v32, v32, v35
	v_add_f32_e32 v34, 0x41000000, v170
	v_cmp_gt_f32_e32 vcc, v32, v34
	s_cbranch_vccz .LBB0_278
	v_mov_b32_e32 v34, v32
	s_nop 1
	v_permlane16_swap_b32 v32, v34
	s_nop 0
	v_max_f32_e32 v34, v34, v34
	v_max_f32_e32 v32, v32, v32
	v_max_f32_e32 v32, v32, v34
	v_mov_b32_e32 v34, v32
	s_nop 1
	v_permlane32_swap_b32 v34, v32
	s_nop 0
	v_max3_f32 v34, v170, v34, v32
	v_sub_f32_e32 v32, v170, v34
	v_exp_f32_e32 v32, v32
	v_mov_b32_e32 v170, v34
	v_pk_mul_f32 v[126:127], v[126:127], v[32:33] op_sel_hi:[1,0]
	v_pk_mul_f32 v[124:125], v[124:125], v[32:33] op_sel_hi:[1,0]
	v_pk_mul_f32 v[122:123], v[122:123], v[32:33] op_sel_hi:[1,0]
	v_pk_mul_f32 v[120:121], v[120:121], v[32:33] op_sel_hi:[1,0]
	v_pk_mul_f32 v[118:119], v[118:119], v[32:33] op_sel_hi:[1,0]
	v_pk_mul_f32 v[116:117], v[116:117], v[32:33] op_sel_hi:[1,0]
	v_pk_mul_f32 v[114:115], v[114:115], v[32:33] op_sel_hi:[1,0]
	v_pk_mul_f32 v[112:113], v[112:113], v[32:33] op_sel_hi:[1,0]
	v_pk_mul_f32 v[130:131], v[130:131], v[32:33] op_sel_hi:[1,0]
	v_pk_mul_f32 v[128:129], v[128:129], v[32:33] op_sel_hi:[1,0]
.LBB0_278:
	v_sub_f32_e32 v152, v152, v170
	v_sub_f32_e32 v34, v157, v170
	v_exp_f32_e32 v157, v152
	v_sub_f32_e32 v152, v153, v170
	v_sub_f32_e32 v35, v158, v170
	v_exp_f32_e32 v158, v152
	v_sub_f32_e32 v152, v154, v170
	v_sub_f32_e32 v32, v156, v170
	v_sub_f32_e32 v156, v159, v170
	v_exp_f32_e32 v159, v152
	v_sub_f32_e32 v152, v155, v170
	v_exp_f32_e32 v32, v32
	v_exp_f32_e32 v34, v34
	v_exp_f32_e32 v35, v35
	v_exp_f32_e32 v156, v156
	v_exp_f32_e32 v155, v152
	v_cvt_pk_bf16_f32 v152, v32, v34
	v_cvt_pk_bf16_f32 v154, v157, v158
	v_cvt_pk_bf16_f32 v153, v35, v156
	v_cvt_pk_bf16_f32 v155, v159, v155
	s_nop 1
	v_mfma_f32_16x16x32_bf16 v[124:127], v[40:43], v[152:155], v[124:127]
	v_mfma_f32_16x16x32_bf16 v[120:123], v[44:47], v[152:155], v[120:123]
	v_mfma_f32_16x16x32_bf16 v[116:119], v[48:51], v[152:155], v[116:119]
	v_mfma_f32_16x16x32_bf16 v[112:115], v[52:55], v[152:155], v[112:115]
	v_mfma_f32_16x16x32_bf16 v[128:131], v[36:39], v[152:155], v[128:131]
	ds_read_b128 v[152:155], v161 offset:24576
	ds_read_b128 v[172:175], v161 offset:25600
	s_waitcnt lgkmcnt(1)
	v_mfma_f32_16x16x32_bf16 v[156:159], v[64:67], v[152:155], 0
	v_mfma_f32_16x16x32_bf16 v[152:155], v[68:71], v[152:155], 0
	s_waitcnt lgkmcnt(0)
	v_mfma_f32_16x16x32_bf16 v[156:159], v[60:63], v[172:175], v[156:159]
	v_mfma_f32_16x16x32_bf16 v[152:155], v[56:59], v[172:175], v[152:155]
	s_nop 6
	v_max3_f32 v32, v156, v157, v158
	v_max3_f32 v35, v159, v152, v153
	v_max3_f32 v32, v32, v154, v155
	v_max_f32_e32 v32, v32, v35
	v_add_f32_e32 v34, 0x41000000, v169
	v_cmp_gt_f32_e32 vcc, v32, v34
	s_cbranch_vccz .LBB0_280
	v_mov_b32_e32 v34, v32
	s_nop 1
	v_permlane16_swap_b32 v32, v34
	s_nop 0
	v_max_f32_e32 v34, v34, v34
	v_max_f32_e32 v32, v32, v32
	v_max_f32_e32 v32, v32, v34
	v_mov_b32_e32 v34, v32
	s_nop 1
	v_permlane32_swap_b32 v32, v34
	s_nop 0
	v_max3_f32 v34, v169, v32, v34
	v_sub_f32_e32 v32, v169, v34
	v_exp_f32_e32 v32, v32
	v_mov_b32_e32 v169, v34
	v_pk_mul_f32 v[106:107], v[106:107], v[32:33] op_sel_hi:[1,0]
	v_pk_mul_f32 v[104:105], v[104:105], v[32:33] op_sel_hi:[1,0]
	v_pk_mul_f32 v[102:103], v[102:103], v[32:33] op_sel_hi:[1,0]
	v_pk_mul_f32 v[100:101], v[100:101], v[32:33] op_sel_hi:[1,0]
	v_pk_mul_f32 v[98:99], v[98:99], v[32:33] op_sel_hi:[1,0]
	v_pk_mul_f32 v[96:97], v[96:97], v[32:33] op_sel_hi:[1,0]
	v_pk_mul_f32 v[94:95], v[94:95], v[32:33] op_sel_hi:[1,0]
	v_pk_mul_f32 v[92:93], v[92:93], v[32:33] op_sel_hi:[1,0]
	v_pk_mul_f32 v[110:111], v[110:111], v[32:33] op_sel_hi:[1,0]
	v_pk_mul_f32 v[108:109], v[108:109], v[32:33] op_sel_hi:[1,0]
.LBB0_280:
	v_sub_f32_e32 v35, v158, v169
	v_sub_f32_e32 v37, v159, v169
	v_sub_f32_e32 v38, v152, v169
	v_sub_f32_e32 v39, v153, v169
	v_exp_f32_e32 v35, v35
	v_exp_f32_e32 v37, v37
	v_exp_f32_e32 v38, v38
	v_exp_f32_e32 v39, v39
	v_sub_f32_e32 v152, v154, v169
	v_sub_f32_e32 v32, v156, v169
	v_sub_f32_e32 v34, v157, v169
	v_exp_f32_e32 v156, v152
	v_sub_f32_e32 v152, v155, v169
	v_exp_f32_e32 v32, v32
	v_exp_f32_e32 v34, v34
	v_exp_f32_e32 v155, v152
	v_cvt_pk_bf16_f32 v153, v35, v37
	v_cvt_pk_bf16_f32 v154, v38, v39
	v_mov_b32_e32 v37, v36
	v_mov_b32_e32 v38, v36
	v_mov_b32_e32 v39, v36
	v_cvt_pk_bf16_f32 v152, v32, v34
	v_cvt_pk_bf16_f32 v155, v156, v155
	s_nop 1
	v_mfma_f32_16x16x32_bf16 v[104:107], v[40:43], v[152:155], v[104:107]
	v_mfma_f32_16x16x32_bf16 v[100:103], v[44:47], v[152:155], v[100:103]
	v_mfma_f32_16x16x32_bf16 v[96:99], v[48:51], v[152:155], v[96:99]
	v_mfma_f32_16x16x32_bf16 v[92:95], v[52:55], v[152:155], v[92:95]
	v_mfma_f32_16x16x32_bf16 v[108:111], v[36:39], v[152:155], v[108:111]
	ds_read_b128 v[152:155], v161 offset:26624
	s_waitcnt lgkmcnt(0)
	v_mfma_f32_16x16x32_bf16 v[64:67], v[64:67], v[152:155], 0
	v_mfma_f32_16x16x32_bf16 v[68:71], v[68:71], v[152:155], 0
	ds_read_b128 v[152:155], v161 offset:27648
	s_waitcnt lgkmcnt(0)
	v_mfma_f32_16x16x32_bf16 v[60:63], v[60:63], v[152:155], v[64:67]
	v_mfma_f32_16x16x32_bf16 v[56:59], v[56:59], v[152:155], v[68:71]
	s_nop 6
	v_max3_f32 v32, v60, v61, v62
	v_max3_f32 v35, v63, v56, v57
	v_max3_f32 v32, v32, v58, v59
	v_max_f32_e32 v32, v32, v35
	v_add_f32_e32 v34, 0x41000000, v168
	v_cmp_gt_f32_e32 vcc, v32, v34
	s_cbranch_vccz .LBB0_265
	v_mov_b32_e32 v34, v32
	s_nop 1
	v_permlane16_swap_b32 v32, v34
	s_nop 0
	v_max_f32_e32 v34, v34, v34
	v_max_f32_e32 v32, v32, v32
	v_max_f32_e32 v32, v32, v34
	v_mov_b32_e32 v34, v32
	s_nop 1
	v_permlane32_swap_b32 v32, v34
	s_nop 0
	v_max3_f32 v34, v168, v32, v34
	v_sub_f32_e32 v32, v168, v34
	v_exp_f32_e32 v32, v32
	v_mov_b32_e32 v168, v34
	v_pk_mul_f32 v[86:87], v[86:87], v[32:33] op_sel_hi:[1,0]
	v_pk_mul_f32 v[84:85], v[84:85], v[32:33] op_sel_hi:[1,0]
	v_pk_mul_f32 v[82:83], v[82:83], v[32:33] op_sel_hi:[1,0]
	v_pk_mul_f32 v[80:81], v[80:81], v[32:33] op_sel_hi:[1,0]
	v_pk_mul_f32 v[78:79], v[78:79], v[32:33] op_sel_hi:[1,0]
	v_pk_mul_f32 v[76:77], v[76:77], v[32:33] op_sel_hi:[1,0]
	v_pk_mul_f32 v[74:75], v[74:75], v[32:33] op_sel_hi:[1,0]
	v_pk_mul_f32 v[72:73], v[72:73], v[32:33] op_sel_hi:[1,0]
	v_pk_mul_f32 v[90:91], v[90:91], v[32:33] op_sel_hi:[1,0]
	v_pk_mul_f32 v[88:89], v[88:89], v[32:33] op_sel_hi:[1,0]
	s_branch .LBB0_265

.LBB0_300:
	s_lshl_b64 s[62:63], s[0:1], 14
	s_add_i32 s27, s34, s25
	v_lshl_add_u64 v[34:35], v[164:165], 0, s[62:63]
	s_add_i32 s30, s27, 1
	s_mov_b32 s31, s1
	global_load_dwordx4 v[136:139], v[34:35], off
	global_load_dwordx4 v[140:143], v[34:35], off offset:1024
	v_add_co_u32_e32 v34, vcc, s72, v34
	s_lshl_b64 s[30:31], s[30:31], 15
	s_nop 0
	v_addc_co_u32_e32 v35, vcc, 0, v35, vcc
	v_lshl_add_u64 v[38:39], v[166:167], 0, s[30:31]
	global_load_dwordx4 v[148:151], v[34:35], off
	global_load_dwordx4 v[144:147], v[34:35], off offset:1024
	global_load_dwordx4 v[120:123], v[38:39], off
	global_load_dwordx4 v[124:127], v[38:39], off offset:1024
	global_load_dwordx4 v[128:131], v[38:39], off offset:2048
	global_load_dwordx4 v[132:135], v[38:39], off offset:3072
	ds_read_b128 v[210:213], v161 offset:20480
	ds_read_b128 v[214:217], v161 offset:21504
	ds_read_b32 v218, v208 offset:128
	ds_read_b32 v222, v208 offset:192
	ds_read_b32 v219, v208 offset:132
	ds_read_b32 v223, v208 offset:196
	ds_read_b32 v220, v208 offset:136
	ds_read_b32 v224, v208 offset:200
	ds_read_b32 v221, v208 offset:140
	ds_read_b32 v225, v208 offset:204
	s_waitcnt vmcnt(15) lgkmcnt(1)
	v_mfma_f32_16x16x32_bf16 v[218:221], v[20:23], v[210:213], v[218:221]
	s_waitcnt vmcnt(13) lgkmcnt(0)
	v_mfma_f32_16x16x32_bf16 v[210:213], v[28:31], v[210:213], v[222:225]
	v_mfma_f32_16x16x32_bf16 v[218:221], v[16:19], v[214:217], v[218:221]
	s_waitcnt vmcnt(12)
	v_mfma_f32_16x16x32_bf16 v[212:215], v[24:27], v[214:217], v[210:213]
	s_nop 5
	v_cndmask_b32_e64 v210, v242, v218, s[42:43]
	v_cndmask_b32_e64 v209, v242, v219, s[44:45]
	v_cndmask_b32_e64 v39, v242, v220, s[46:47]
	v_cndmask_b32_e64 v38, v242, v221, s[48:49]
	v_cndmask_b32_e64 v37, v242, v212, s[50:51]
	v_cndmask_b32_e64 v35, v242, v213, s[52:53]
	v_cndmask_b32_e64 v34, v242, v214, s[54:55]
	v_cndmask_b32_e64 v32, v242, v215, s[56:57]
	v_max3_f32 v211, v210, v209, v39
	v_max3_f32 v213, v38, v37, v35
	v_max3_f32 v211, v211, v34, v32
	v_max_f32_e32 v211, v211, v213
	v_add_f32_e32 v212, 0x41000000, v170
	v_cmp_gt_f32_e32 vcc, v211, v212
	s_cbranch_vccz .LBB0_302
	v_mov_b32_e32 v212, v211
	s_nop 1
	v_permlane16_swap_b32 v211, v212
	s_nop 0
	v_max_f32_e32 v212, v212, v212
	v_max_f32_e32 v211, v211, v211
	v_max_f32_e32 v211, v211, v212
	v_mov_b32_e32 v212, v211
	s_nop 1
	v_permlane32_swap_b32 v211, v212
	s_nop 0
	v_max3_f32 v211, v170, v211, v212
	v_sub_f32_e32 v170, v170, v211
	v_exp_f32_e32 v170, v170
	s_nop 0
	v_pk_mul_f32 v[74:75], v[74:75], v[170:171] op_sel_hi:[1,0]
	v_pk_mul_f32 v[72:73], v[72:73], v[170:171] op_sel_hi:[1,0]
	v_pk_mul_f32 v[70:71], v[70:71], v[170:171] op_sel_hi:[1,0]
	v_pk_mul_f32 v[68:69], v[68:69], v[170:171] op_sel_hi:[1,0]
	v_pk_mul_f32 v[66:67], v[66:67], v[170:171] op_sel_hi:[1,0]
	v_pk_mul_f32 v[64:65], v[64:65], v[170:171] op_sel_hi:[1,0]
	v_pk_mul_f32 v[62:63], v[62:63], v[170:171] op_sel_hi:[1,0]
	v_pk_mul_f32 v[60:61], v[60:61], v[170:171] op_sel_hi:[1,0]
	v_pk_mul_f32 v[78:79], v[78:79], v[170:171] op_sel_hi:[1,0]
	v_pk_mul_f32 v[76:77], v[76:77], v[170:171] op_sel_hi:[1,0]
	v_mov_b32_e32 v170, v211
.LBB0_302:
	v_sub_f32_e32 v39, v39, v170
	v_sub_f32_e32 v38, v38, v170
	v_sub_f32_e32 v37, v37, v170
	v_sub_f32_e32 v35, v35, v170
	v_exp_f32_e32 v39, v39
	v_exp_f32_e32 v38, v38
	v_exp_f32_e32 v37, v37
	v_exp_f32_e32 v35, v35
	v_sub_f32_e32 v210, v210, v170
	v_sub_f32_e32 v209, v209, v170
	v_sub_f32_e32 v34, v34, v170
	v_sub_f32_e32 v32, v32, v170
	v_exp_f32_e32 v210, v210
	v_exp_f32_e32 v209, v209
	v_exp_f32_e32 v34, v34
	v_exp_f32_e32 v32, v32
	v_cvt_pk_bf16_f32 v211, v39, v38
	v_cvt_pk_bf16_f32 v212, v37, v35
	v_mov_b32_e32 v37, v36
	v_mov_b32_e32 v38, v36
	v_mov_b32_e32 v39, v36
	v_cvt_pk_bf16_f32 v210, v210, v209
	v_cvt_pk_bf16_f32 v213, v34, v32
	s_waitcnt vmcnt(11)
	s_nop 0
	v_mfma_f32_16x16x32_bf16 v[72:75], v[0:3], v[210:213], v[72:75]
	s_waitcnt vmcnt(10)
	v_mfma_f32_16x16x32_bf16 v[68:71], v[4:7], v[210:213], v[68:71]
	s_waitcnt vmcnt(9)
	v_mfma_f32_16x16x32_bf16 v[64:67], v[8:11], v[210:213], v[64:67]
	s_waitcnt vmcnt(8)
	v_mfma_f32_16x16x32_bf16 v[60:63], v[12:15], v[210:213], v[60:63]
	v_mfma_f32_16x16x32_bf16 v[76:79], v[36:39], v[210:213], v[76:79]
	ds_read_b128 v[210:213], v161 offset:22528
	ds_read_b128 v[214:217], v161 offset:23552
	ds_read_b32 v218, v208 offset:64
	ds_read_b32 v222, v208 offset:128
	ds_read_b32 v219, v208 offset:68
	ds_read_b32 v223, v208 offset:132
	ds_read_b32 v220, v208 offset:72
	ds_read_b32 v224, v208 offset:136
	ds_read_b32 v221, v208 offset:76
	ds_read_b32 v225, v208 offset:140
	v_bitop3_b32 v32, v152, s29, v152 bitop3:0xc
	v_bitop3_b32 v34, v153, s29, v153 bitop3:0xc
	v_bitop3_b32 v35, v154, s29, v154 bitop3:0xc
	s_waitcnt lgkmcnt(1)
	v_mfma_f32_16x16x32_bf16 v[218:221], v[20:23], v[210:213], v[218:221]
	v_bitop3_b32 v209, v155, s29, v155 bitop3:0xc
	s_waitcnt lgkmcnt(0)
	v_mfma_f32_16x16x32_bf16 v[210:213], v[28:31], v[210:213], v[222:225]
	v_mfma_f32_16x16x32_bf16 v[210:213], v[24:27], v[214:217], v[210:213]
	v_mfma_f32_16x16x32_bf16 v[218:221], v[16:19], v[214:217], v[218:221]
	v_bitop3_b32 v214, v156, s29, v156 bitop3:0xc
	s_nop 5
	v_and_or_b32 v210, v210, v156, v214
	v_bitop3_b32 v214, v157, s29, v157 bitop3:0xc
	v_and_or_b32 v211, v211, v157, v214
	v_bitop3_b32 v214, v158, s29, v158 bitop3:0xc
	v_and_or_b32 v32, v218, v152, v32
	v_and_or_b32 v34, v219, v153, v34
	v_and_or_b32 v212, v212, v158, v214
	v_bitop3_b32 v214, v159, s29, v159 bitop3:0xc
	v_and_or_b32 v35, v220, v154, v35
	v_and_or_b32 v209, v221, v155, v209
	v_and_or_b32 v213, v213, v159, v214
	v_max3_f32 v214, v210, v211, v32
	v_max3_f32 v216, v34, v212, v35
	v_max3_f32 v214, v214, v209, v213
	v_max_f32_e32 v214, v214, v216
	v_add_f32_e32 v215, 0x41000000, v172
	v_cmp_gt_f32_e32 vcc, v214, v215
	s_cbranch_vccz .LBB0_304
	v_mov_b32_e32 v215, v214
	s_nop 1
	v_permlane16_swap_b32 v214, v215
	s_nop 0
	v_max_f32_e32 v215, v215, v215
	v_max_f32_e32 v214, v214, v214
	v_max_f32_e32 v214, v214, v215
	v_mov_b32_e32 v215, v214
	s_nop 1
	v_permlane32_swap_b32 v214, v215
	s_nop 0
	v_max3_f32 v214, v172, v214, v215
	v_sub_f32_e32 v172, v172, v214
	v_exp_f32_e32 v172, v172
	s_nop 0
	v_pk_mul_f32 v[114:115], v[114:115], v[172:173] op_sel_hi:[1,0]
	v_pk_mul_f32 v[112:113], v[112:113], v[172:173] op_sel_hi:[1,0]
	v_pk_mul_f32 v[110:111], v[110:111], v[172:173] op_sel_hi:[1,0]
	v_pk_mul_f32 v[108:109], v[108:109], v[172:173] op_sel_hi:[1,0]
	v_pk_mul_f32 v[106:107], v[106:107], v[172:173] op_sel_hi:[1,0]
	v_pk_mul_f32 v[104:105], v[104:105], v[172:173] op_sel_hi:[1,0]
	v_pk_mul_f32 v[102:103], v[102:103], v[172:173] op_sel_hi:[1,0]
	v_pk_mul_f32 v[100:101], v[100:101], v[172:173] op_sel_hi:[1,0]
	v_pk_mul_f32 v[118:119], v[118:119], v[172:173] op_sel_hi:[1,0]
	v_pk_mul_f32 v[116:117], v[116:117], v[172:173] op_sel_hi:[1,0]
	v_mov_b32_e32 v172, v214
.LBB0_304:
	v_sub_f32_e32 v210, v210, v172
	v_exp_f32_e32 v214, v210
	v_sub_f32_e32 v210, v211, v172
	v_exp_f32_e32 v215, v210
	v_sub_f32_e32 v210, v212, v172
	v_sub_f32_e32 v32, v32, v172
	v_sub_f32_e32 v34, v34, v172
	v_sub_f32_e32 v35, v35, v172
	v_sub_f32_e32 v209, v209, v172
	v_exp_f32_e32 v216, v210
	v_sub_f32_e32 v210, v213, v172
	v_exp_f32_e32 v32, v32
	v_exp_f32_e32 v34, v34
	v_exp_f32_e32 v35, v35
	v_exp_f32_e32 v209, v209
	v_exp_f32_e32 v213, v210
	v_cvt_pk_bf16_f32 v210, v32, v34
	v_cvt_pk_bf16_f32 v212, v214, v215
	v_cvt_pk_bf16_f32 v211, v35, v209
	v_cvt_pk_bf16_f32 v213, v216, v213
	s_nop 1
	v_mfma_f32_16x16x32_bf16 v[112:115], v[0:3], v[210:213], v[112:115]
	v_mfma_f32_16x16x32_bf16 v[108:111], v[4:7], v[210:213], v[108:111]
	v_mfma_f32_16x16x32_bf16 v[104:107], v[8:11], v[210:213], v[104:107]
	v_mfma_f32_16x16x32_bf16 v[100:103], v[12:15], v[210:213], v[100:103]
	v_mfma_f32_16x16x32_bf16 v[116:119], v[36:39], v[210:213], v[116:119]
	ds_read_b128 v[210:213], v161 offset:24576
	ds_read_b128 v[214:217], v161 offset:25600
	ds_read_b32 v218, v208
	ds_read_b32 v222, v208 offset:64
	ds_read_b32 v219, v208 offset:4
	ds_read_b32 v223, v208 offset:68
	ds_read_b32 v220, v208 offset:8
	ds_read_b32 v224, v208 offset:72
	ds_read_b32 v221, v208 offset:12
	ds_read_b32 v225, v208 offset:76
	s_waitcnt lgkmcnt(1)
	v_mfma_f32_16x16x32_bf16 v[20:23], v[20:23], v[210:213], v[218:221]
	v_mfma_f32_16x16x32_bf16 v[16:19], v[16:19], v[214:217], v[20:23]
	s_waitcnt lgkmcnt(0)
	s_nop 5
	v_mfma_f32_16x16x32_bf16 v[20:23], v[28:31], v[210:213], v[222:225]
	v_mfma_f32_16x16x32_bf16 v[20:23], v[24:27], v[214:217], v[20:23]
	v_bitop3_b32 v24, v173, s29, v173 bitop3:0xc
	s_nop 3
	v_and_or_b32 v17, v17, v173, v24
	v_bitop3_b32 v24, v174, s29, v174 bitop3:0xc
	v_and_or_b32 v18, v18, v174, v24
	v_bitop3_b32 v24, v175, s29, v175 bitop3:0xc
	v_and_or_b32 v19, v19, v175, v24
	v_bitop3_b32 v24, v176, s29, v176 bitop3:0xc
	v_and_or_b32 v20, v20, v176, v24
	v_bitop3_b32 v24, v177, s29, v177 bitop3:0xc
	v_and_or_b32 v21, v21, v177, v24
	v_bitop3_b32 v24, v178, s29, v178 bitop3:0xc
	v_cndmask_b32_e64 v16, v242, v16, s[58:59]
	v_and_or_b32 v22, v22, v178, v24
	v_bitop3_b32 v24, v183, s29, v183 bitop3:0xc
	v_and_or_b32 v23, v23, v183, v24
	v_max3_f32 v24, v17, v18, v19
	v_max3_f32 v26, v20, v21, v16
	v_max3_f32 v24, v24, v22, v23
	v_max_f32_e32 v24, v24, v26
	v_add_f32_e32 v25, 0x41000000, v171
	v_cmp_gt_f32_e32 vcc, v24, v25
	s_cbranch_vccz .LBB0_306
	v_mov_b32_e32 v25, v24
	s_nop 1
	v_permlane16_swap_b32 v24, v25
	s_nop 0
	v_max_f32_e32 v25, v25, v25
	v_max_f32_e32 v24, v24, v24
	v_max_f32_e32 v24, v24, v25
	v_mov_b32_e32 v25, v24
	s_nop 1
	v_permlane32_swap_b32 v25, v24
	s_nop 0
	v_max3_f32 v25, v171, v25, v24
	v_sub_f32_e32 v24, v171, v25
	v_exp_f32_e32 v24, v24
	v_mov_b32_e32 v171, v25
	v_pk_mul_f32 v[94:95], v[94:95], v[24:25] op_sel_hi:[1,0]
	v_pk_mul_f32 v[92:93], v[92:93], v[24:25] op_sel_hi:[1,0]
	v_pk_mul_f32 v[90:91], v[90:91], v[24:25] op_sel_hi:[1,0]
	v_pk_mul_f32 v[88:89], v[88:89], v[24:25] op_sel_hi:[1,0]
	v_pk_mul_f32 v[86:87], v[86:87], v[24:25] op_sel_hi:[1,0]
	v_pk_mul_f32 v[84:85], v[84:85], v[24:25] op_sel_hi:[1,0]
	v_pk_mul_f32 v[82:83], v[82:83], v[24:25] op_sel_hi:[1,0]
	v_pk_mul_f32 v[80:81], v[80:81], v[24:25] op_sel_hi:[1,0]
	v_pk_mul_f32 v[98:99], v[98:99], v[24:25] op_sel_hi:[1,0]
	v_pk_mul_f32 v[96:97], v[96:97], v[24:25] op_sel_hi:[1,0]
.LBB0_306:
	v_sub_f32_e32 v16, v16, v171
	v_sub_f32_e32 v17, v17, v171
	v_sub_f32_e32 v18, v18, v171
	v_sub_f32_e32 v19, v19, v171
	v_sub_f32_e32 v20, v20, v171
	v_sub_f32_e32 v21, v21, v171
	v_sub_f32_e32 v22, v22, v171
	v_sub_f32_e32 v23, v23, v171
	v_exp_f32_e32 v16, v16
	v_exp_f32_e32 v17, v17
	v_exp_f32_e32 v18, v18
	v_exp_f32_e32 v19, v19
	v_exp_f32_e32 v20, v20
	v_exp_f32_e32 v21, v21
	v_exp_f32_e32 v22, v22
	v_exp_f32_e32 v23, v23
	v_mov_b32_e32 v37, v36
	v_mov_b32_e32 v38, v36
	v_mov_b32_e32 v39, v36
	v_cvt_pk_bf16_f32 v16, v16, v17
	v_cvt_pk_bf16_f32 v17, v18, v19
	v_cvt_pk_bf16_f32 v18, v20, v21
	v_cvt_pk_bf16_f32 v19, v22, v23
	s_nop 1
	v_mfma_f32_16x16x32_bf16 v[92:95], v[0:3], v[16:19], v[92:95]
	v_mfma_f32_16x16x32_bf16 v[88:91], v[4:7], v[16:19], v[88:91]
	v_mfma_f32_16x16x32_bf16 v[84:87], v[8:11], v[16:19], v[84:87]
	v_mfma_f32_16x16x32_bf16 v[80:83], v[12:15], v[16:19], v[80:83]
	v_mfma_f32_16x16x32_bf16 v[96:99], v[36:39], v[16:19], v[96:99]
	s_add_i32 s27, s27, 2
	s_cmp_eq_u32 s25, 14
	s_cselect_b32 s30, s24, s27
	s_lshl_b32 s62, s30, 1
	s_mov_b32 s63, s1
	s_lshl_b64 s[62:63], s[62:63], 14
	v_lshl_add_u64 v[0:1], v[164:165], 0, s[62:63]
	s_mov_b32 s31, s1
	s_lshl_b64 s[30:31], s[30:31], 15
	global_load_dwordx4 v[20:23], v[0:1], off
	global_load_dwordx4 v[16:19], v[0:1], off offset:1024
	v_add_co_u32_e32 v0, vcc, s72, v0
	v_lshl_add_u64 v[12:13], v[166:167], 0, s[30:31]
	s_nop 0
	v_addc_co_u32_e32 v1, vcc, 0, v1, vcc
	global_load_dwordx4 v[28:31], v[0:1], off
	global_load_dwordx4 v[24:27], v[0:1], off offset:1024
	s_nop 0
	global_load_dwordx4 v[0:3], v[12:13], off
	global_load_dwordx4 v[4:7], v[12:13], off offset:1024
	global_load_dwordx4 v[8:11], v[12:13], off offset:2048
	s_nop 0
	global_load_dwordx4 v[12:15], v[12:13], off offset:3072
	ds_read_b128 v[210:213], v161 offset:22528
	ds_read_b128 v[214:217], v161 offset:23552
	ds_read_b32 v218, v208 offset:192
	ds_read_b32 v222, v208 offset:256
	ds_read_b32 v219, v208 offset:196
	ds_read_b32 v223, v208 offset:260
	ds_read_b32 v220, v208 offset:200
	ds_read_b32 v224, v208 offset:264
	ds_read_b32 v221, v208 offset:204
	ds_read_b32 v225, v208 offset:268
	s_waitcnt vmcnt(15) lgkmcnt(1)
	v_mfma_f32_16x16x32_bf16 v[218:221], v[136:139], v[210:213], v[218:221]
	v_bitop3_b32 v32, v184, s29, v184 bitop3:0xc
	v_bitop3_b32 v34, v185, s29, v185 bitop3:0xc
	v_bitop3_b32 v35, v186, s29, v186 bitop3:0xc
	s_waitcnt vmcnt(13) lgkmcnt(0)
	v_mfma_f32_16x16x32_bf16 v[210:213], v[148:151], v[210:213], v[222:225]
	v_bitop3_b32 v209, v187, s29, v187 bitop3:0xc
	s_waitcnt vmcnt(12)
	v_mfma_f32_16x16x32_bf16 v[210:213], v[144:147], v[214:217], v[210:213]
	v_mfma_f32_16x16x32_bf16 v[218:221], v[140:143], v[214:217], v[218:221]
	v_bitop3_b32 v214, v188, s29, v188 bitop3:0xc
	s_nop 5
	v_and_or_b32 v210, v210, v188, v214
	v_bitop3_b32 v214, v189, s29, v189 bitop3:0xc
	v_and_or_b32 v211, v211, v189, v214
	v_bitop3_b32 v214, v190, s29, v190 bitop3:0xc
	v_and_or_b32 v32, v218, v184, v32
	v_and_or_b32 v34, v219, v185, v34
	v_and_or_b32 v212, v212, v190, v214
	v_bitop3_b32 v214, v191, s29, v191 bitop3:0xc
	v_and_or_b32 v35, v220, v186, v35
	v_and_or_b32 v209, v221, v187, v209
	v_and_or_b32 v213, v213, v191, v214
	v_max3_f32 v214, v210, v211, v32
	v_max3_f32 v216, v34, v212, v35
	v_max3_f32 v214, v214, v209, v213
	v_max_f32_e32 v214, v214, v216
	v_add_f32_e32 v215, 0x41000000, v172
	v_cmp_gt_f32_e32 vcc, v214, v215
	s_cbranch_vccz .LBB0_308
	v_mov_b32_e32 v215, v214
	s_nop 1
	v_permlane16_swap_b32 v214, v215
	s_nop 0
	v_max_f32_e32 v215, v215, v215
	v_max_f32_e32 v214, v214, v214
	v_max_f32_e32 v214, v214, v215
	v_mov_b32_e32 v215, v214
	s_nop 1
	v_permlane32_swap_b32 v214, v215
	s_nop 0
	v_max3_f32 v214, v172, v214, v215
	v_sub_f32_e32 v172, v172, v214
	v_exp_f32_e32 v172, v172
	s_nop 0
	v_pk_mul_f32 v[114:115], v[114:115], v[172:173] op_sel_hi:[1,0]
	v_pk_mul_f32 v[112:113], v[112:113], v[172:173] op_sel_hi:[1,0]
	v_pk_mul_f32 v[110:111], v[110:111], v[172:173] op_sel_hi:[1,0]
	v_pk_mul_f32 v[108:109], v[108:109], v[172:173] op_sel_hi:[1,0]
	v_pk_mul_f32 v[106:107], v[106:107], v[172:173] op_sel_hi:[1,0]
	v_pk_mul_f32 v[104:105], v[104:105], v[172:173] op_sel_hi:[1,0]
	v_pk_mul_f32 v[102:103], v[102:103], v[172:173] op_sel_hi:[1,0]
	v_pk_mul_f32 v[100:101], v[100:101], v[172:173] op_sel_hi:[1,0]
	v_pk_mul_f32 v[118:119], v[118:119], v[172:173] op_sel_hi:[1,0]
	v_pk_mul_f32 v[116:117], v[116:117], v[172:173] op_sel_hi:[1,0]
	v_mov_b32_e32 v172, v214
.LBB0_308:
	v_sub_f32_e32 v210, v210, v172
	v_exp_f32_e32 v214, v210
	v_sub_f32_e32 v210, v211, v172
	v_exp_f32_e32 v215, v210
	v_sub_f32_e32 v210, v212, v172
	v_sub_f32_e32 v32, v32, v172
	v_sub_f32_e32 v34, v34, v172
	v_sub_f32_e32 v35, v35, v172
	v_sub_f32_e32 v209, v209, v172
	v_exp_f32_e32 v216, v210
	v_sub_f32_e32 v210, v213, v172
	v_exp_f32_e32 v32, v32
	v_exp_f32_e32 v34, v34
	v_exp_f32_e32 v35, v35
	v_exp_f32_e32 v209, v209
	v_exp_f32_e32 v213, v210
	v_cvt_pk_bf16_f32 v210, v32, v34
	v_cvt_pk_bf16_f32 v212, v214, v215
	v_cvt_pk_bf16_f32 v211, v35, v209
	v_cvt_pk_bf16_f32 v213, v216, v213
	s_waitcnt vmcnt(11)
	s_nop 0
	v_mfma_f32_16x16x32_bf16 v[112:115], v[120:123], v[210:213], v[112:115]
	s_waitcnt vmcnt(10)
	v_mfma_f32_16x16x32_bf16 v[108:111], v[124:127], v[210:213], v[108:111]
	s_waitcnt vmcnt(9)
	v_mfma_f32_16x16x32_bf16 v[104:107], v[128:131], v[210:213], v[104:107]
	s_waitcnt vmcnt(8)
	v_mfma_f32_16x16x32_bf16 v[100:103], v[132:135], v[210:213], v[100:103]
	v_mfma_f32_16x16x32_bf16 v[116:119], v[36:39], v[210:213], v[116:119]
	ds_read_b128 v[210:213], v161 offset:24576
	ds_read_b128 v[214:217], v161 offset:25600
	ds_read_b32 v218, v208 offset:128
	ds_read_b32 v222, v208 offset:192
	ds_read_b32 v219, v208 offset:132
	ds_read_b32 v223, v208 offset:196
	ds_read_b32 v220, v208 offset:136
	ds_read_b32 v224, v208 offset:200
	ds_read_b32 v221, v208 offset:140
	ds_read_b32 v225, v208 offset:204
	v_bitop3_b32 v32, v192, s29, v192 bitop3:0xc
	v_bitop3_b32 v34, v193, s29, v193 bitop3:0xc
	v_bitop3_b32 v35, v194, s29, v194 bitop3:0xc
	s_waitcnt lgkmcnt(1)
	v_mfma_f32_16x16x32_bf16 v[218:221], v[136:139], v[210:213], v[218:221]
	v_bitop3_b32 v37, v195, s29, v195 bitop3:0xc
	v_bitop3_b32 v38, v196, s29, v196 bitop3:0xc
	v_bitop3_b32 v39, v197, s29, v197 bitop3:0xc
	s_waitcnt lgkmcnt(0)
	v_mfma_f32_16x16x32_bf16 v[210:213], v[148:151], v[210:213], v[222:225]
	v_bitop3_b32 v209, v198, s29, v198 bitop3:0xc
	v_mfma_f32_16x16x32_bf16 v[218:221], v[140:143], v[214:217], v[218:221]
	v_mfma_f32_16x16x32_bf16 v[210:213], v[144:147], v[214:217], v[210:213]
	s_nop 6
	v_and_or_b32 v32, v218, v192, v32
	v_and_or_b32 v34, v219, v193, v34
	v_and_or_b32 v35, v220, v194, v35
	v_and_or_b32 v37, v221, v195, v37
	v_and_or_b32 v38, v210, v196, v38
	v_and_or_b32 v39, v211, v197, v39
	v_and_or_b32 v209, v212, v198, v209
	v_bitop3_b32 v210, v199, s29, v199 bitop3:0xc
	v_and_or_b32 v210, v213, v199, v210
	v_max3_f32 v211, v32, v34, v35
	v_max3_f32 v213, v37, v38, v39
	v_max3_f32 v211, v211, v209, v210
	v_max_f32_e32 v211, v211, v213
	v_add_f32_e32 v212, 0x41000000, v171
	v_cmp_gt_f32_e32 vcc, v211, v212
	s_cbranch_vccz .LBB0_310
	v_mov_b32_e32 v212, v211
	s_nop 1
	v_permlane16_swap_b32 v211, v212
	s_nop 0
	v_max_f32_e32 v212, v212, v212
	v_max_f32_e32 v211, v211, v211
	v_max_f32_e32 v211, v211, v212
	v_mov_b32_e32 v212, v211
	s_nop 1
	v_permlane32_swap_b32 v211, v212
	s_nop 0
	v_max3_f32 v211, v171, v211, v212
	v_sub_f32_e32 v171, v171, v211
	v_exp_f32_e32 v212, v171
	v_mov_b32_e32 v171, v211
	v_pk_mul_f32 v[94:95], v[94:95], v[212:213] op_sel_hi:[1,0]
	v_pk_mul_f32 v[92:93], v[92:93], v[212:213] op_sel_hi:[1,0]
	v_pk_mul_f32 v[90:91], v[90:91], v[212:213] op_sel_hi:[1,0]
	v_pk_mul_f32 v[88:89], v[88:89], v[212:213] op_sel_hi:[1,0]
	v_pk_mul_f32 v[86:87], v[86:87], v[212:213] op_sel_hi:[1,0]
	v_pk_mul_f32 v[84:85], v[84:85], v[212:213] op_sel_hi:[1,0]
	v_pk_mul_f32 v[82:83], v[82:83], v[212:213] op_sel_hi:[1,0]
	v_pk_mul_f32 v[80:81], v[80:81], v[212:213] op_sel_hi:[1,0]
	v_pk_mul_f32 v[98:99], v[98:99], v[212:213] op_sel_hi:[1,0]
	v_pk_mul_f32 v[96:97], v[96:97], v[212:213] op_sel_hi:[1,0]
.LBB0_310:
	v_sub_f32_e32 v35, v35, v171
	v_sub_f32_e32 v37, v37, v171
	v_sub_f32_e32 v38, v38, v171
	v_sub_f32_e32 v39, v39, v171
	v_exp_f32_e32 v35, v35
	v_exp_f32_e32 v37, v37
	v_exp_f32_e32 v38, v38
	v_exp_f32_e32 v39, v39
	v_sub_f32_e32 v32, v32, v171
	v_sub_f32_e32 v34, v34, v171
	v_sub_f32_e32 v209, v209, v171
	v_sub_f32_e32 v210, v210, v171
	v_exp_f32_e32 v32, v32
	v_exp_f32_e32 v34, v34
	v_exp_f32_e32 v209, v209
	v_exp_f32_e32 v213, v210
	v_cvt_pk_bf16_f32 v211, v35, v37
	v_cvt_pk_bf16_f32 v212, v38, v39
	v_mov_b32_e32 v37, v36
	v_mov_b32_e32 v38, v36
	v_mov_b32_e32 v39, v36
	v_cvt_pk_bf16_f32 v210, v32, v34
	v_cvt_pk_bf16_f32 v213, v209, v213
	s_nop 1
	v_mfma_f32_16x16x32_bf16 v[92:95], v[120:123], v[210:213], v[92:95]
	v_mfma_f32_16x16x32_bf16 v[88:91], v[124:127], v[210:213], v[88:91]
	v_mfma_f32_16x16x32_bf16 v[84:87], v[128:131], v[210:213], v[84:87]
	v_mfma_f32_16x16x32_bf16 v[80:83], v[132:135], v[210:213], v[80:83]
	v_mfma_f32_16x16x32_bf16 v[96:99], v[36:39], v[210:213], v[96:99]
	ds_read_b128 v[210:213], v161 offset:26624
	ds_read_b128 v[214:217], v161 offset:27648
	ds_read_b32 v218, v208 offset:64
	ds_read_b32 v222, v208 offset:128
	ds_read_b32 v219, v208 offset:68
	ds_read_b32 v223, v208 offset:132
	ds_read_b32 v220, v208 offset:72
	ds_read_b32 v224, v208 offset:136
	ds_read_b32 v221, v208 offset:76
	ds_read_b32 v225, v208 offset:140
	v_bitop3_b32 v32, v200, s29, v200 bitop3:0xc
	v_bitop3_b32 v34, v201, s29, v201 bitop3:0xc
	v_bitop3_b32 v35, v202, s29, v202 bitop3:0xc
	s_waitcnt lgkmcnt(1)
	v_mfma_f32_16x16x32_bf16 v[136:139], v[136:139], v[210:213], v[218:221]
	v_mfma_f32_16x16x32_bf16 v[136:139], v[140:143], v[214:217], v[136:139]
	s_waitcnt lgkmcnt(0)
	v_mfma_f32_16x16x32_bf16 v[140:143], v[148:151], v[210:213], v[222:225]
	v_mfma_f32_16x16x32_bf16 v[140:143], v[144:147], v[214:217], v[140:143]
	s_nop 4
	v_and_or_b32 v32, v136, v200, v32
	v_bitop3_b32 v136, v203, s29, v203 bitop3:0xc
	v_and_or_b32 v34, v137, v201, v34
	v_and_or_b32 v35, v138, v202, v35
	v_and_or_b32 v136, v139, v203, v136
	v_bitop3_b32 v137, v204, s29, v204 bitop3:0xc
	v_bitop3_b32 v138, v205, s29, v205 bitop3:0xc
	v_bitop3_b32 v139, v206, s29, v206 bitop3:0xc
	v_and_or_b32 v137, v140, v204, v137
	v_and_or_b32 v138, v141, v205, v138
	v_and_or_b32 v139, v142, v206, v139
	v_bitop3_b32 v140, v207, s29, v207 bitop3:0xc
	v_and_or_b32 v140, v143, v207, v140
	v_max3_f32 v141, v32, v34, v35
	v_max3_f32 v143, v136, v137, v138
	v_max3_f32 v141, v141, v139, v140
	v_max_f32_e32 v141, v141, v143
	v_add_f32_e32 v142, 0x41000000, v169
	v_cmp_gt_f32_e32 vcc, v141, v142
	s_cbranch_vccz .LBB0_299
	v_mov_b32_e32 v142, v141
	s_nop 1
	v_permlane16_swap_b32 v141, v142
	s_nop 0
	v_max_f32_e32 v142, v142, v142
	v_max_f32_e32 v141, v141, v141
	v_max_f32_e32 v141, v141, v142
	v_mov_b32_e32 v142, v141
	s_nop 1
	v_permlane32_swap_b32 v141, v142
	s_nop 0
	v_max3_f32 v141, v169, v141, v142
	v_sub_f32_e32 v142, v169, v141
	v_exp_f32_e32 v142, v142
	v_mov_b32_e32 v169, v141
	v_pk_mul_f32 v[54:55], v[54:55], v[142:143] op_sel_hi:[1,0]
	v_pk_mul_f32 v[52:53], v[52:53], v[142:143] op_sel_hi:[1,0]
	v_pk_mul_f32 v[50:51], v[50:51], v[142:143] op_sel_hi:[1,0]
	v_pk_mul_f32 v[48:49], v[48:49], v[142:143] op_sel_hi:[1,0]
	v_pk_mul_f32 v[46:47], v[46:47], v[142:143] op_sel_hi:[1,0]
	v_pk_mul_f32 v[44:45], v[44:45], v[142:143] op_sel_hi:[1,0]
	v_pk_mul_f32 v[42:43], v[42:43], v[142:143] op_sel_hi:[1,0]
	v_pk_mul_f32 v[40:41], v[40:41], v[142:143] op_sel_hi:[1,0]
	v_pk_mul_f32 v[58:59], v[58:59], v[142:143] op_sel_hi:[1,0]
	v_pk_mul_f32 v[56:57], v[56:57], v[142:143] op_sel_hi:[1,0]
	s_branch .LBB0_299

.LBB0_316:
	ds_read_b128 v[128:131], v161 offset:20480
	v_lshl_add_u64 v[34:35], s[34:35], 0, v[162:163]
	s_mov_b32 s25, 0x12708000
	v_add_co_u32_e32 v120, vcc, s25, v34
	s_mov_b32 s25, 0x1270c000
	s_nop 0
	v_addc_co_u32_e32 v121, vcc, 0, v35, vcc
	global_load_dwordx4 v[144:147], v[120:121], off
	global_load_dwordx4 v[140:143], v[120:121], off offset:1024
	ds_read_b128 v[156:159], v161 offset:21504
	s_waitcnt vmcnt(9) lgkmcnt(1)
	v_mfma_f32_16x16x32_bf16 v[120:123], v[20:23], v[128:131], 0
	v_add_co_u32_e32 v34, vcc, s25, v34
	v_lshl_add_u64 v[38:39], s[26:27], 0, v[162:163]
	s_nop 0
	v_addc_co_u32_e32 v35, vcc, 0, v35, vcc
	s_waitcnt vmcnt(8) lgkmcnt(0)
	v_mfma_f32_16x16x32_bf16 v[152:155], v[16:19], v[156:159], v[120:123]
	global_load_dwordx4 v[148:151], v[34:35], off
	global_load_dwordx4 v[136:139], v[34:35], off offset:1024
	s_nop 0
	global_load_dwordx4 v[120:123], v[38:39], off offset:-2048
	global_load_dwordx4 v[124:127], v[38:39], off offset:-1024
	s_nop 2
	s_waitcnt vmcnt(11)
	v_mfma_f32_16x16x32_bf16 v[174:177], v[28:31], v[128:131], 0
	global_load_dwordx4 v[128:131], v[38:39], off
	global_load_dwordx4 v[132:135], v[38:39], off offset:1024
	s_waitcnt vmcnt(12)
	v_mfma_f32_16x16x32_bf16 v[156:159], v[24:27], v[156:159], v[174:177]
	s_nop 4
	v_max3_f32 v32, v152, v153, v154
	s_nop 1
	v_max3_f32 v35, v155, v156, v157
	v_max3_f32 v32, v32, v158, v159
	v_max_f32_e32 v32, v32, v35
	v_add_f32_e32 v34, 0x41000000, v170
	v_cmp_gt_f32_e32 vcc, v32, v34
	s_cbranch_vccz .LBB0_318
	v_mov_b32_e32 v34, v32
	s_nop 1
	v_permlane16_swap_b32 v32, v34
	s_nop 0
	v_max_f32_e32 v34, v34, v34
	v_max_f32_e32 v32, v32, v32
	v_max_f32_e32 v32, v32, v34
	v_mov_b32_e32 v34, v32
	s_nop 1
	v_permlane32_swap_b32 v32, v34
	s_nop 0
	v_max3_f32 v34, v170, v32, v34
	v_sub_f32_e32 v32, v170, v34
	v_exp_f32_e32 v32, v32
	v_mov_b32_e32 v170, v34
	v_pk_mul_f32 v[74:75], v[74:75], v[32:33] op_sel_hi:[1,0]
	v_pk_mul_f32 v[72:73], v[72:73], v[32:33] op_sel_hi:[1,0]
	v_pk_mul_f32 v[70:71], v[70:71], v[32:33] op_sel_hi:[1,0]
	v_pk_mul_f32 v[68:69], v[68:69], v[32:33] op_sel_hi:[1,0]
	v_pk_mul_f32 v[66:67], v[66:67], v[32:33] op_sel_hi:[1,0]
	v_pk_mul_f32 v[64:65], v[64:65], v[32:33] op_sel_hi:[1,0]
	v_pk_mul_f32 v[62:63], v[62:63], v[32:33] op_sel_hi:[1,0]
	v_pk_mul_f32 v[60:61], v[60:61], v[32:33] op_sel_hi:[1,0]
	v_pk_mul_f32 v[78:79], v[78:79], v[32:33] op_sel_hi:[1,0]
	v_pk_mul_f32 v[76:77], v[76:77], v[32:33] op_sel_hi:[1,0]
.LBB0_318:
	v_sub_f32_e32 v35, v154, v170
	v_sub_f32_e32 v37, v155, v170
	v_sub_f32_e32 v38, v156, v170
	v_sub_f32_e32 v39, v157, v170
	v_exp_f32_e32 v35, v35
	v_exp_f32_e32 v37, v37
	v_exp_f32_e32 v38, v38
	v_exp_f32_e32 v39, v39
	v_sub_f32_e32 v32, v152, v170
	v_sub_f32_e32 v152, v158, v170
	v_sub_f32_e32 v34, v153, v170
	v_exp_f32_e32 v155, v152
	v_sub_f32_e32 v152, v159, v170
	v_exp_f32_e32 v32, v32
	v_exp_f32_e32 v34, v34
	v_exp_f32_e32 v156, v152
	v_cvt_pk_bf16_f32 v153, v35, v37
	v_cvt_pk_bf16_f32 v154, v38, v39
	v_mov_b32_e32 v37, v36
	v_mov_b32_e32 v38, v36
	v_mov_b32_e32 v39, v36
	v_cvt_pk_bf16_f32 v152, v32, v34
	v_cvt_pk_bf16_f32 v155, v155, v156
	s_waitcnt vmcnt(11)
	s_nop 0
	v_mfma_f32_16x16x32_bf16 v[72:75], v[0:3], v[152:155], v[72:75]
	s_waitcnt vmcnt(10)
	v_mfma_f32_16x16x32_bf16 v[68:71], v[4:7], v[152:155], v[68:71]
	s_waitcnt vmcnt(9)
	v_mfma_f32_16x16x32_bf16 v[64:67], v[8:11], v[152:155], v[64:67]
	s_waitcnt vmcnt(8)
	v_mfma_f32_16x16x32_bf16 v[60:63], v[12:15], v[152:155], v[60:63]
	v_mfma_f32_16x16x32_bf16 v[76:79], v[36:39], v[152:155], v[76:79]
	ds_read_b128 v[152:155], v161 offset:22528
	ds_read_b128 v[174:177], v161 offset:23552
	s_waitcnt lgkmcnt(1)
	v_mfma_f32_16x16x32_bf16 v[156:159], v[20:23], v[152:155], 0
	v_mfma_f32_16x16x32_bf16 v[152:155], v[28:31], v[152:155], 0
	s_waitcnt lgkmcnt(0)
	v_mfma_f32_16x16x32_bf16 v[156:159], v[16:19], v[174:177], v[156:159]
	v_mfma_f32_16x16x32_bf16 v[152:155], v[24:27], v[174:177], v[152:155]
	s_nop 6
	v_max3_f32 v32, v156, v157, v158
	v_max3_f32 v35, v159, v152, v153
	v_max3_f32 v32, v32, v154, v155
	v_max_f32_e32 v32, v32, v35
	v_add_f32_e32 v34, 0x41000000, v172
	v_cmp_gt_f32_e32 vcc, v32, v34
	s_cbranch_vccz .LBB0_320
	v_mov_b32_e32 v34, v32
	s_nop 1
	v_permlane16_swap_b32 v32, v34
	s_nop 0
	v_max_f32_e32 v34, v34, v34
	v_max_f32_e32 v32, v32, v32
	v_max_f32_e32 v32, v32, v34
	v_mov_b32_e32 v34, v32
	s_nop 1
	v_permlane32_swap_b32 v34, v32
	s_nop 0
	v_max3_f32 v34, v172, v34, v32
	v_sub_f32_e32 v32, v172, v34
	v_exp_f32_e32 v32, v32
	v_mov_b32_e32 v172, v34
	v_pk_mul_f32 v[114:115], v[114:115], v[32:33] op_sel_hi:[1,0]
	v_pk_mul_f32 v[112:113], v[112:113], v[32:33] op_sel_hi:[1,0]
	v_pk_mul_f32 v[110:111], v[110:111], v[32:33] op_sel_hi:[1,0]
	v_pk_mul_f32 v[108:109], v[108:109], v[32:33] op_sel_hi:[1,0]
	v_pk_mul_f32 v[106:107], v[106:107], v[32:33] op_sel_hi:[1,0]
	v_pk_mul_f32 v[104:105], v[104:105], v[32:33] op_sel_hi:[1,0]
	v_pk_mul_f32 v[102:103], v[102:103], v[32:33] op_sel_hi:[1,0]
	v_pk_mul_f32 v[100:101], v[100:101], v[32:33] op_sel_hi:[1,0]
	v_pk_mul_f32 v[118:119], v[118:119], v[32:33] op_sel_hi:[1,0]
	v_pk_mul_f32 v[116:117], v[116:117], v[32:33] op_sel_hi:[1,0]
.LBB0_320:
	v_sub_f32_e32 v152, v152, v172
	v_sub_f32_e32 v34, v157, v172
	v_exp_f32_e32 v157, v152
	v_sub_f32_e32 v152, v153, v172
	v_sub_f32_e32 v35, v158, v172
	v_exp_f32_e32 v158, v152
	v_sub_f32_e32 v152, v154, v172
	v_sub_f32_e32 v32, v156, v172
	v_sub_f32_e32 v156, v159, v172
	v_exp_f32_e32 v159, v152
	v_sub_f32_e32 v152, v155, v172
	v_exp_f32_e32 v32, v32
	v_exp_f32_e32 v34, v34
	v_exp_f32_e32 v35, v35
	v_exp_f32_e32 v156, v156
	v_exp_f32_e32 v155, v152
	v_cvt_pk_bf16_f32 v152, v32, v34
	v_cvt_pk_bf16_f32 v154, v157, v158
	v_cvt_pk_bf16_f32 v153, v35, v156
	v_cvt_pk_bf16_f32 v155, v159, v155
	s_nop 1
	v_mfma_f32_16x16x32_bf16 v[112:115], v[0:3], v[152:155], v[112:115]
	v_mfma_f32_16x16x32_bf16 v[108:111], v[4:7], v[152:155], v[108:111]
	v_mfma_f32_16x16x32_bf16 v[104:107], v[8:11], v[152:155], v[104:107]
	v_mfma_f32_16x16x32_bf16 v[100:103], v[12:15], v[152:155], v[100:103]
	v_mfma_f32_16x16x32_bf16 v[116:119], v[36:39], v[152:155], v[116:119]
	ds_read_b128 v[152:155], v161 offset:24576
	ds_read_b128 v[174:177], v161 offset:25600
	s_waitcnt lgkmcnt(1)
	v_mfma_f32_16x16x32_bf16 v[156:159], v[20:23], v[152:155], 0
	v_mfma_f32_16x16x32_bf16 v[152:155], v[28:31], v[152:155], 0
	s_waitcnt lgkmcnt(0)
	v_mfma_f32_16x16x32_bf16 v[156:159], v[16:19], v[174:177], v[156:159]
	v_mfma_f32_16x16x32_bf16 v[152:155], v[24:27], v[174:177], v[152:155]
	s_nop 6
	v_max3_f32 v32, v156, v157, v158
	v_max3_f32 v35, v159, v152, v153
	v_max3_f32 v32, v32, v154, v155
	v_max_f32_e32 v32, v32, v35
	v_add_f32_e32 v34, 0x41000000, v171
	v_cmp_gt_f32_e32 vcc, v32, v34
	s_cbranch_vccz .LBB0_322
	v_mov_b32_e32 v34, v32
	s_nop 1
	v_permlane16_swap_b32 v32, v34
	s_nop 0
	v_max_f32_e32 v34, v34, v34
	v_max_f32_e32 v32, v32, v32
	v_max_f32_e32 v32, v32, v34
	v_mov_b32_e32 v34, v32
	s_nop 1
	v_permlane32_swap_b32 v32, v34
	s_nop 0
	v_max3_f32 v34, v171, v32, v34
	v_sub_f32_e32 v32, v171, v34
	v_exp_f32_e32 v32, v32
	v_mov_b32_e32 v171, v34
	v_pk_mul_f32 v[94:95], v[94:95], v[32:33] op_sel_hi:[1,0]
	v_pk_mul_f32 v[92:93], v[92:93], v[32:33] op_sel_hi:[1,0]
	v_pk_mul_f32 v[90:91], v[90:91], v[32:33] op_sel_hi:[1,0]
	v_pk_mul_f32 v[88:89], v[88:89], v[32:33] op_sel_hi:[1,0]
	v_pk_mul_f32 v[86:87], v[86:87], v[32:33] op_sel_hi:[1,0]
	v_pk_mul_f32 v[84:85], v[84:85], v[32:33] op_sel_hi:[1,0]
	v_pk_mul_f32 v[82:83], v[82:83], v[32:33] op_sel_hi:[1,0]
	v_pk_mul_f32 v[80:81], v[80:81], v[32:33] op_sel_hi:[1,0]
	v_pk_mul_f32 v[98:99], v[98:99], v[32:33] op_sel_hi:[1,0]
	v_pk_mul_f32 v[96:97], v[96:97], v[32:33] op_sel_hi:[1,0]
.LBB0_322:
	v_sub_f32_e32 v35, v158, v171
	v_sub_f32_e32 v37, v159, v171
	v_sub_f32_e32 v38, v152, v171
	v_sub_f32_e32 v39, v153, v171
	v_exp_f32_e32 v35, v35
	v_exp_f32_e32 v37, v37
	v_exp_f32_e32 v38, v38
	v_exp_f32_e32 v39, v39
	v_sub_f32_e32 v152, v154, v171
	v_sub_f32_e32 v32, v156, v171
	v_sub_f32_e32 v34, v157, v171
	v_exp_f32_e32 v156, v152
	v_sub_f32_e32 v152, v155, v171
	v_exp_f32_e32 v32, v32
	v_exp_f32_e32 v34, v34
	v_exp_f32_e32 v155, v152
	v_cvt_pk_bf16_f32 v153, v35, v37
	v_cvt_pk_bf16_f32 v154, v38, v39
	v_mov_b32_e32 v37, v36
	v_mov_b32_e32 v38, v36
	v_mov_b32_e32 v39, v36
	v_cvt_pk_bf16_f32 v152, v32, v34
	v_cvt_pk_bf16_f32 v155, v156, v155
	s_nop 1
	v_mfma_f32_16x16x32_bf16 v[92:95], v[0:3], v[152:155], v[92:95]
	v_mfma_f32_16x16x32_bf16 v[88:91], v[4:7], v[152:155], v[88:91]
	v_mfma_f32_16x16x32_bf16 v[84:87], v[8:11], v[152:155], v[84:87]
	v_mfma_f32_16x16x32_bf16 v[80:83], v[12:15], v[152:155], v[80:83]
	v_mfma_f32_16x16x32_bf16 v[96:99], v[36:39], v[152:155], v[96:99]
	ds_read_b128 v[152:155], v161 offset:26624
	s_waitcnt lgkmcnt(0)
	v_mfma_f32_16x16x32_bf16 v[20:23], v[20:23], v[152:155], 0
	v_mfma_f32_16x16x32_bf16 v[28:31], v[28:31], v[152:155], 0
	ds_read_b128 v[152:155], v161 offset:27648
	s_waitcnt lgkmcnt(0)
	v_mfma_f32_16x16x32_bf16 v[16:19], v[16:19], v[152:155], v[20:23]
	s_nop 7
	v_mfma_f32_16x16x32_bf16 v[20:23], v[24:27], v[152:155], v[28:31]
	s_nop 7
	v_max3_f32 v24, v16, v17, v18
	v_max3_f32 v25, v19, v20, v21
	v_max3_f32 v24, v24, v22, v23
	v_max_f32_e32 v24, v24, v25
	v_add_f32_e32 v25, 0x41000000, v169
	v_cmp_gt_f32_e32 vcc, v24, v25
	s_cbranch_vccz .LBB0_324
	v_mov_b32_e32 v25, v24
	s_nop 1
	v_permlane16_swap_b32 v24, v25
	s_nop 0
	v_max_f32_e32 v25, v25, v25
	v_max_f32_e32 v24, v24, v24
	v_max_f32_e32 v24, v24, v25
	v_mov_b32_e32 v25, v24
	s_nop 1
	v_permlane32_swap_b32 v24, v25
	s_nop 0
	v_max3_f32 v25, v169, v24, v25
	v_sub_f32_e32 v24, v169, v25
	v_exp_f32_e32 v24, v24
	v_mov_b32_e32 v169, v25
	v_pk_mul_f32 v[54:55], v[54:55], v[24:25] op_sel_hi:[1,0]
	v_pk_mul_f32 v[52:53], v[52:53], v[24:25] op_sel_hi:[1,0]
	v_pk_mul_f32 v[50:51], v[50:51], v[24:25] op_sel_hi:[1,0]
	v_pk_mul_f32 v[48:49], v[48:49], v[24:25] op_sel_hi:[1,0]
	v_pk_mul_f32 v[46:47], v[46:47], v[24:25] op_sel_hi:[1,0]
	v_pk_mul_f32 v[44:45], v[44:45], v[24:25] op_sel_hi:[1,0]
	v_pk_mul_f32 v[42:43], v[42:43], v[24:25] op_sel_hi:[1,0]
	v_pk_mul_f32 v[40:41], v[40:41], v[24:25] op_sel_hi:[1,0]
	v_pk_mul_f32 v[58:59], v[58:59], v[24:25] op_sel_hi:[1,0]
	v_pk_mul_f32 v[56:57], v[56:57], v[24:25] op_sel_hi:[1,0]
.LBB0_324:
	v_sub_f32_e32 v16, v16, v169
	v_sub_f32_e32 v17, v17, v169
	v_sub_f32_e32 v18, v18, v169
	v_sub_f32_e32 v19, v19, v169
	v_sub_f32_e32 v20, v20, v169
	v_sub_f32_e32 v21, v21, v169
	v_sub_f32_e32 v22, v22, v169
	v_sub_f32_e32 v23, v23, v169
	v_exp_f32_e32 v16, v16
	v_exp_f32_e32 v17, v17
	v_exp_f32_e32 v18, v18
	v_exp_f32_e32 v19, v19
	v_exp_f32_e32 v20, v20
	v_exp_f32_e32 v21, v21
	v_exp_f32_e32 v22, v22
	v_exp_f32_e32 v23, v23
	v_cvt_pk_bf16_f32 v16, v16, v17
	v_cvt_pk_bf16_f32 v17, v18, v19
	v_cvt_pk_bf16_f32 v18, v20, v21
	v_cvt_pk_bf16_f32 v19, v22, v23
	s_add_i32 s25, s0, -2
	s_nop 0
	v_mfma_f32_16x16x32_bf16 v[52:55], v[0:3], v[16:19], v[52:55]
	v_mfma_f32_16x16x32_bf16 v[48:51], v[4:7], v[16:19], v[48:51]
	v_mfma_f32_16x16x32_bf16 v[44:47], v[8:11], v[16:19], v[44:47]
	v_mfma_f32_16x16x32_bf16 v[40:43], v[12:15], v[16:19], v[40:43]
	v_mfma_f32_16x16x32_bf16 v[56:59], v[36:39], v[16:19], v[56:59]
	s_cmp_lt_u32 s25, 6
	s_cselect_b32 s30, s0, 0
	s_add_i32 s30, s30, s24
	s_lshl_b32 s42, s30, 1
	ds_read_b128 v[8:11], v161 offset:20480
	s_ashr_i32 s43, s42, 31
	s_lshl_b64 s[42:43], s[42:43], 14
	v_lshl_add_u64 v[4:5], v[164:165], 0, s[42:43]
	global_load_dwordx4 v[20:23], v[4:5], off
	global_load_dwordx4 v[16:19], v[4:5], off offset:1024
	ds_read_b128 v[156:159], v161 offset:21504
	s_waitcnt vmcnt(9) lgkmcnt(1)
	v_mfma_f32_16x16x32_bf16 v[0:3], v[144:147], v[8:11], 0
	s_ashr_i32 s31, s30, 31
	v_add_co_u32_e32 v4, vcc, s72, v4
	s_lshl_b64 s[30:31], s[30:31], 15
	s_nop 0
	v_addc_co_u32_e32 v5, vcc, 0, v5, vcc
	v_lshl_add_u64 v[12:13], v[166:167], 0, s[30:31]
	s_waitcnt vmcnt(8) lgkmcnt(0)
	v_mfma_f32_16x16x32_bf16 v[152:155], v[140:143], v[156:159], v[0:3]
	global_load_dwordx4 v[28:31], v[4:5], off
	global_load_dwordx4 v[24:27], v[4:5], off offset:1024
	s_nop 0
	global_load_dwordx4 v[0:3], v[12:13], off
	global_load_dwordx4 v[4:7], v[12:13], off offset:1024
	s_nop 2
	s_waitcnt vmcnt(11)
	v_mfma_f32_16x16x32_bf16 v[174:177], v[148:151], v[8:11], 0
	global_load_dwordx4 v[8:11], v[12:13], off offset:2048
	s_nop 0
	global_load_dwordx4 v[12:15], v[12:13], off offset:3072
	s_waitcnt vmcnt(12)
	v_mfma_f32_16x16x32_bf16 v[156:159], v[136:139], v[156:159], v[174:177]
	s_nop 4
	v_max3_f32 v32, v152, v153, v154
	s_nop 1
	v_max3_f32 v35, v155, v156, v157
	v_max3_f32 v32, v32, v158, v159
	v_max_f32_e32 v32, v32, v35
	v_add_f32_e32 v34, 0x41000000, v170
	v_cmp_gt_f32_e32 vcc, v32, v34
	s_cbranch_vccz .LBB0_326
	v_mov_b32_e32 v34, v32
	s_nop 1
	v_permlane16_swap_b32 v32, v34
	s_nop 0
	v_max_f32_e32 v34, v34, v34
	v_max_f32_e32 v32, v32, v32
	v_max_f32_e32 v32, v32, v34
	v_mov_b32_e32 v34, v32
	s_nop 1
	v_permlane32_swap_b32 v32, v34
	s_nop 0
	v_max3_f32 v34, v170, v32, v34
	v_sub_f32_e32 v32, v170, v34
	v_exp_f32_e32 v32, v32
	v_mov_b32_e32 v170, v34
	v_pk_mul_f32 v[74:75], v[74:75], v[32:33] op_sel_hi:[1,0]
	v_pk_mul_f32 v[72:73], v[72:73], v[32:33] op_sel_hi:[1,0]
	v_pk_mul_f32 v[70:71], v[70:71], v[32:33] op_sel_hi:[1,0]
	v_pk_mul_f32 v[68:69], v[68:69], v[32:33] op_sel_hi:[1,0]
	v_pk_mul_f32 v[66:67], v[66:67], v[32:33] op_sel_hi:[1,0]
	v_pk_mul_f32 v[64:65], v[64:65], v[32:33] op_sel_hi:[1,0]
	v_pk_mul_f32 v[62:63], v[62:63], v[32:33] op_sel_hi:[1,0]
	v_pk_mul_f32 v[60:61], v[60:61], v[32:33] op_sel_hi:[1,0]
	v_pk_mul_f32 v[78:79], v[78:79], v[32:33] op_sel_hi:[1,0]
	v_pk_mul_f32 v[76:77], v[76:77], v[32:33] op_sel_hi:[1,0]
.LBB0_326:
	v_sub_f32_e32 v35, v154, v170
	v_sub_f32_e32 v37, v155, v170
	v_sub_f32_e32 v38, v156, v170
	v_sub_f32_e32 v39, v157, v170
	v_exp_f32_e32 v35, v35
	v_exp_f32_e32 v37, v37
	v_exp_f32_e32 v38, v38
	v_exp_f32_e32 v39, v39
	v_sub_f32_e32 v32, v152, v170
	v_sub_f32_e32 v152, v158, v170
	v_sub_f32_e32 v34, v153, v170
	v_exp_f32_e32 v155, v152
	v_sub_f32_e32 v152, v159, v170
	v_exp_f32_e32 v32, v32
	v_exp_f32_e32 v34, v34
	v_exp_f32_e32 v156, v152
	v_cvt_pk_bf16_f32 v153, v35, v37
	v_cvt_pk_bf16_f32 v154, v38, v39
	v_mov_b32_e32 v37, v36
	v_mov_b32_e32 v38, v36
	v_mov_b32_e32 v39, v36
	v_cvt_pk_bf16_f32 v152, v32, v34
	v_cvt_pk_bf16_f32 v155, v155, v156
	s_waitcnt vmcnt(11)
	s_nop 0
	v_mfma_f32_16x16x32_bf16 v[72:75], v[120:123], v[152:155], v[72:75]
	s_waitcnt vmcnt(10)
	v_mfma_f32_16x16x32_bf16 v[68:71], v[124:127], v[152:155], v[68:71]
	s_waitcnt vmcnt(9)
	v_mfma_f32_16x16x32_bf16 v[64:67], v[128:131], v[152:155], v[64:67]
	s_waitcnt vmcnt(8)
	v_mfma_f32_16x16x32_bf16 v[60:63], v[132:135], v[152:155], v[60:63]
	v_mfma_f32_16x16x32_bf16 v[76:79], v[36:39], v[152:155], v[76:79]
	ds_read_b128 v[152:155], v161 offset:22528
	ds_read_b128 v[174:177], v161 offset:23552
	s_waitcnt lgkmcnt(1)
	v_mfma_f32_16x16x32_bf16 v[156:159], v[144:147], v[152:155], 0
	v_mfma_f32_16x16x32_bf16 v[152:155], v[148:151], v[152:155], 0
	s_waitcnt lgkmcnt(0)
	v_mfma_f32_16x16x32_bf16 v[156:159], v[140:143], v[174:177], v[156:159]
	v_mfma_f32_16x16x32_bf16 v[152:155], v[136:139], v[174:177], v[152:155]
	s_nop 6
	v_max3_f32 v32, v156, v157, v158
	v_max3_f32 v35, v159, v152, v153
	v_max3_f32 v32, v32, v154, v155
	v_max_f32_e32 v32, v32, v35
	v_add_f32_e32 v34, 0x41000000, v172
	v_cmp_gt_f32_e32 vcc, v32, v34
	s_cbranch_vccz .LBB0_328
	v_mov_b32_e32 v34, v32
	s_nop 1
	v_permlane16_swap_b32 v32, v34
	s_nop 0
	v_max_f32_e32 v34, v34, v34
	v_max_f32_e32 v32, v32, v32
	v_max_f32_e32 v32, v32, v34
	v_mov_b32_e32 v34, v32
	s_nop 1
	v_permlane32_swap_b32 v32, v34
	s_nop 0
	v_max3_f32 v34, v172, v32, v34
	v_sub_f32_e32 v32, v172, v34
	v_exp_f32_e32 v32, v32
	v_mov_b32_e32 v172, v34
	v_pk_mul_f32 v[114:115], v[114:115], v[32:33] op_sel_hi:[1,0]
	v_pk_mul_f32 v[112:113], v[112:113], v[32:33] op_sel_hi:[1,0]
	v_pk_mul_f32 v[110:111], v[110:111], v[32:33] op_sel_hi:[1,0]
	v_pk_mul_f32 v[108:109], v[108:109], v[32:33] op_sel_hi:[1,0]
	v_pk_mul_f32 v[106:107], v[106:107], v[32:33] op_sel_hi:[1,0]
	v_pk_mul_f32 v[104:105], v[104:105], v[32:33] op_sel_hi:[1,0]
	v_pk_mul_f32 v[102:103], v[102:103], v[32:33] op_sel_hi:[1,0]
	v_pk_mul_f32 v[100:101], v[100:101], v[32:33] op_sel_hi:[1,0]
	v_pk_mul_f32 v[118:119], v[118:119], v[32:33] op_sel_hi:[1,0]
	v_pk_mul_f32 v[116:117], v[116:117], v[32:33] op_sel_hi:[1,0]
.LBB0_328:
	v_sub_f32_e32 v152, v152, v172
	v_sub_f32_e32 v34, v157, v172
	v_exp_f32_e32 v157, v152
	v_sub_f32_e32 v152, v153, v172
	v_sub_f32_e32 v35, v158, v172
	v_exp_f32_e32 v158, v152
	v_sub_f32_e32 v152, v154, v172
	v_sub_f32_e32 v32, v156, v172
	v_sub_f32_e32 v156, v159, v172
	v_exp_f32_e32 v159, v152
	v_sub_f32_e32 v152, v155, v172
	v_exp_f32_e32 v32, v32
	v_exp_f32_e32 v34, v34
	v_exp_f32_e32 v35, v35
	v_exp_f32_e32 v156, v156
	v_exp_f32_e32 v155, v152
	v_cvt_pk_bf16_f32 v152, v32, v34
	v_cvt_pk_bf16_f32 v154, v157, v158
	v_cvt_pk_bf16_f32 v153, v35, v156
	v_cvt_pk_bf16_f32 v155, v159, v155
	s_nop 1
	v_mfma_f32_16x16x32_bf16 v[112:115], v[120:123], v[152:155], v[112:115]
	v_mfma_f32_16x16x32_bf16 v[108:111], v[124:127], v[152:155], v[108:111]
	v_mfma_f32_16x16x32_bf16 v[104:107], v[128:131], v[152:155], v[104:107]
	v_mfma_f32_16x16x32_bf16 v[100:103], v[132:135], v[152:155], v[100:103]
	v_mfma_f32_16x16x32_bf16 v[116:119], v[36:39], v[152:155], v[116:119]
	ds_read_b128 v[152:155], v161 offset:24576
	ds_read_b128 v[174:177], v161 offset:25600
	s_waitcnt lgkmcnt(1)
	v_mfma_f32_16x16x32_bf16 v[156:159], v[144:147], v[152:155], 0
	v_mfma_f32_16x16x32_bf16 v[152:155], v[148:151], v[152:155], 0
	s_waitcnt lgkmcnt(0)
	v_mfma_f32_16x16x32_bf16 v[156:159], v[140:143], v[174:177], v[156:159]
	v_mfma_f32_16x16x32_bf16 v[152:155], v[136:139], v[174:177], v[152:155]
	s_nop 6
	v_max3_f32 v32, v156, v157, v158
	v_max3_f32 v35, v159, v152, v153
	v_max3_f32 v32, v32, v154, v155
	v_max_f32_e32 v32, v32, v35
	v_add_f32_e32 v34, 0x41000000, v171
	v_cmp_gt_f32_e32 vcc, v32, v34
	s_cbranch_vccz .LBB0_330
	v_mov_b32_e32 v34, v32
	s_nop 1
	v_permlane16_swap_b32 v32, v34
	s_nop 0
	v_max_f32_e32 v34, v34, v34
	v_max_f32_e32 v32, v32, v32
	v_max_f32_e32 v32, v32, v34
	v_mov_b32_e32 v34, v32
	s_nop 1
	v_permlane32_swap_b32 v34, v32
	s_nop 0
	v_max3_f32 v34, v171, v34, v32
	v_sub_f32_e32 v32, v171, v34
	v_exp_f32_e32 v32, v32
	v_mov_b32_e32 v171, v34
	v_pk_mul_f32 v[94:95], v[94:95], v[32:33] op_sel_hi:[1,0]
	v_pk_mul_f32 v[92:93], v[92:93], v[32:33] op_sel_hi:[1,0]
	v_pk_mul_f32 v[90:91], v[90:91], v[32:33] op_sel_hi:[1,0]
	v_pk_mul_f32 v[88:89], v[88:89], v[32:33] op_sel_hi:[1,0]
	v_pk_mul_f32 v[86:87], v[86:87], v[32:33] op_sel_hi:[1,0]
	v_pk_mul_f32 v[84:85], v[84:85], v[32:33] op_sel_hi:[1,0]
	v_pk_mul_f32 v[82:83], v[82:83], v[32:33] op_sel_hi:[1,0]
	v_pk_mul_f32 v[80:81], v[80:81], v[32:33] op_sel_hi:[1,0]
	v_pk_mul_f32 v[98:99], v[98:99], v[32:33] op_sel_hi:[1,0]
	v_pk_mul_f32 v[96:97], v[96:97], v[32:33] op_sel_hi:[1,0]
.LBB0_330:
	v_sub_f32_e32 v35, v158, v171
	v_sub_f32_e32 v37, v159, v171
	v_sub_f32_e32 v38, v152, v171
	v_sub_f32_e32 v39, v153, v171
	v_exp_f32_e32 v35, v35
	v_exp_f32_e32 v37, v37
	v_exp_f32_e32 v38, v38
	v_exp_f32_e32 v39, v39
	v_sub_f32_e32 v152, v154, v171
	v_sub_f32_e32 v32, v156, v171
	v_sub_f32_e32 v34, v157, v171
	v_exp_f32_e32 v156, v152
	v_sub_f32_e32 v152, v155, v171
	v_exp_f32_e32 v32, v32
	v_exp_f32_e32 v34, v34
	v_exp_f32_e32 v155, v152
	v_cvt_pk_bf16_f32 v153, v35, v37
	v_cvt_pk_bf16_f32 v154, v38, v39
	v_mov_b32_e32 v37, v36
	v_mov_b32_e32 v38, v36
	v_mov_b32_e32 v39, v36
	v_cvt_pk_bf16_f32 v152, v32, v34
	v_cvt_pk_bf16_f32 v155, v156, v155
	s_nop 1
	v_mfma_f32_16x16x32_bf16 v[92:95], v[120:123], v[152:155], v[92:95]
	v_mfma_f32_16x16x32_bf16 v[88:91], v[124:127], v[152:155], v[88:91]
	v_mfma_f32_16x16x32_bf16 v[84:87], v[128:131], v[152:155], v[84:87]
	v_mfma_f32_16x16x32_bf16 v[80:83], v[132:135], v[152:155], v[80:83]
	v_mfma_f32_16x16x32_bf16 v[96:99], v[36:39], v[152:155], v[96:99]
	ds_read_b128 v[152:155], v161 offset:26624
	s_waitcnt lgkmcnt(0)
	v_mfma_f32_16x16x32_bf16 v[144:147], v[144:147], v[152:155], 0
	v_mfma_f32_16x16x32_bf16 v[148:151], v[148:151], v[152:155], 0
	ds_read_b128 v[152:155], v161 offset:27648
	s_waitcnt lgkmcnt(0)
	v_mfma_f32_16x16x32_bf16 v[140:143], v[140:143], v[152:155], v[144:147]
	v_mfma_f32_16x16x32_bf16 v[136:139], v[136:139], v[152:155], v[148:151]
	s_nop 6
	v_max3_f32 v32, v140, v141, v142
	v_max3_f32 v35, v143, v136, v137
	v_max3_f32 v32, v32, v138, v139
	v_max_f32_e32 v32, v32, v35
	v_add_f32_e32 v34, 0x41000000, v169
	v_cmp_gt_f32_e32 vcc, v32, v34
	s_cbranch_vccz .LBB0_315
	v_mov_b32_e32 v34, v32
	s_nop 1
	v_permlane16_swap_b32 v32, v34
	s_nop 0
	v_max_f32_e32 v34, v34, v34
	v_max_f32_e32 v32, v32, v32
	v_max_f32_e32 v32, v32, v34
	v_mov_b32_e32 v34, v32
	s_nop 1
	v_permlane32_swap_b32 v32, v34
	s_nop 0
	v_max3_f32 v34, v169, v32, v34
	v_sub_f32_e32 v32, v169, v34
	v_exp_f32_e32 v32, v32
	v_mov_b32_e32 v169, v34
	v_pk_mul_f32 v[54:55], v[54:55], v[32:33] op_sel_hi:[1,0]
	v_pk_mul_f32 v[52:53], v[52:53], v[32:33] op_sel_hi:[1,0]
	v_pk_mul_f32 v[50:51], v[50:51], v[32:33] op_sel_hi:[1,0]
	v_pk_mul_f32 v[48:49], v[48:49], v[32:33] op_sel_hi:[1,0]
	v_pk_mul_f32 v[46:47], v[46:47], v[32:33] op_sel_hi:[1,0]
	v_pk_mul_f32 v[44:45], v[44:45], v[32:33] op_sel_hi:[1,0]
	v_pk_mul_f32 v[42:43], v[42:43], v[32:33] op_sel_hi:[1,0]
	v_pk_mul_f32 v[40:41], v[40:41], v[32:33] op_sel_hi:[1,0]
	v_pk_mul_f32 v[58:59], v[58:59], v[32:33] op_sel_hi:[1,0]
	v_pk_mul_f32 v[56:57], v[56:57], v[32:33] op_sel_hi:[1,0]
	s_branch .LBB0_315

.LBB0_349:
	v_lshl_add_u64 v[34:35], v[152:153], 0, s[34:35]
	s_mov_b32 s0, 0x11708000
	v_add_co_u32_e32 v120, vcc, s0, v34
	s_mov_b32 s0, 0x1170c000
	s_nop 0
	v_addc_co_u32_e32 v121, vcc, 0, v35, vcc
	v_add_co_u32_e32 v34, vcc, s0, v34
	v_lshl_add_u64 v[38:39], v[154:155], 0, s[34:35]
	s_nop 0
	v_addc_co_u32_e32 v35, vcc, 0, v35, vcc
	global_load_dwordx4 v[136:139], v[120:121], off
	global_load_dwordx4 v[140:143], v[120:121], off offset:1024
	global_load_dwordx4 v[148:151], v[34:35], off
	global_load_dwordx4 v[144:147], v[34:35], off offset:1024
	s_nop 0
	global_load_dwordx4 v[120:123], v[38:39], off offset:-2048
	global_load_dwordx4 v[124:127], v[38:39], off offset:-1024
	global_load_dwordx4 v[128:131], v[38:39], off
	global_load_dwordx4 v[132:135], v[38:39], off offset:1024
	ds_read_b128 v[214:217], v168 offset:20480
	ds_read_b128 v[218:221], v168 offset:21504
	ds_read_b32 v222, v212 offset:128
	ds_read_b32 v246, v212 offset:192
	ds_read_b32 v223, v212 offset:132
	ds_read_b32 v247, v212 offset:196
	ds_read_b32 v224, v212 offset:136
	ds_read_b32 v248, v212 offset:200
	ds_read_b32 v225, v212 offset:140
	ds_read_b32 v249, v212 offset:204
	s_waitcnt vmcnt(15) lgkmcnt(1)
	v_mfma_f32_16x16x32_bf16 v[222:225], v[24:27], v[214:217], v[222:225]
	s_waitcnt vmcnt(13) lgkmcnt(0)
	v_mfma_f32_16x16x32_bf16 v[214:217], v[28:31], v[214:217], v[246:249]
	v_mfma_f32_16x16x32_bf16 v[222:225], v[16:19], v[218:221], v[222:225]
	s_waitcnt vmcnt(12)
	v_mfma_f32_16x16x32_bf16 v[216:219], v[20:23], v[218:221], v[214:217]
	s_nop 5
	v_cndmask_b32_e64 v214, v242, v222, s[42:43]
	v_cndmask_b32_e64 v213, v242, v223, s[46:47]
	v_cndmask_b32_e64 v39, v242, v224, s[48:49]
	v_cndmask_b32_e64 v38, v242, v225, s[50:51]
	v_cndmask_b32_e64 v37, v242, v216, s[44:45]
	v_cndmask_b32_e64 v35, v242, v217, s[52:53]
	v_cndmask_b32_e64 v34, v242, v218, s[54:55]
	v_cndmask_b32_e64 v32, v242, v219, s[56:57]
	v_max3_f32 v215, v214, v213, v39
	v_max3_f32 v217, v38, v37, v35
	v_max3_f32 v215, v215, v34, v32
	v_max_f32_e32 v215, v215, v217
	v_add_f32_e32 v216, 0x41000000, v170
	v_cmp_gt_f32_e32 vcc, v215, v216
	s_cbranch_vccz .LBB0_351
	v_mov_b32_e32 v216, v215
	s_nop 1
	v_permlane16_swap_b32 v215, v216
	s_nop 0
	v_max_f32_e32 v216, v216, v216
	v_max_f32_e32 v215, v215, v215
	v_max_f32_e32 v215, v215, v216
	v_mov_b32_e32 v216, v215
	s_nop 1
	v_permlane32_swap_b32 v216, v215
	s_nop 0
	v_max3_f32 v215, v170, v216, v215
	v_sub_f32_e32 v170, v170, v215
	v_exp_f32_e32 v170, v170
	s_nop 0
	v_pk_mul_f32 v[74:75], v[74:75], v[170:171] op_sel_hi:[1,0]
	v_pk_mul_f32 v[72:73], v[72:73], v[170:171] op_sel_hi:[1,0]
	v_pk_mul_f32 v[70:71], v[70:71], v[170:171] op_sel_hi:[1,0]
	v_pk_mul_f32 v[68:69], v[68:69], v[170:171] op_sel_hi:[1,0]
	v_pk_mul_f32 v[66:67], v[66:67], v[170:171] op_sel_hi:[1,0]
	v_pk_mul_f32 v[64:65], v[64:65], v[170:171] op_sel_hi:[1,0]
	v_pk_mul_f32 v[62:63], v[62:63], v[170:171] op_sel_hi:[1,0]
	v_pk_mul_f32 v[60:61], v[60:61], v[170:171] op_sel_hi:[1,0]
	v_pk_mul_f32 v[78:79], v[78:79], v[170:171] op_sel_hi:[1,0]
	v_pk_mul_f32 v[76:77], v[76:77], v[170:171] op_sel_hi:[1,0]
	v_mov_b32_e32 v170, v215
.LBB0_351:
	v_sub_f32_e32 v39, v39, v170
	v_sub_f32_e32 v38, v38, v170
	v_sub_f32_e32 v37, v37, v170
	v_sub_f32_e32 v35, v35, v170
	v_exp_f32_e32 v39, v39
	v_exp_f32_e32 v38, v38
	v_exp_f32_e32 v37, v37
	v_exp_f32_e32 v35, v35
	v_sub_f32_e32 v214, v214, v170
	v_sub_f32_e32 v213, v213, v170
	v_sub_f32_e32 v34, v34, v170
	v_sub_f32_e32 v32, v32, v170
	v_exp_f32_e32 v214, v214
	v_exp_f32_e32 v213, v213
	v_exp_f32_e32 v34, v34
	v_exp_f32_e32 v32, v32
	v_cvt_pk_bf16_f32 v215, v39, v38
	v_cvt_pk_bf16_f32 v216, v37, v35
	v_mov_b32_e32 v37, v36
	v_mov_b32_e32 v38, v36
	v_mov_b32_e32 v39, v36
	v_cvt_pk_bf16_f32 v214, v214, v213
	v_cvt_pk_bf16_f32 v217, v34, v32
	s_waitcnt vmcnt(11)
	s_nop 0
	v_mfma_f32_16x16x32_bf16 v[72:75], v[0:3], v[214:217], v[72:75]
	s_waitcnt vmcnt(10)
	v_mfma_f32_16x16x32_bf16 v[68:71], v[4:7], v[214:217], v[68:71]
	s_waitcnt vmcnt(9)
	v_mfma_f32_16x16x32_bf16 v[64:67], v[8:11], v[214:217], v[64:67]
	s_waitcnt vmcnt(8)
	v_mfma_f32_16x16x32_bf16 v[60:63], v[12:15], v[214:217], v[60:63]
	v_mfma_f32_16x16x32_bf16 v[76:79], v[36:39], v[214:217], v[76:79]
	ds_read_b128 v[214:217], v168 offset:22528
	ds_read_b128 v[218:221], v168 offset:23552
	ds_read_b32 v222, v212 offset:64
	ds_read_b32 v246, v212 offset:128
	ds_read_b32 v223, v212 offset:68
	ds_read_b32 v247, v212 offset:132
	ds_read_b32 v224, v212 offset:72
	ds_read_b32 v248, v212 offset:136
	ds_read_b32 v225, v212 offset:76
	ds_read_b32 v249, v212 offset:140
	v_bitop3_b32 v32, v156, s29, v156 bitop3:0xc
	v_bitop3_b32 v34, v157, s29, v157 bitop3:0xc
	v_bitop3_b32 v35, v158, s29, v158 bitop3:0xc
	s_waitcnt lgkmcnt(1)
	v_mfma_f32_16x16x32_bf16 v[222:225], v[24:27], v[214:217], v[222:225]
	v_bitop3_b32 v213, v159, s29, v159 bitop3:0xc
	s_waitcnt lgkmcnt(0)
	v_mfma_f32_16x16x32_bf16 v[214:217], v[28:31], v[214:217], v[246:249]
	v_mfma_f32_16x16x32_bf16 v[214:217], v[20:23], v[218:221], v[214:217]
	v_mfma_f32_16x16x32_bf16 v[222:225], v[16:19], v[218:221], v[222:225]
	v_bitop3_b32 v218, v173, s29, v173 bitop3:0xc
	s_nop 5
	v_and_or_b32 v214, v214, v173, v218
	v_bitop3_b32 v218, v174, s29, v174 bitop3:0xc
	v_and_or_b32 v215, v215, v174, v218
	v_bitop3_b32 v218, v175, s29, v175 bitop3:0xc
	v_and_or_b32 v32, v222, v156, v32
	v_and_or_b32 v34, v223, v157, v34
	v_and_or_b32 v216, v216, v175, v218
	v_bitop3_b32 v218, v176, s29, v176 bitop3:0xc
	v_and_or_b32 v35, v224, v158, v35
	v_and_or_b32 v213, v225, v159, v213
	v_and_or_b32 v217, v217, v176, v218
	v_max3_f32 v218, v214, v215, v32
	v_max3_f32 v220, v34, v216, v35
	v_max3_f32 v218, v218, v213, v217
	v_max_f32_e32 v218, v218, v220
	v_add_f32_e32 v219, 0x41000000, v172
	v_cmp_gt_f32_e32 vcc, v218, v219
	s_cbranch_vccz .LBB0_353
	v_mov_b32_e32 v219, v218
	s_nop 1
	v_permlane16_swap_b32 v218, v219
	s_nop 0
	v_max_f32_e32 v219, v219, v219
	v_max_f32_e32 v218, v218, v218
	v_max_f32_e32 v218, v218, v219
	v_mov_b32_e32 v219, v218
	s_nop 1
	v_permlane32_swap_b32 v218, v219
	s_nop 0
	v_max3_f32 v218, v172, v218, v219
	v_sub_f32_e32 v172, v172, v218
	v_exp_f32_e32 v172, v172
	s_nop 0
	v_pk_mul_f32 v[114:115], v[114:115], v[172:173] op_sel_hi:[1,0]
	v_pk_mul_f32 v[112:113], v[112:113], v[172:173] op_sel_hi:[1,0]
	v_pk_mul_f32 v[110:111], v[110:111], v[172:173] op_sel_hi:[1,0]
	v_pk_mul_f32 v[108:109], v[108:109], v[172:173] op_sel_hi:[1,0]
	v_pk_mul_f32 v[106:107], v[106:107], v[172:173] op_sel_hi:[1,0]
	v_pk_mul_f32 v[104:105], v[104:105], v[172:173] op_sel_hi:[1,0]
	v_pk_mul_f32 v[102:103], v[102:103], v[172:173] op_sel_hi:[1,0]
	v_pk_mul_f32 v[100:101], v[100:101], v[172:173] op_sel_hi:[1,0]
	v_pk_mul_f32 v[118:119], v[118:119], v[172:173] op_sel_hi:[1,0]
	v_pk_mul_f32 v[116:117], v[116:117], v[172:173] op_sel_hi:[1,0]
	v_mov_b32_e32 v172, v218
.LBB0_353:
	v_sub_f32_e32 v214, v214, v172
	v_exp_f32_e32 v218, v214
	v_sub_f32_e32 v214, v215, v172
	v_exp_f32_e32 v219, v214
	v_sub_f32_e32 v214, v216, v172
	v_sub_f32_e32 v32, v32, v172
	v_sub_f32_e32 v34, v34, v172
	v_sub_f32_e32 v35, v35, v172
	v_sub_f32_e32 v213, v213, v172
	v_exp_f32_e32 v220, v214
	v_sub_f32_e32 v214, v217, v172
	v_exp_f32_e32 v32, v32
	v_exp_f32_e32 v34, v34
	v_exp_f32_e32 v35, v35
	v_exp_f32_e32 v213, v213
	v_exp_f32_e32 v217, v214
	v_cvt_pk_bf16_f32 v214, v32, v34
	v_cvt_pk_bf16_f32 v216, v218, v219
	v_cvt_pk_bf16_f32 v215, v35, v213
	v_cvt_pk_bf16_f32 v217, v220, v217
	s_nop 1
	v_mfma_f32_16x16x32_bf16 v[112:115], v[0:3], v[214:217], v[112:115]
	v_mfma_f32_16x16x32_bf16 v[108:111], v[4:7], v[214:217], v[108:111]
	v_mfma_f32_16x16x32_bf16 v[104:107], v[8:11], v[214:217], v[104:107]
	v_mfma_f32_16x16x32_bf16 v[100:103], v[12:15], v[214:217], v[100:103]
	v_mfma_f32_16x16x32_bf16 v[116:119], v[36:39], v[214:217], v[116:119]
	ds_read_b128 v[214:217], v168 offset:24576
	ds_read_b128 v[218:221], v168 offset:25600
	ds_read_b32 v222, v212
	ds_read_b32 v246, v212 offset:64
	ds_read_b32 v223, v212 offset:4
	ds_read_b32 v247, v212 offset:68
	ds_read_b32 v224, v212 offset:8
	ds_read_b32 v248, v212 offset:72
	ds_read_b32 v225, v212 offset:12
	ds_read_b32 v249, v212 offset:76
	s_waitcnt lgkmcnt(1)
	v_mfma_f32_16x16x32_bf16 v[24:27], v[24:27], v[214:217], v[222:225]
	v_mfma_f32_16x16x32_bf16 v[16:19], v[16:19], v[218:221], v[24:27]
	s_waitcnt lgkmcnt(0)
	s_nop 5
	v_mfma_f32_16x16x32_bf16 v[24:27], v[28:31], v[214:217], v[246:249]
	v_mfma_f32_16x16x32_bf16 v[20:23], v[20:23], v[218:221], v[24:27]
	s_nop 4
	v_cndmask_b32_e64 v16, v242, v16, s[58:59]
	s_nop 0
	v_bitop3_b32 v24, v177, s29, v177 bitop3:0xc
	v_and_or_b32 v17, v17, v177, v24
	v_bitop3_b32 v24, v178, s29, v178 bitop3:0xc
	v_and_or_b32 v18, v18, v178, v24
	v_bitop3_b32 v24, v183, s29, v183 bitop3:0xc
	v_and_or_b32 v19, v19, v183, v24
	v_bitop3_b32 v24, v184, s29, v184 bitop3:0xc
	v_and_or_b32 v20, v20, v184, v24
	v_bitop3_b32 v24, v185, s29, v185 bitop3:0xc
	v_and_or_b32 v21, v21, v185, v24
	v_bitop3_b32 v24, v186, s29, v186 bitop3:0xc
	v_and_or_b32 v22, v22, v186, v24
	v_bitop3_b32 v24, v187, s29, v187 bitop3:0xc
	v_and_or_b32 v23, v23, v187, v24
	v_max3_f32 v24, v16, v17, v18
	v_max3_f32 v26, v19, v20, v21
	v_max3_f32 v24, v24, v22, v23
	v_max_f32_e32 v24, v24, v26
	v_add_f32_e32 v25, 0x41000000, v171
	v_cmp_gt_f32_e32 vcc, v24, v25
	s_cbranch_vccz .LBB0_355
	v_mov_b32_e32 v25, v24
	s_nop 1
	v_permlane16_swap_b32 v24, v25
	s_nop 0
	v_max_f32_e32 v25, v25, v25
	v_max_f32_e32 v24, v24, v24
	v_max_f32_e32 v24, v24, v25
	v_mov_b32_e32 v25, v24
	s_nop 1
	v_permlane32_swap_b32 v24, v25
	s_nop 0
	v_max3_f32 v25, v171, v24, v25
	v_sub_f32_e32 v24, v171, v25
	v_exp_f32_e32 v24, v24
	v_mov_b32_e32 v171, v25
	v_pk_mul_f32 v[94:95], v[94:95], v[24:25] op_sel_hi:[1,0]
	v_pk_mul_f32 v[92:93], v[92:93], v[24:25] op_sel_hi:[1,0]
	v_pk_mul_f32 v[90:91], v[90:91], v[24:25] op_sel_hi:[1,0]
	v_pk_mul_f32 v[88:89], v[88:89], v[24:25] op_sel_hi:[1,0]
	v_pk_mul_f32 v[86:87], v[86:87], v[24:25] op_sel_hi:[1,0]
	v_pk_mul_f32 v[84:85], v[84:85], v[24:25] op_sel_hi:[1,0]
	v_pk_mul_f32 v[82:83], v[82:83], v[24:25] op_sel_hi:[1,0]
	v_pk_mul_f32 v[80:81], v[80:81], v[24:25] op_sel_hi:[1,0]
	v_pk_mul_f32 v[98:99], v[98:99], v[24:25] op_sel_hi:[1,0]
	v_pk_mul_f32 v[96:97], v[96:97], v[24:25] op_sel_hi:[1,0]
.LBB0_355:
	v_sub_f32_e32 v16, v16, v171
	v_sub_f32_e32 v17, v17, v171
	v_sub_f32_e32 v18, v18, v171
	v_sub_f32_e32 v19, v19, v171
	v_sub_f32_e32 v20, v20, v171
	v_sub_f32_e32 v21, v21, v171
	v_sub_f32_e32 v22, v22, v171
	v_sub_f32_e32 v23, v23, v171
	v_exp_f32_e32 v16, v16
	v_exp_f32_e32 v17, v17
	v_exp_f32_e32 v18, v18
	v_exp_f32_e32 v19, v19
	v_exp_f32_e32 v20, v20
	v_exp_f32_e32 v21, v21
	v_exp_f32_e32 v22, v22
	v_exp_f32_e32 v23, v23
	v_mov_b32_e32 v37, v36
	v_mov_b32_e32 v38, v36
	v_mov_b32_e32 v39, v36
	v_cvt_pk_bf16_f32 v16, v16, v17
	v_cvt_pk_bf16_f32 v17, v18, v19
	v_cvt_pk_bf16_f32 v18, v20, v21
	v_cvt_pk_bf16_f32 v19, v22, v23
	s_nop 1
	v_mfma_f32_16x16x32_bf16 v[92:95], v[0:3], v[16:19], v[92:95]
	v_mfma_f32_16x16x32_bf16 v[88:91], v[4:7], v[16:19], v[88:91]
	v_mfma_f32_16x16x32_bf16 v[84:87], v[8:11], v[16:19], v[84:87]
	v_mfma_f32_16x16x32_bf16 v[80:83], v[12:15], v[16:19], v[80:83]
	v_mfma_f32_16x16x32_bf16 v[96:99], v[36:39], v[16:19], v[96:99]
	s_cmp_eq_u32 s34, 0x70000
	s_cselect_b32 s40, s60, s30
	s_lshl_b32 s0, s40, 1
	s_lshl_b64 s[60:61], s[0:1], 14
	v_lshl_add_u64 v[0:1], v[164:165], 0, s[60:61]
	s_mov_b32 s41, s1
	s_lshl_b64 s[40:41], s[40:41], 15
	global_load_dwordx4 v[24:27], v[0:1], off
	global_load_dwordx4 v[16:19], v[0:1], off offset:1024
	v_add_co_u32_e32 v0, vcc, s72, v0
	v_lshl_add_u64 v[12:13], v[166:167], 0, s[40:41]
	s_nop 0
	v_addc_co_u32_e32 v1, vcc, 0, v1, vcc
	global_load_dwordx4 v[28:31], v[0:1], off
	global_load_dwordx4 v[20:23], v[0:1], off offset:1024
	s_nop 0
	global_load_dwordx4 v[0:3], v[12:13], off
	global_load_dwordx4 v[4:7], v[12:13], off offset:1024
	global_load_dwordx4 v[8:11], v[12:13], off offset:2048
	s_nop 0
	global_load_dwordx4 v[12:15], v[12:13], off offset:3072
	ds_read_b128 v[214:217], v168 offset:22528
	ds_read_b128 v[218:221], v168 offset:23552
	ds_read_b32 v222, v212 offset:192
	ds_read_b32 v246, v212 offset:256
	ds_read_b32 v223, v212 offset:196
	ds_read_b32 v247, v212 offset:260
	ds_read_b32 v224, v212 offset:200
	ds_read_b32 v248, v212 offset:264
	ds_read_b32 v225, v212 offset:204
	ds_read_b32 v249, v212 offset:268
	s_waitcnt vmcnt(15) lgkmcnt(1)
	v_mfma_f32_16x16x32_bf16 v[222:225], v[136:139], v[214:217], v[222:225]
	v_bitop3_b32 v32, v188, s29, v188 bitop3:0xc
	v_bitop3_b32 v34, v189, s29, v189 bitop3:0xc
	v_bitop3_b32 v35, v190, s29, v190 bitop3:0xc
	s_waitcnt vmcnt(13) lgkmcnt(0)
	v_mfma_f32_16x16x32_bf16 v[214:217], v[148:151], v[214:217], v[246:249]
	v_bitop3_b32 v213, v191, s29, v191 bitop3:0xc
	s_waitcnt vmcnt(12)
	v_mfma_f32_16x16x32_bf16 v[214:217], v[144:147], v[218:221], v[214:217]
	v_mfma_f32_16x16x32_bf16 v[222:225], v[140:143], v[218:221], v[222:225]
	v_bitop3_b32 v218, v192, s29, v192 bitop3:0xc
	s_nop 5
	v_and_or_b32 v214, v214, v192, v218
	v_bitop3_b32 v218, v193, s29, v193 bitop3:0xc
	v_and_or_b32 v215, v215, v193, v218
	v_bitop3_b32 v218, v194, s29, v194 bitop3:0xc
	v_and_or_b32 v32, v222, v188, v32
	v_and_or_b32 v34, v223, v189, v34
	v_and_or_b32 v216, v216, v194, v218
	v_bitop3_b32 v218, v195, s29, v195 bitop3:0xc
	v_and_or_b32 v35, v224, v190, v35
	v_and_or_b32 v213, v225, v191, v213
	v_and_or_b32 v217, v217, v195, v218
	v_max3_f32 v218, v214, v215, v32
	v_max3_f32 v220, v34, v216, v35
	v_max3_f32 v218, v218, v213, v217
	v_max_f32_e32 v218, v218, v220
	v_add_f32_e32 v219, 0x41000000, v172
	v_cmp_gt_f32_e32 vcc, v218, v219
	s_cbranch_vccz .LBB0_357
	v_mov_b32_e32 v219, v218
	s_nop 1
	v_permlane16_swap_b32 v218, v219
	s_nop 0
	v_max_f32_e32 v219, v219, v219
	v_max_f32_e32 v218, v218, v218
	v_max_f32_e32 v218, v218, v219
	v_mov_b32_e32 v219, v218
	s_nop 1
	v_permlane32_swap_b32 v219, v218
	s_nop 0
	v_max3_f32 v218, v172, v219, v218
	v_sub_f32_e32 v172, v172, v218
	v_exp_f32_e32 v172, v172
	s_nop 0
	v_pk_mul_f32 v[114:115], v[114:115], v[172:173] op_sel_hi:[1,0]
	v_pk_mul_f32 v[112:113], v[112:113], v[172:173] op_sel_hi:[1,0]
	v_pk_mul_f32 v[110:111], v[110:111], v[172:173] op_sel_hi:[1,0]
	v_pk_mul_f32 v[108:109], v[108:109], v[172:173] op_sel_hi:[1,0]
	v_pk_mul_f32 v[106:107], v[106:107], v[172:173] op_sel_hi:[1,0]
	v_pk_mul_f32 v[104:105], v[104:105], v[172:173] op_sel_hi:[1,0]
	v_pk_mul_f32 v[102:103], v[102:103], v[172:173] op_sel_hi:[1,0]
	v_pk_mul_f32 v[100:101], v[100:101], v[172:173] op_sel_hi:[1,0]
	v_pk_mul_f32 v[118:119], v[118:119], v[172:173] op_sel_hi:[1,0]
	v_pk_mul_f32 v[116:117], v[116:117], v[172:173] op_sel_hi:[1,0]
	v_mov_b32_e32 v172, v218
.LBB0_357:
	v_sub_f32_e32 v214, v214, v172
	v_exp_f32_e32 v218, v214
	v_sub_f32_e32 v214, v215, v172
	v_exp_f32_e32 v219, v214
	v_sub_f32_e32 v214, v216, v172
	v_sub_f32_e32 v32, v32, v172
	v_sub_f32_e32 v34, v34, v172
	v_sub_f32_e32 v35, v35, v172
	v_sub_f32_e32 v213, v213, v172
	v_exp_f32_e32 v220, v214
	v_sub_f32_e32 v214, v217, v172
	v_exp_f32_e32 v32, v32
	v_exp_f32_e32 v34, v34
	v_exp_f32_e32 v35, v35
	v_exp_f32_e32 v213, v213
	v_exp_f32_e32 v217, v214
	v_cvt_pk_bf16_f32 v214, v32, v34
	v_cvt_pk_bf16_f32 v216, v218, v219
	v_cvt_pk_bf16_f32 v215, v35, v213
	v_cvt_pk_bf16_f32 v217, v220, v217
	s_waitcnt vmcnt(11)
	s_nop 0
	v_mfma_f32_16x16x32_bf16 v[112:115], v[120:123], v[214:217], v[112:115]
	s_waitcnt vmcnt(10)
	v_mfma_f32_16x16x32_bf16 v[108:111], v[124:127], v[214:217], v[108:111]
	s_waitcnt vmcnt(9)
	v_mfma_f32_16x16x32_bf16 v[104:107], v[128:131], v[214:217], v[104:107]
	s_waitcnt vmcnt(8)
	v_mfma_f32_16x16x32_bf16 v[100:103], v[132:135], v[214:217], v[100:103]
	v_mfma_f32_16x16x32_bf16 v[116:119], v[36:39], v[214:217], v[116:119]
	ds_read_b128 v[214:217], v168 offset:24576
	ds_read_b128 v[218:221], v168 offset:25600
	ds_read_b32 v222, v212 offset:128
	ds_read_b32 v246, v212 offset:192
	ds_read_b32 v223, v212 offset:132
	ds_read_b32 v247, v212 offset:196
	ds_read_b32 v224, v212 offset:136
	ds_read_b32 v248, v212 offset:200
	ds_read_b32 v225, v212 offset:140
	ds_read_b32 v249, v212 offset:204
	v_bitop3_b32 v32, v196, s29, v196 bitop3:0xc
	v_bitop3_b32 v34, v197, s29, v197 bitop3:0xc
	v_bitop3_b32 v35, v198, s29, v198 bitop3:0xc
	s_waitcnt lgkmcnt(1)
	v_mfma_f32_16x16x32_bf16 v[222:225], v[136:139], v[214:217], v[222:225]
	v_bitop3_b32 v37, v199, s29, v199 bitop3:0xc
	v_bitop3_b32 v38, v200, s29, v200 bitop3:0xc
	v_bitop3_b32 v39, v201, s29, v201 bitop3:0xc
	s_waitcnt lgkmcnt(0)
	v_mfma_f32_16x16x32_bf16 v[214:217], v[148:151], v[214:217], v[246:249]
	v_bitop3_b32 v213, v202, s29, v202 bitop3:0xc
	v_readlane_b32 s60, v252, 47
	v_mfma_f32_16x16x32_bf16 v[222:225], v[140:143], v[218:221], v[222:225]
	v_mfma_f32_16x16x32_bf16 v[214:217], v[144:147], v[218:221], v[214:217]
	s_nop 6
	v_and_or_b32 v32, v222, v196, v32
	v_and_or_b32 v34, v223, v197, v34
	v_and_or_b32 v35, v224, v198, v35
	v_and_or_b32 v37, v225, v199, v37
	v_and_or_b32 v38, v214, v200, v38
	v_and_or_b32 v39, v215, v201, v39
	v_and_or_b32 v213, v216, v202, v213
	v_bitop3_b32 v214, v203, s29, v203 bitop3:0xc
	v_and_or_b32 v214, v217, v203, v214
	v_max3_f32 v215, v32, v34, v35
	v_max3_f32 v217, v37, v38, v39
	v_max3_f32 v215, v215, v213, v214
	v_max_f32_e32 v215, v215, v217
	v_add_f32_e32 v216, 0x41000000, v171
	v_cmp_gt_f32_e32 vcc, v215, v216
	s_cbranch_vccz .LBB0_359
	v_mov_b32_e32 v216, v215
	s_nop 1
	v_permlane16_swap_b32 v215, v216
	s_nop 0
	v_max_f32_e32 v216, v216, v216
	v_max_f32_e32 v215, v215, v215
	v_max_f32_e32 v215, v215, v216
	v_mov_b32_e32 v216, v215
	s_nop 1
	v_permlane32_swap_b32 v215, v216
	s_nop 0
	v_max3_f32 v215, v171, v215, v216
	v_sub_f32_e32 v171, v171, v215
	v_exp_f32_e32 v216, v171
	v_mov_b32_e32 v171, v215
	v_pk_mul_f32 v[94:95], v[94:95], v[216:217] op_sel_hi:[1,0]
	v_pk_mul_f32 v[92:93], v[92:93], v[216:217] op_sel_hi:[1,0]
	v_pk_mul_f32 v[90:91], v[90:91], v[216:217] op_sel_hi:[1,0]
	v_pk_mul_f32 v[88:89], v[88:89], v[216:217] op_sel_hi:[1,0]
	v_pk_mul_f32 v[86:87], v[86:87], v[216:217] op_sel_hi:[1,0]
	v_pk_mul_f32 v[84:85], v[84:85], v[216:217] op_sel_hi:[1,0]
	v_pk_mul_f32 v[82:83], v[82:83], v[216:217] op_sel_hi:[1,0]
	v_pk_mul_f32 v[80:81], v[80:81], v[216:217] op_sel_hi:[1,0]
	v_pk_mul_f32 v[98:99], v[98:99], v[216:217] op_sel_hi:[1,0]
	v_pk_mul_f32 v[96:97], v[96:97], v[216:217] op_sel_hi:[1,0]
.LBB0_359:
	v_sub_f32_e32 v35, v35, v171
	v_sub_f32_e32 v37, v37, v171
	v_sub_f32_e32 v38, v38, v171
	v_sub_f32_e32 v39, v39, v171
	v_exp_f32_e32 v35, v35
	v_exp_f32_e32 v37, v37
	v_exp_f32_e32 v38, v38
	v_exp_f32_e32 v39, v39
	v_sub_f32_e32 v32, v32, v171
	v_sub_f32_e32 v34, v34, v171
	v_sub_f32_e32 v213, v213, v171
	v_sub_f32_e32 v214, v214, v171
	v_exp_f32_e32 v32, v32
	v_exp_f32_e32 v34, v34
	v_exp_f32_e32 v213, v213
	v_exp_f32_e32 v217, v214
	v_cvt_pk_bf16_f32 v215, v35, v37
	v_cvt_pk_bf16_f32 v216, v38, v39
	v_mov_b32_e32 v37, v36
	v_mov_b32_e32 v38, v36
	v_mov_b32_e32 v39, v36
	v_cvt_pk_bf16_f32 v214, v32, v34
	v_cvt_pk_bf16_f32 v217, v213, v217
	s_nop 1
	v_mfma_f32_16x16x32_bf16 v[92:95], v[120:123], v[214:217], v[92:95]
	v_mfma_f32_16x16x32_bf16 v[88:91], v[124:127], v[214:217], v[88:91]
	v_mfma_f32_16x16x32_bf16 v[84:87], v[128:131], v[214:217], v[84:87]
	v_mfma_f32_16x16x32_bf16 v[80:83], v[132:135], v[214:217], v[80:83]
	v_mfma_f32_16x16x32_bf16 v[96:99], v[36:39], v[214:217], v[96:99]
	ds_read_b128 v[214:217], v168 offset:26624
	ds_read_b128 v[218:221], v168 offset:27648
	ds_read_b32 v222, v212 offset:64
	ds_read_b32 v246, v212 offset:128
	ds_read_b32 v223, v212 offset:68
	ds_read_b32 v247, v212 offset:132
	ds_read_b32 v224, v212 offset:72
	ds_read_b32 v248, v212 offset:136
	ds_read_b32 v225, v212 offset:76
	ds_read_b32 v249, v212 offset:140
	v_bitop3_b32 v32, v204, s29, v204 bitop3:0xc
	v_bitop3_b32 v34, v205, s29, v205 bitop3:0xc
	v_bitop3_b32 v35, v206, s29, v206 bitop3:0xc
	s_waitcnt lgkmcnt(1)
	v_mfma_f32_16x16x32_bf16 v[136:139], v[136:139], v[214:217], v[222:225]
	v_mfma_f32_16x16x32_bf16 v[136:139], v[140:143], v[218:221], v[136:139]
	s_waitcnt lgkmcnt(0)
	v_mfma_f32_16x16x32_bf16 v[140:143], v[148:151], v[214:217], v[246:249]
	v_mfma_f32_16x16x32_bf16 v[140:143], v[144:147], v[218:221], v[140:143]
	s_nop 4
	v_and_or_b32 v32, v136, v204, v32
	v_bitop3_b32 v136, v207, s29, v207 bitop3:0xc
	v_and_or_b32 v34, v137, v205, v34
	v_and_or_b32 v35, v138, v206, v35
	v_and_or_b32 v136, v139, v207, v136
	v_bitop3_b32 v137, v208, s29, v208 bitop3:0xc
	v_bitop3_b32 v138, v209, s29, v209 bitop3:0xc
	v_bitop3_b32 v139, v210, s29, v210 bitop3:0xc
	v_and_or_b32 v137, v140, v208, v137
	v_and_or_b32 v138, v141, v209, v138
	v_and_or_b32 v139, v142, v210, v139
	v_bitop3_b32 v140, v211, s29, v211 bitop3:0xc
	v_and_or_b32 v140, v143, v211, v140
	v_max3_f32 v141, v32, v34, v35
	v_max3_f32 v143, v136, v137, v138
	v_max3_f32 v141, v141, v139, v140
	v_max_f32_e32 v141, v141, v143
	v_add_f32_e32 v142, 0x41000000, v169
	v_cmp_gt_f32_e32 vcc, v141, v142
	s_cbranch_vccz .LBB0_348
	v_mov_b32_e32 v142, v141
	s_nop 1
	v_permlane16_swap_b32 v141, v142
	s_nop 0
	v_max_f32_e32 v142, v142, v142
	v_max_f32_e32 v141, v141, v141
	v_max_f32_e32 v141, v141, v142
	v_mov_b32_e32 v142, v141
	s_nop 1
	v_permlane32_swap_b32 v141, v142
	s_nop 0
	v_max3_f32 v141, v169, v141, v142
	v_sub_f32_e32 v142, v169, v141
	v_exp_f32_e32 v142, v142
	v_mov_b32_e32 v169, v141
	v_pk_mul_f32 v[54:55], v[54:55], v[142:143] op_sel_hi:[1,0]
	v_pk_mul_f32 v[52:53], v[52:53], v[142:143] op_sel_hi:[1,0]
	v_pk_mul_f32 v[50:51], v[50:51], v[142:143] op_sel_hi:[1,0]
	v_pk_mul_f32 v[48:49], v[48:49], v[142:143] op_sel_hi:[1,0]
	v_pk_mul_f32 v[46:47], v[46:47], v[142:143] op_sel_hi:[1,0]
	v_pk_mul_f32 v[44:45], v[44:45], v[142:143] op_sel_hi:[1,0]
	v_pk_mul_f32 v[42:43], v[42:43], v[142:143] op_sel_hi:[1,0]
	v_pk_mul_f32 v[40:41], v[40:41], v[142:143] op_sel_hi:[1,0]
	v_pk_mul_f32 v[58:59], v[58:59], v[142:143] op_sel_hi:[1,0]
	v_pk_mul_f32 v[56:57], v[56:57], v[142:143] op_sel_hi:[1,0]
	s_branch .LBB0_348

.LBB0_363:
	ds_read_b128 v[128:131], v168 offset:20480
	v_lshl_add_u64 v[34:35], s[24:25], 0, v[162:163]
	s_mov_b32 s0, 0x12708000
	v_add_co_u32_e32 v120, vcc, s0, v34
	s_mov_b32 s0, 0x1270c000
	s_nop 0
	v_addc_co_u32_e32 v121, vcc, 0, v35, vcc
	global_load_dwordx4 v[144:147], v[120:121], off
	global_load_dwordx4 v[140:143], v[120:121], off offset:1024
	ds_read_b128 v[156:159], v168 offset:21504
	s_waitcnt vmcnt(9) lgkmcnt(1)
	v_mfma_f32_16x16x32_bf16 v[120:123], v[24:27], v[128:131], 0
	v_add_co_u32_e32 v34, vcc, s0, v34
	v_lshl_add_u64 v[38:39], s[26:27], 0, v[162:163]
	s_nop 0
	v_addc_co_u32_e32 v35, vcc, 0, v35, vcc
	s_waitcnt vmcnt(8) lgkmcnt(0)
	v_mfma_f32_16x16x32_bf16 v[152:155], v[16:19], v[156:159], v[120:123]
	global_load_dwordx4 v[148:151], v[34:35], off
	global_load_dwordx4 v[136:139], v[34:35], off offset:1024
	s_nop 0
	global_load_dwordx4 v[120:123], v[38:39], off offset:-2048
	global_load_dwordx4 v[124:127], v[38:39], off offset:-1024
	s_nop 2
	s_waitcnt vmcnt(11)
	v_mfma_f32_16x16x32_bf16 v[174:177], v[28:31], v[128:131], 0
	global_load_dwordx4 v[128:131], v[38:39], off
	global_load_dwordx4 v[132:135], v[38:39], off offset:1024
	s_waitcnt vmcnt(12)
	v_mfma_f32_16x16x32_bf16 v[156:159], v[20:23], v[156:159], v[174:177]
	s_nop 4
	v_max3_f32 v32, v152, v153, v154
	s_nop 1
	v_max3_f32 v35, v155, v156, v157
	v_max3_f32 v32, v32, v158, v159
	v_max_f32_e32 v32, v32, v35
	v_add_f32_e32 v34, 0x41000000, v170
	v_cmp_gt_f32_e32 vcc, v32, v34
	s_cbranch_vccz .LBB0_365
	v_mov_b32_e32 v34, v32
	s_nop 1
	v_permlane16_swap_b32 v32, v34
	s_nop 0
	v_max_f32_e32 v34, v34, v34
	v_max_f32_e32 v32, v32, v32
	v_max_f32_e32 v32, v32, v34
	v_mov_b32_e32 v34, v32
	s_nop 1
	v_permlane32_swap_b32 v32, v34
	s_nop 0
	v_max3_f32 v34, v170, v32, v34
	v_sub_f32_e32 v32, v170, v34
	v_exp_f32_e32 v32, v32
	v_mov_b32_e32 v170, v34
	v_pk_mul_f32 v[74:75], v[74:75], v[32:33] op_sel_hi:[1,0]
	v_pk_mul_f32 v[72:73], v[72:73], v[32:33] op_sel_hi:[1,0]
	v_pk_mul_f32 v[70:71], v[70:71], v[32:33] op_sel_hi:[1,0]
	v_pk_mul_f32 v[68:69], v[68:69], v[32:33] op_sel_hi:[1,0]
	v_pk_mul_f32 v[66:67], v[66:67], v[32:33] op_sel_hi:[1,0]
	v_pk_mul_f32 v[64:65], v[64:65], v[32:33] op_sel_hi:[1,0]
	v_pk_mul_f32 v[62:63], v[62:63], v[32:33] op_sel_hi:[1,0]
	v_pk_mul_f32 v[60:61], v[60:61], v[32:33] op_sel_hi:[1,0]
	v_pk_mul_f32 v[78:79], v[78:79], v[32:33] op_sel_hi:[1,0]
	v_pk_mul_f32 v[76:77], v[76:77], v[32:33] op_sel_hi:[1,0]
.LBB0_365:
	v_sub_f32_e32 v35, v154, v170
	v_sub_f32_e32 v37, v155, v170
	v_sub_f32_e32 v38, v156, v170
	v_sub_f32_e32 v39, v157, v170
	v_exp_f32_e32 v35, v35
	v_exp_f32_e32 v37, v37
	v_exp_f32_e32 v38, v38
	v_exp_f32_e32 v39, v39
	v_sub_f32_e32 v32, v152, v170
	v_sub_f32_e32 v152, v158, v170
	v_sub_f32_e32 v34, v153, v170
	v_exp_f32_e32 v155, v152
	v_sub_f32_e32 v152, v159, v170
	v_exp_f32_e32 v32, v32
	v_exp_f32_e32 v34, v34
	v_exp_f32_e32 v156, v152
	v_cvt_pk_bf16_f32 v153, v35, v37
	v_cvt_pk_bf16_f32 v154, v38, v39
	v_mov_b32_e32 v37, v36
	v_mov_b32_e32 v38, v36
	v_mov_b32_e32 v39, v36
	v_cvt_pk_bf16_f32 v152, v32, v34
	v_cvt_pk_bf16_f32 v155, v155, v156
	s_waitcnt vmcnt(11)
	s_nop 0
	v_mfma_f32_16x16x32_bf16 v[72:75], v[0:3], v[152:155], v[72:75]
	s_waitcnt vmcnt(10)
	v_mfma_f32_16x16x32_bf16 v[68:71], v[4:7], v[152:155], v[68:71]
	s_waitcnt vmcnt(9)
	v_mfma_f32_16x16x32_bf16 v[64:67], v[8:11], v[152:155], v[64:67]
	s_waitcnt vmcnt(8)
	v_mfma_f32_16x16x32_bf16 v[60:63], v[12:15], v[152:155], v[60:63]
	v_mfma_f32_16x16x32_bf16 v[76:79], v[36:39], v[152:155], v[76:79]
	ds_read_b128 v[152:155], v168 offset:22528
	ds_read_b128 v[174:177], v168 offset:23552
	s_waitcnt lgkmcnt(1)
	v_mfma_f32_16x16x32_bf16 v[156:159], v[24:27], v[152:155], 0
	v_mfma_f32_16x16x32_bf16 v[152:155], v[28:31], v[152:155], 0
	s_waitcnt lgkmcnt(0)
	v_mfma_f32_16x16x32_bf16 v[156:159], v[16:19], v[174:177], v[156:159]
	v_mfma_f32_16x16x32_bf16 v[152:155], v[20:23], v[174:177], v[152:155]
	s_nop 6
	v_max3_f32 v32, v156, v157, v158
	v_max3_f32 v35, v159, v152, v153
	v_max3_f32 v32, v32, v154, v155
	v_max_f32_e32 v32, v32, v35
	v_add_f32_e32 v34, 0x41000000, v172
	v_cmp_gt_f32_e32 vcc, v32, v34
	s_cbranch_vccz .LBB0_367
	v_mov_b32_e32 v34, v32
	s_nop 1
	v_permlane16_swap_b32 v32, v34
	s_nop 0
	v_max_f32_e32 v34, v34, v34
	v_max_f32_e32 v32, v32, v32
	v_max_f32_e32 v32, v32, v34
	v_mov_b32_e32 v34, v32
	s_nop 1
	v_permlane32_swap_b32 v32, v34
	s_nop 0
	v_max3_f32 v34, v172, v32, v34
	v_sub_f32_e32 v32, v172, v34
	v_exp_f32_e32 v32, v32
	v_mov_b32_e32 v172, v34
	v_pk_mul_f32 v[114:115], v[114:115], v[32:33] op_sel_hi:[1,0]
	v_pk_mul_f32 v[112:113], v[112:113], v[32:33] op_sel_hi:[1,0]
	v_pk_mul_f32 v[110:111], v[110:111], v[32:33] op_sel_hi:[1,0]
	v_pk_mul_f32 v[108:109], v[108:109], v[32:33] op_sel_hi:[1,0]
	v_pk_mul_f32 v[106:107], v[106:107], v[32:33] op_sel_hi:[1,0]
	v_pk_mul_f32 v[104:105], v[104:105], v[32:33] op_sel_hi:[1,0]
	v_pk_mul_f32 v[102:103], v[102:103], v[32:33] op_sel_hi:[1,0]
	v_pk_mul_f32 v[100:101], v[100:101], v[32:33] op_sel_hi:[1,0]
	v_pk_mul_f32 v[118:119], v[118:119], v[32:33] op_sel_hi:[1,0]
	v_pk_mul_f32 v[116:117], v[116:117], v[32:33] op_sel_hi:[1,0]
.LBB0_367:
	v_sub_f32_e32 v152, v152, v172
	v_sub_f32_e32 v34, v157, v172
	v_exp_f32_e32 v157, v152
	v_sub_f32_e32 v152, v153, v172
	v_sub_f32_e32 v35, v158, v172
	v_exp_f32_e32 v158, v152
	v_sub_f32_e32 v152, v154, v172
	v_sub_f32_e32 v32, v156, v172
	v_sub_f32_e32 v156, v159, v172
	v_exp_f32_e32 v159, v152
	v_sub_f32_e32 v152, v155, v172
	v_exp_f32_e32 v32, v32
	v_exp_f32_e32 v34, v34
	v_exp_f32_e32 v35, v35
	v_exp_f32_e32 v156, v156
	v_exp_f32_e32 v155, v152
	v_cvt_pk_bf16_f32 v152, v32, v34
	v_cvt_pk_bf16_f32 v154, v157, v158
	v_cvt_pk_bf16_f32 v153, v35, v156
	v_cvt_pk_bf16_f32 v155, v159, v155
	s_nop 1
	v_mfma_f32_16x16x32_bf16 v[112:115], v[0:3], v[152:155], v[112:115]
	v_mfma_f32_16x16x32_bf16 v[108:111], v[4:7], v[152:155], v[108:111]
	v_mfma_f32_16x16x32_bf16 v[104:107], v[8:11], v[152:155], v[104:107]
	v_mfma_f32_16x16x32_bf16 v[100:103], v[12:15], v[152:155], v[100:103]
	v_mfma_f32_16x16x32_bf16 v[116:119], v[36:39], v[152:155], v[116:119]
	ds_read_b128 v[152:155], v168 offset:24576
	ds_read_b128 v[174:177], v168 offset:25600
	s_waitcnt lgkmcnt(1)
	v_mfma_f32_16x16x32_bf16 v[156:159], v[24:27], v[152:155], 0
	v_mfma_f32_16x16x32_bf16 v[152:155], v[28:31], v[152:155], 0
	s_waitcnt lgkmcnt(0)
	v_mfma_f32_16x16x32_bf16 v[156:159], v[16:19], v[174:177], v[156:159]
	v_mfma_f32_16x16x32_bf16 v[152:155], v[20:23], v[174:177], v[152:155]
	s_nop 6
	v_max3_f32 v32, v156, v157, v158
	v_max3_f32 v35, v159, v152, v153
	v_max3_f32 v32, v32, v154, v155
	v_max_f32_e32 v32, v32, v35
	v_add_f32_e32 v34, 0x41000000, v171
	v_cmp_gt_f32_e32 vcc, v32, v34
	s_cbranch_vccz .LBB0_369
	v_mov_b32_e32 v34, v32
	s_nop 1
	v_permlane16_swap_b32 v32, v34
	s_nop 0
	v_max_f32_e32 v34, v34, v34
	v_max_f32_e32 v32, v32, v32
	v_max_f32_e32 v32, v32, v34
	v_mov_b32_e32 v34, v32
	s_nop 1
	v_permlane32_swap_b32 v34, v32
	s_nop 0
	v_max3_f32 v34, v171, v34, v32
	v_sub_f32_e32 v32, v171, v34
	v_exp_f32_e32 v32, v32
	v_mov_b32_e32 v171, v34
	v_pk_mul_f32 v[94:95], v[94:95], v[32:33] op_sel_hi:[1,0]
	v_pk_mul_f32 v[92:93], v[92:93], v[32:33] op_sel_hi:[1,0]
	v_pk_mul_f32 v[90:91], v[90:91], v[32:33] op_sel_hi:[1,0]
	v_pk_mul_f32 v[88:89], v[88:89], v[32:33] op_sel_hi:[1,0]
	v_pk_mul_f32 v[86:87], v[86:87], v[32:33] op_sel_hi:[1,0]
	v_pk_mul_f32 v[84:85], v[84:85], v[32:33] op_sel_hi:[1,0]
	v_pk_mul_f32 v[82:83], v[82:83], v[32:33] op_sel_hi:[1,0]
	v_pk_mul_f32 v[80:81], v[80:81], v[32:33] op_sel_hi:[1,0]
	v_pk_mul_f32 v[98:99], v[98:99], v[32:33] op_sel_hi:[1,0]
	v_pk_mul_f32 v[96:97], v[96:97], v[32:33] op_sel_hi:[1,0]
.LBB0_369:
	v_sub_f32_e32 v35, v158, v171
	v_sub_f32_e32 v37, v159, v171
	v_sub_f32_e32 v38, v152, v171
	v_sub_f32_e32 v39, v153, v171
	v_exp_f32_e32 v35, v35
	v_exp_f32_e32 v37, v37
	v_exp_f32_e32 v38, v38
	v_exp_f32_e32 v39, v39
	v_sub_f32_e32 v152, v154, v171
	v_sub_f32_e32 v32, v156, v171
	v_sub_f32_e32 v34, v157, v171
	v_exp_f32_e32 v156, v152
	v_sub_f32_e32 v152, v155, v171
	v_exp_f32_e32 v32, v32
	v_exp_f32_e32 v34, v34
	v_exp_f32_e32 v155, v152
	v_cvt_pk_bf16_f32 v153, v35, v37
	v_cvt_pk_bf16_f32 v154, v38, v39
	v_mov_b32_e32 v37, v36
	v_mov_b32_e32 v38, v36
	v_mov_b32_e32 v39, v36
	v_cvt_pk_bf16_f32 v152, v32, v34
	v_cvt_pk_bf16_f32 v155, v156, v155
	s_nop 1
	v_mfma_f32_16x16x32_bf16 v[92:95], v[0:3], v[152:155], v[92:95]
	v_mfma_f32_16x16x32_bf16 v[88:91], v[4:7], v[152:155], v[88:91]
	v_mfma_f32_16x16x32_bf16 v[84:87], v[8:11], v[152:155], v[84:87]
	v_mfma_f32_16x16x32_bf16 v[80:83], v[12:15], v[152:155], v[80:83]
	v_mfma_f32_16x16x32_bf16 v[96:99], v[36:39], v[152:155], v[96:99]
	ds_read_b128 v[152:155], v168 offset:26624
	s_waitcnt lgkmcnt(0)
	v_mfma_f32_16x16x32_bf16 v[24:27], v[24:27], v[152:155], 0
	v_mfma_f32_16x16x32_bf16 v[28:31], v[28:31], v[152:155], 0
	ds_read_b128 v[152:155], v168 offset:27648
	s_waitcnt lgkmcnt(0)
	v_mfma_f32_16x16x32_bf16 v[16:19], v[16:19], v[152:155], v[24:27]
	v_mfma_f32_16x16x32_bf16 v[20:23], v[20:23], v[152:155], v[28:31]
	s_nop 6
	v_max3_f32 v24, v16, v17, v18
	v_max3_f32 v26, v19, v20, v21
	v_max3_f32 v24, v24, v22, v23
	v_max_f32_e32 v24, v24, v26
	v_add_f32_e32 v25, 0x41000000, v169
	v_cmp_gt_f32_e32 vcc, v24, v25
	s_cbranch_vccz .LBB0_371
	v_mov_b32_e32 v25, v24
	s_nop 1
	v_permlane16_swap_b32 v24, v25
	s_nop 0
	v_max_f32_e32 v25, v25, v25
	v_max_f32_e32 v24, v24, v24
	v_max_f32_e32 v24, v24, v25
	v_mov_b32_e32 v25, v24
	s_nop 1
	v_permlane32_swap_b32 v24, v25
	s_nop 0
	v_max3_f32 v25, v169, v24, v25
	v_sub_f32_e32 v24, v169, v25
	v_exp_f32_e32 v24, v24
	v_mov_b32_e32 v169, v25
	v_pk_mul_f32 v[54:55], v[54:55], v[24:25] op_sel_hi:[1,0]
	v_pk_mul_f32 v[52:53], v[52:53], v[24:25] op_sel_hi:[1,0]
	v_pk_mul_f32 v[50:51], v[50:51], v[24:25] op_sel_hi:[1,0]
	v_pk_mul_f32 v[48:49], v[48:49], v[24:25] op_sel_hi:[1,0]
	v_pk_mul_f32 v[46:47], v[46:47], v[24:25] op_sel_hi:[1,0]
	v_pk_mul_f32 v[44:45], v[44:45], v[24:25] op_sel_hi:[1,0]
	v_pk_mul_f32 v[42:43], v[42:43], v[24:25] op_sel_hi:[1,0]
	v_pk_mul_f32 v[40:41], v[40:41], v[24:25] op_sel_hi:[1,0]
	v_pk_mul_f32 v[58:59], v[58:59], v[24:25] op_sel_hi:[1,0]
	v_pk_mul_f32 v[56:57], v[56:57], v[24:25] op_sel_hi:[1,0]
.LBB0_371:
	v_sub_f32_e32 v16, v16, v169
	v_sub_f32_e32 v17, v17, v169
	v_sub_f32_e32 v18, v18, v169
	v_sub_f32_e32 v19, v19, v169
	v_sub_f32_e32 v20, v20, v169
	v_sub_f32_e32 v21, v21, v169
	v_sub_f32_e32 v22, v22, v169
	v_sub_f32_e32 v23, v23, v169
	v_exp_f32_e32 v16, v16
	v_exp_f32_e32 v17, v17
	v_exp_f32_e32 v18, v18
	v_exp_f32_e32 v19, v19
	v_exp_f32_e32 v20, v20
	v_exp_f32_e32 v21, v21
	v_exp_f32_e32 v22, v22
	v_exp_f32_e32 v23, v23
	v_cvt_pk_bf16_f32 v16, v16, v17
	v_cvt_pk_bf16_f32 v17, v18, v19
	v_cvt_pk_bf16_f32 v18, v20, v21
	v_cvt_pk_bf16_f32 v19, v22, v23
	s_add_i32 s31, s30, -2
	s_nop 0
	v_mfma_f32_16x16x32_bf16 v[52:55], v[0:3], v[16:19], v[52:55]
	v_mfma_f32_16x16x32_bf16 v[48:51], v[4:7], v[16:19], v[48:51]
	v_mfma_f32_16x16x32_bf16 v[44:47], v[8:11], v[16:19], v[44:47]
	v_mfma_f32_16x16x32_bf16 v[40:43], v[12:15], v[16:19], v[40:43]
	v_mfma_f32_16x16x32_bf16 v[56:59], v[36:39], v[16:19], v[56:59]
	s_cmp_lt_u32 s31, 6
	s_cselect_b32 s0, s30, 0
	s_add_i32 s34, s0, s60
	ds_read_b128 v[8:11], v168 offset:20480
	s_lshl_b32 s0, s34, 1
	s_lshl_b64 s[40:41], s[0:1], 14
	v_lshl_add_u64 v[4:5], v[164:165], 0, s[40:41]
	global_load_dwordx4 v[24:27], v[4:5], off
	global_load_dwordx4 v[16:19], v[4:5], off offset:1024
	ds_read_b128 v[156:159], v168 offset:21504
	s_waitcnt vmcnt(9) lgkmcnt(1)
	v_mfma_f32_16x16x32_bf16 v[0:3], v[144:147], v[8:11], 0
	s_mov_b32 s35, s1
	v_add_co_u32_e32 v4, vcc, s72, v4
	s_lshl_b64 s[34:35], s[34:35], 15
	s_nop 0
	v_addc_co_u32_e32 v5, vcc, 0, v5, vcc
	v_lshl_add_u64 v[12:13], v[166:167], 0, s[34:35]
	s_waitcnt vmcnt(8) lgkmcnt(0)
	v_mfma_f32_16x16x32_bf16 v[152:155], v[140:143], v[156:159], v[0:3]
	global_load_dwordx4 v[28:31], v[4:5], off
	global_load_dwordx4 v[20:23], v[4:5], off offset:1024
	s_nop 0
	global_load_dwordx4 v[0:3], v[12:13], off
	global_load_dwordx4 v[4:7], v[12:13], off offset:1024
	s_nop 2
	s_waitcnt vmcnt(11)
	v_mfma_f32_16x16x32_bf16 v[174:177], v[148:151], v[8:11], 0
	global_load_dwordx4 v[8:11], v[12:13], off offset:2048
	s_nop 0
	global_load_dwordx4 v[12:15], v[12:13], off offset:3072
	s_waitcnt vmcnt(12)
	v_mfma_f32_16x16x32_bf16 v[156:159], v[136:139], v[156:159], v[174:177]
	s_nop 4
	v_max3_f32 v32, v152, v153, v154
	s_nop 1
	v_max3_f32 v35, v155, v156, v157
	v_max3_f32 v32, v32, v158, v159
	v_max_f32_e32 v32, v32, v35
	v_add_f32_e32 v34, 0x41000000, v170
	v_cmp_gt_f32_e32 vcc, v32, v34
	s_cbranch_vccz .LBB0_373
	v_mov_b32_e32 v34, v32
	s_nop 1
	v_permlane16_swap_b32 v32, v34
	s_nop 0
	v_max_f32_e32 v34, v34, v34
	v_max_f32_e32 v32, v32, v32
	v_max_f32_e32 v32, v32, v34
	v_mov_b32_e32 v34, v32
	s_nop 1
	v_permlane32_swap_b32 v34, v32
	s_nop 0
	v_max3_f32 v34, v170, v34, v32
	v_sub_f32_e32 v32, v170, v34
	v_exp_f32_e32 v32, v32
	v_mov_b32_e32 v170, v34
	v_pk_mul_f32 v[74:75], v[74:75], v[32:33] op_sel_hi:[1,0]
	v_pk_mul_f32 v[72:73], v[72:73], v[32:33] op_sel_hi:[1,0]
	v_pk_mul_f32 v[70:71], v[70:71], v[32:33] op_sel_hi:[1,0]
	v_pk_mul_f32 v[68:69], v[68:69], v[32:33] op_sel_hi:[1,0]
	v_pk_mul_f32 v[66:67], v[66:67], v[32:33] op_sel_hi:[1,0]
	v_pk_mul_f32 v[64:65], v[64:65], v[32:33] op_sel_hi:[1,0]
	v_pk_mul_f32 v[62:63], v[62:63], v[32:33] op_sel_hi:[1,0]
	v_pk_mul_f32 v[60:61], v[60:61], v[32:33] op_sel_hi:[1,0]
	v_pk_mul_f32 v[78:79], v[78:79], v[32:33] op_sel_hi:[1,0]
	v_pk_mul_f32 v[76:77], v[76:77], v[32:33] op_sel_hi:[1,0]
.LBB0_373:
	v_sub_f32_e32 v35, v154, v170
	v_sub_f32_e32 v37, v155, v170
	v_sub_f32_e32 v38, v156, v170
	v_sub_f32_e32 v39, v157, v170
	v_exp_f32_e32 v35, v35
	v_exp_f32_e32 v37, v37
	v_exp_f32_e32 v38, v38
	v_exp_f32_e32 v39, v39
	v_sub_f32_e32 v32, v152, v170
	v_sub_f32_e32 v152, v158, v170
	v_sub_f32_e32 v34, v153, v170
	v_exp_f32_e32 v155, v152
	v_sub_f32_e32 v152, v159, v170
	v_exp_f32_e32 v32, v32
	v_exp_f32_e32 v34, v34
	v_exp_f32_e32 v156, v152
	v_cvt_pk_bf16_f32 v153, v35, v37
	v_cvt_pk_bf16_f32 v154, v38, v39
	v_mov_b32_e32 v37, v36
	v_mov_b32_e32 v38, v36
	v_mov_b32_e32 v39, v36
	v_cvt_pk_bf16_f32 v152, v32, v34
	v_cvt_pk_bf16_f32 v155, v155, v156
	s_waitcnt vmcnt(11)
	s_nop 0
	v_mfma_f32_16x16x32_bf16 v[72:75], v[120:123], v[152:155], v[72:75]
	s_waitcnt vmcnt(10)
	v_mfma_f32_16x16x32_bf16 v[68:71], v[124:127], v[152:155], v[68:71]
	s_waitcnt vmcnt(9)
	v_mfma_f32_16x16x32_bf16 v[64:67], v[128:131], v[152:155], v[64:67]
	s_waitcnt vmcnt(8)
	v_mfma_f32_16x16x32_bf16 v[60:63], v[132:135], v[152:155], v[60:63]
	v_mfma_f32_16x16x32_bf16 v[76:79], v[36:39], v[152:155], v[76:79]
	ds_read_b128 v[152:155], v168 offset:22528
	ds_read_b128 v[174:177], v168 offset:23552
	s_waitcnt lgkmcnt(1)
	v_mfma_f32_16x16x32_bf16 v[156:159], v[144:147], v[152:155], 0
	v_mfma_f32_16x16x32_bf16 v[152:155], v[148:151], v[152:155], 0
	s_waitcnt lgkmcnt(0)
	v_mfma_f32_16x16x32_bf16 v[156:159], v[140:143], v[174:177], v[156:159]
	v_mfma_f32_16x16x32_bf16 v[152:155], v[136:139], v[174:177], v[152:155]
	s_nop 6
	v_max3_f32 v32, v156, v157, v158
	v_max3_f32 v35, v159, v152, v153
	v_max3_f32 v32, v32, v154, v155
	v_max_f32_e32 v32, v32, v35
	v_add_f32_e32 v34, 0x41000000, v172
	v_cmp_gt_f32_e32 vcc, v32, v34
	s_cbranch_vccz .LBB0_375
	v_mov_b32_e32 v34, v32
	s_nop 1
	v_permlane16_swap_b32 v32, v34
	s_nop 0
	v_max_f32_e32 v34, v34, v34
	v_max_f32_e32 v32, v32, v32
	v_max_f32_e32 v32, v32, v34
	v_mov_b32_e32 v34, v32
	s_nop 1
	v_permlane32_swap_b32 v32, v34
	s_nop 0
	v_max3_f32 v34, v172, v32, v34
	v_sub_f32_e32 v32, v172, v34
	v_exp_f32_e32 v32, v32
	v_mov_b32_e32 v172, v34
	v_pk_mul_f32 v[114:115], v[114:115], v[32:33] op_sel_hi:[1,0]
	v_pk_mul_f32 v[112:113], v[112:113], v[32:33] op_sel_hi:[1,0]
	v_pk_mul_f32 v[110:111], v[110:111], v[32:33] op_sel_hi:[1,0]
	v_pk_mul_f32 v[108:109], v[108:109], v[32:33] op_sel_hi:[1,0]
	v_pk_mul_f32 v[106:107], v[106:107], v[32:33] op_sel_hi:[1,0]
	v_pk_mul_f32 v[104:105], v[104:105], v[32:33] op_sel_hi:[1,0]
	v_pk_mul_f32 v[102:103], v[102:103], v[32:33] op_sel_hi:[1,0]
	v_pk_mul_f32 v[100:101], v[100:101], v[32:33] op_sel_hi:[1,0]
	v_pk_mul_f32 v[118:119], v[118:119], v[32:33] op_sel_hi:[1,0]
	v_pk_mul_f32 v[116:117], v[116:117], v[32:33] op_sel_hi:[1,0]
.LBB0_375:
	v_sub_f32_e32 v152, v152, v172
	v_sub_f32_e32 v34, v157, v172
	v_exp_f32_e32 v157, v152
	v_sub_f32_e32 v152, v153, v172
	v_sub_f32_e32 v35, v158, v172
	v_exp_f32_e32 v158, v152
	v_sub_f32_e32 v152, v154, v172
	v_sub_f32_e32 v32, v156, v172
	v_sub_f32_e32 v156, v159, v172
	v_exp_f32_e32 v159, v152
	v_sub_f32_e32 v152, v155, v172
	v_exp_f32_e32 v32, v32
	v_exp_f32_e32 v34, v34
	v_exp_f32_e32 v35, v35
	v_exp_f32_e32 v156, v156
	v_exp_f32_e32 v155, v152
	v_cvt_pk_bf16_f32 v152, v32, v34
	v_cvt_pk_bf16_f32 v154, v157, v158
	v_cvt_pk_bf16_f32 v153, v35, v156
	v_cvt_pk_bf16_f32 v155, v159, v155
	s_nop 1
	v_mfma_f32_16x16x32_bf16 v[112:115], v[120:123], v[152:155], v[112:115]
	v_mfma_f32_16x16x32_bf16 v[108:111], v[124:127], v[152:155], v[108:111]
	v_mfma_f32_16x16x32_bf16 v[104:107], v[128:131], v[152:155], v[104:107]
	v_mfma_f32_16x16x32_bf16 v[100:103], v[132:135], v[152:155], v[100:103]
	v_mfma_f32_16x16x32_bf16 v[116:119], v[36:39], v[152:155], v[116:119]
	ds_read_b128 v[152:155], v168 offset:24576
	ds_read_b128 v[174:177], v168 offset:25600
	s_waitcnt lgkmcnt(1)
	v_mfma_f32_16x16x32_bf16 v[156:159], v[144:147], v[152:155], 0
	v_mfma_f32_16x16x32_bf16 v[152:155], v[148:151], v[152:155], 0
	s_waitcnt lgkmcnt(0)
	v_mfma_f32_16x16x32_bf16 v[156:159], v[140:143], v[174:177], v[156:159]
	v_mfma_f32_16x16x32_bf16 v[152:155], v[136:139], v[174:177], v[152:155]
	s_nop 6
	v_max3_f32 v32, v156, v157, v158
	v_max3_f32 v35, v159, v152, v153
	v_max3_f32 v32, v32, v154, v155
	v_max_f32_e32 v32, v32, v35
	v_add_f32_e32 v34, 0x41000000, v171
	v_cmp_gt_f32_e32 vcc, v32, v34
	s_cbranch_vccz .LBB0_377
	v_mov_b32_e32 v34, v32
	s_nop 1
	v_permlane16_swap_b32 v32, v34
	s_nop 0
	v_max_f32_e32 v34, v34, v34
	v_max_f32_e32 v32, v32, v32
	v_max_f32_e32 v32, v32, v34
	v_mov_b32_e32 v34, v32
	s_nop 1
	v_permlane32_swap_b32 v32, v34
	s_nop 0
	v_max3_f32 v34, v171, v32, v34
	v_sub_f32_e32 v32, v171, v34
	v_exp_f32_e32 v32, v32
	v_mov_b32_e32 v171, v34
	v_pk_mul_f32 v[94:95], v[94:95], v[32:33] op_sel_hi:[1,0]
	v_pk_mul_f32 v[92:93], v[92:93], v[32:33] op_sel_hi:[1,0]
	v_pk_mul_f32 v[90:91], v[90:91], v[32:33] op_sel_hi:[1,0]
	v_pk_mul_f32 v[88:89], v[88:89], v[32:33] op_sel_hi:[1,0]
	v_pk_mul_f32 v[86:87], v[86:87], v[32:33] op_sel_hi:[1,0]
	v_pk_mul_f32 v[84:85], v[84:85], v[32:33] op_sel_hi:[1,0]
	v_pk_mul_f32 v[82:83], v[82:83], v[32:33] op_sel_hi:[1,0]
	v_pk_mul_f32 v[80:81], v[80:81], v[32:33] op_sel_hi:[1,0]
	v_pk_mul_f32 v[98:99], v[98:99], v[32:33] op_sel_hi:[1,0]
	v_pk_mul_f32 v[96:97], v[96:97], v[32:33] op_sel_hi:[1,0]
.LBB0_377:
	v_sub_f32_e32 v35, v158, v171
	v_sub_f32_e32 v37, v159, v171
	v_sub_f32_e32 v38, v152, v171
	v_sub_f32_e32 v39, v153, v171
	v_exp_f32_e32 v35, v35
	v_exp_f32_e32 v37, v37
	v_exp_f32_e32 v38, v38
	v_exp_f32_e32 v39, v39
	v_sub_f32_e32 v152, v154, v171
	v_sub_f32_e32 v32, v156, v171
	v_sub_f32_e32 v34, v157, v171
	v_exp_f32_e32 v156, v152
	v_sub_f32_e32 v152, v155, v171
	v_exp_f32_e32 v32, v32
	v_exp_f32_e32 v34, v34
	v_exp_f32_e32 v155, v152
	v_cvt_pk_bf16_f32 v153, v35, v37
	v_cvt_pk_bf16_f32 v154, v38, v39
	v_mov_b32_e32 v37, v36
	v_mov_b32_e32 v38, v36
	v_mov_b32_e32 v39, v36
	v_cvt_pk_bf16_f32 v152, v32, v34
	v_cvt_pk_bf16_f32 v155, v156, v155
	s_nop 1
	v_mfma_f32_16x16x32_bf16 v[92:95], v[120:123], v[152:155], v[92:95]
	v_mfma_f32_16x16x32_bf16 v[88:91], v[124:127], v[152:155], v[88:91]
	v_mfma_f32_16x16x32_bf16 v[84:87], v[128:131], v[152:155], v[84:87]
	v_mfma_f32_16x16x32_bf16 v[80:83], v[132:135], v[152:155], v[80:83]
	v_mfma_f32_16x16x32_bf16 v[96:99], v[36:39], v[152:155], v[96:99]
	ds_read_b128 v[152:155], v168 offset:26624
	s_waitcnt lgkmcnt(0)
	v_mfma_f32_16x16x32_bf16 v[144:147], v[144:147], v[152:155], 0
	v_mfma_f32_16x16x32_bf16 v[148:151], v[148:151], v[152:155], 0
	ds_read_b128 v[152:155], v168 offset:27648
	s_waitcnt lgkmcnt(0)
	v_mfma_f32_16x16x32_bf16 v[140:143], v[140:143], v[152:155], v[144:147]
	v_mfma_f32_16x16x32_bf16 v[136:139], v[136:139], v[152:155], v[148:151]
	s_nop 6
	v_max3_f32 v32, v140, v141, v142
	v_max3_f32 v35, v143, v136, v137
	v_max3_f32 v32, v32, v138, v139
	v_max_f32_e32 v32, v32, v35
	v_add_f32_e32 v34, 0x41000000, v169
	v_cmp_gt_f32_e32 vcc, v32, v34
	s_cbranch_vccz .LBB0_362
	v_mov_b32_e32 v34, v32
	s_nop 1
	v_permlane16_swap_b32 v32, v34
	s_nop 0
	v_max_f32_e32 v34, v34, v34
	v_max_f32_e32 v32, v32, v32
	v_max_f32_e32 v32, v32, v34
	v_mov_b32_e32 v34, v32
	s_nop 1
	v_permlane32_swap_b32 v32, v34
	s_nop 0
	v_max3_f32 v34, v169, v32, v34
	v_sub_f32_e32 v32, v169, v34
	v_exp_f32_e32 v32, v32
	v_mov_b32_e32 v169, v34
	v_pk_mul_f32 v[54:55], v[54:55], v[32:33] op_sel_hi:[1,0]
	v_pk_mul_f32 v[52:53], v[52:53], v[32:33] op_sel_hi:[1,0]
	v_pk_mul_f32 v[50:51], v[50:51], v[32:33] op_sel_hi:[1,0]
	v_pk_mul_f32 v[48:49], v[48:49], v[32:33] op_sel_hi:[1,0]
	v_pk_mul_f32 v[46:47], v[46:47], v[32:33] op_sel_hi:[1,0]
	v_pk_mul_f32 v[44:45], v[44:45], v[32:33] op_sel_hi:[1,0]
	v_pk_mul_f32 v[42:43], v[42:43], v[32:33] op_sel_hi:[1,0]
	v_pk_mul_f32 v[40:41], v[40:41], v[32:33] op_sel_hi:[1,0]
	v_pk_mul_f32 v[58:59], v[58:59], v[32:33] op_sel_hi:[1,0]
	v_pk_mul_f32 v[56:57], v[56:57], v[32:33] op_sel_hi:[1,0]
	s_branch .LBB0_362

.LBB0_382:
	ds_read_b128 v[48:51], v167 offset:20480
	v_lshl_add_u64 v[34:35], s[34:35], 0, v[160:161]
	s_mov_b32 s0, 0x12708000
	v_add_co_u32_e32 v38, vcc, s0, v34
	s_mov_b32 s0, 0x1270c000
	s_nop 0
	v_addc_co_u32_e32 v39, vcc, 0, v35, vcc
	global_load_dwordx4 v[64:67], v[38:39], off
	global_load_dwordx4 v[60:63], v[38:39], off offset:1024
	ds_read_b128 v[156:159], v167 offset:21504
	s_waitcnt vmcnt(9) lgkmcnt(1)
	v_mfma_f32_16x16x32_bf16 v[38:41], v[20:23], v[48:51], 0
	v_add_co_u32_e32 v34, vcc, s0, v34
	v_lshl_add_u64 v[52:53], s[26:27], 0, v[160:161]
	s_nop 0
	v_addc_co_u32_e32 v35, vcc, 0, v35, vcc
	s_waitcnt vmcnt(8) lgkmcnt(0)
	v_mfma_f32_16x16x32_bf16 v[152:155], v[16:19], v[156:159], v[38:41]
	global_load_dwordx4 v[68:71], v[34:35], off
	global_load_dwordx4 v[56:59], v[34:35], off offset:1024
	s_nop 0
	global_load_dwordx4 v[40:43], v[52:53], off offset:-2048
	global_load_dwordx4 v[44:47], v[52:53], off offset:-1024
	s_nop 2
	s_waitcnt vmcnt(11)
	v_mfma_f32_16x16x32_bf16 v[172:175], v[28:31], v[48:51], 0
	global_load_dwordx4 v[48:51], v[52:53], off
	s_nop 0
	global_load_dwordx4 v[52:55], v[52:53], off offset:1024
	s_waitcnt vmcnt(12)
	v_mfma_f32_16x16x32_bf16 v[156:159], v[24:27], v[156:159], v[172:175]
	s_nop 4
	v_max3_f32 v32, v152, v153, v154
	s_nop 1
	v_max3_f32 v35, v155, v156, v157
	v_max3_f32 v32, v32, v158, v159
	v_max_f32_e32 v32, v32, v35
	v_add_f32_e32 v34, 0x41000000, v171
	v_cmp_gt_f32_e32 vcc, v32, v34
	s_cbranch_vccz .LBB0_384
	v_mov_b32_e32 v34, v32
	s_nop 1
	v_permlane16_swap_b32 v32, v34
	s_nop 0
	v_max_f32_e32 v34, v34, v34
	v_max_f32_e32 v32, v32, v32
	v_max_f32_e32 v32, v32, v34
	v_mov_b32_e32 v34, v32
	s_nop 1
	v_permlane32_swap_b32 v34, v32
	s_nop 0
	v_max3_f32 v34, v171, v34, v32
	v_sub_f32_e32 v32, v171, v34
	v_exp_f32_e32 v32, v32
	v_mov_b32_e32 v171, v34
	v_pk_mul_f32 v[146:147], v[146:147], v[32:33] op_sel_hi:[1,0]
	v_pk_mul_f32 v[144:145], v[144:145], v[32:33] op_sel_hi:[1,0]
	v_pk_mul_f32 v[142:143], v[142:143], v[32:33] op_sel_hi:[1,0]
	v_pk_mul_f32 v[140:141], v[140:141], v[32:33] op_sel_hi:[1,0]
	v_pk_mul_f32 v[138:139], v[138:139], v[32:33] op_sel_hi:[1,0]
	v_pk_mul_f32 v[136:137], v[136:137], v[32:33] op_sel_hi:[1,0]
	v_pk_mul_f32 v[134:135], v[134:135], v[32:33] op_sel_hi:[1,0]
	v_pk_mul_f32 v[132:133], v[132:133], v[32:33] op_sel_hi:[1,0]
	v_pk_mul_f32 v[150:151], v[150:151], v[32:33] op_sel_hi:[1,0]
	v_pk_mul_f32 v[148:149], v[148:149], v[32:33] op_sel_hi:[1,0]
.LBB0_384:
	v_sub_f32_e32 v35, v154, v171
	v_sub_f32_e32 v37, v155, v171
	v_sub_f32_e32 v38, v156, v171
	v_sub_f32_e32 v39, v157, v171
	v_exp_f32_e32 v35, v35
	v_exp_f32_e32 v37, v37
	v_exp_f32_e32 v38, v38
	v_exp_f32_e32 v39, v39
	v_sub_f32_e32 v32, v152, v171
	v_sub_f32_e32 v152, v158, v171
	v_sub_f32_e32 v34, v153, v171
	v_exp_f32_e32 v155, v152
	v_sub_f32_e32 v152, v159, v171
	v_exp_f32_e32 v32, v32
	v_exp_f32_e32 v34, v34
	v_exp_f32_e32 v156, v152
	v_cvt_pk_bf16_f32 v153, v35, v37
	v_cvt_pk_bf16_f32 v154, v38, v39
	v_mov_b32_e32 v37, v36
	v_mov_b32_e32 v38, v36
	v_mov_b32_e32 v39, v36
	v_cvt_pk_bf16_f32 v152, v32, v34
	v_cvt_pk_bf16_f32 v155, v155, v156
	s_waitcnt vmcnt(11)
	s_nop 0
	v_mfma_f32_16x16x32_bf16 v[144:147], v[0:3], v[152:155], v[144:147]
	s_waitcnt vmcnt(10)
	v_mfma_f32_16x16x32_bf16 v[140:143], v[4:7], v[152:155], v[140:143]
	s_waitcnt vmcnt(9)
	v_mfma_f32_16x16x32_bf16 v[136:139], v[8:11], v[152:155], v[136:139]
	s_waitcnt vmcnt(8)
	v_mfma_f32_16x16x32_bf16 v[132:135], v[12:15], v[152:155], v[132:135]
	v_mfma_f32_16x16x32_bf16 v[148:151], v[36:39], v[152:155], v[148:151]
	ds_read_b128 v[152:155], v167 offset:22528
	ds_read_b128 v[172:175], v167 offset:23552
	s_waitcnt lgkmcnt(1)
	v_mfma_f32_16x16x32_bf16 v[156:159], v[20:23], v[152:155], 0
	v_mfma_f32_16x16x32_bf16 v[152:155], v[28:31], v[152:155], 0
	s_waitcnt lgkmcnt(0)
	v_mfma_f32_16x16x32_bf16 v[156:159], v[16:19], v[172:175], v[156:159]
	v_mfma_f32_16x16x32_bf16 v[152:155], v[24:27], v[172:175], v[152:155]
	s_nop 6
	v_max3_f32 v32, v156, v157, v158
	v_max3_f32 v35, v159, v152, v153
	v_max3_f32 v32, v32, v154, v155
	v_max_f32_e32 v32, v32, v35
	v_add_f32_e32 v34, 0x41000000, v170
	v_cmp_gt_f32_e32 vcc, v32, v34
	s_cbranch_vccz .LBB0_386
	v_mov_b32_e32 v34, v32
	s_nop 1
	v_permlane16_swap_b32 v32, v34
	s_nop 0
	v_max_f32_e32 v34, v34, v34
	v_max_f32_e32 v32, v32, v32
	v_max_f32_e32 v32, v32, v34
	v_mov_b32_e32 v34, v32
	s_nop 1
	v_permlane32_swap_b32 v32, v34
	s_nop 0
	v_max3_f32 v34, v170, v32, v34
	v_sub_f32_e32 v32, v170, v34
	v_exp_f32_e32 v32, v32
	v_mov_b32_e32 v170, v34
	v_pk_mul_f32 v[126:127], v[126:127], v[32:33] op_sel_hi:[1,0]
	v_pk_mul_f32 v[124:125], v[124:125], v[32:33] op_sel_hi:[1,0]
	v_pk_mul_f32 v[122:123], v[122:123], v[32:33] op_sel_hi:[1,0]
	v_pk_mul_f32 v[120:121], v[120:121], v[32:33] op_sel_hi:[1,0]
	v_pk_mul_f32 v[118:119], v[118:119], v[32:33] op_sel_hi:[1,0]
	v_pk_mul_f32 v[116:117], v[116:117], v[32:33] op_sel_hi:[1,0]
	v_pk_mul_f32 v[114:115], v[114:115], v[32:33] op_sel_hi:[1,0]
	v_pk_mul_f32 v[112:113], v[112:113], v[32:33] op_sel_hi:[1,0]
	v_pk_mul_f32 v[130:131], v[130:131], v[32:33] op_sel_hi:[1,0]
	v_pk_mul_f32 v[128:129], v[128:129], v[32:33] op_sel_hi:[1,0]
.LBB0_386:
	v_sub_f32_e32 v152, v152, v170
	v_sub_f32_e32 v34, v157, v170
	v_exp_f32_e32 v157, v152
	v_sub_f32_e32 v152, v153, v170
	v_sub_f32_e32 v35, v158, v170
	v_exp_f32_e32 v158, v152
	v_sub_f32_e32 v152, v154, v170
	v_sub_f32_e32 v32, v156, v170
	v_sub_f32_e32 v156, v159, v170
	v_exp_f32_e32 v159, v152
	v_sub_f32_e32 v152, v155, v170
	v_exp_f32_e32 v32, v32
	v_exp_f32_e32 v34, v34
	v_exp_f32_e32 v35, v35
	v_exp_f32_e32 v156, v156
	v_exp_f32_e32 v155, v152
	v_cvt_pk_bf16_f32 v152, v32, v34
	v_cvt_pk_bf16_f32 v154, v157, v158
	v_cvt_pk_bf16_f32 v153, v35, v156
	v_cvt_pk_bf16_f32 v155, v159, v155
	s_nop 1
	v_mfma_f32_16x16x32_bf16 v[124:127], v[0:3], v[152:155], v[124:127]
	v_mfma_f32_16x16x32_bf16 v[120:123], v[4:7], v[152:155], v[120:123]
	v_mfma_f32_16x16x32_bf16 v[116:119], v[8:11], v[152:155], v[116:119]
	v_mfma_f32_16x16x32_bf16 v[112:115], v[12:15], v[152:155], v[112:115]
	v_mfma_f32_16x16x32_bf16 v[128:131], v[36:39], v[152:155], v[128:131]
	ds_read_b128 v[152:155], v167 offset:24576
	ds_read_b128 v[172:175], v167 offset:25600
	s_waitcnt lgkmcnt(1)
	v_mfma_f32_16x16x32_bf16 v[156:159], v[20:23], v[152:155], 0
	v_mfma_f32_16x16x32_bf16 v[152:155], v[28:31], v[152:155], 0
	s_waitcnt lgkmcnt(0)
	v_mfma_f32_16x16x32_bf16 v[156:159], v[16:19], v[172:175], v[156:159]
	v_mfma_f32_16x16x32_bf16 v[152:155], v[24:27], v[172:175], v[152:155]
	s_nop 6
	v_max3_f32 v32, v156, v157, v158
	v_max3_f32 v35, v159, v152, v153
	v_max3_f32 v32, v32, v154, v155
	v_max_f32_e32 v32, v32, v35
	v_add_f32_e32 v34, 0x41000000, v169
	v_cmp_gt_f32_e32 vcc, v32, v34
	s_cbranch_vccz .LBB0_388
	v_mov_b32_e32 v34, v32
	s_nop 1
	v_permlane16_swap_b32 v32, v34
	s_nop 0
	v_max_f32_e32 v34, v34, v34
	v_max_f32_e32 v32, v32, v32
	v_max_f32_e32 v32, v32, v34
	v_mov_b32_e32 v34, v32
	s_nop 1
	v_permlane32_swap_b32 v32, v34
	s_nop 0
	v_max3_f32 v34, v169, v32, v34
	v_sub_f32_e32 v32, v169, v34
	v_exp_f32_e32 v32, v32
	v_mov_b32_e32 v169, v34
	v_pk_mul_f32 v[106:107], v[106:107], v[32:33] op_sel_hi:[1,0]
	v_pk_mul_f32 v[104:105], v[104:105], v[32:33] op_sel_hi:[1,0]
	v_pk_mul_f32 v[102:103], v[102:103], v[32:33] op_sel_hi:[1,0]
	v_pk_mul_f32 v[100:101], v[100:101], v[32:33] op_sel_hi:[1,0]
	v_pk_mul_f32 v[98:99], v[98:99], v[32:33] op_sel_hi:[1,0]
	v_pk_mul_f32 v[96:97], v[96:97], v[32:33] op_sel_hi:[1,0]
	v_pk_mul_f32 v[94:95], v[94:95], v[32:33] op_sel_hi:[1,0]
	v_pk_mul_f32 v[92:93], v[92:93], v[32:33] op_sel_hi:[1,0]
	v_pk_mul_f32 v[110:111], v[110:111], v[32:33] op_sel_hi:[1,0]
	v_pk_mul_f32 v[108:109], v[108:109], v[32:33] op_sel_hi:[1,0]
.LBB0_388:
	v_sub_f32_e32 v35, v158, v169
	v_sub_f32_e32 v37, v159, v169
	v_sub_f32_e32 v38, v152, v169
	v_sub_f32_e32 v39, v153, v169
	v_exp_f32_e32 v35, v35
	v_exp_f32_e32 v37, v37
	v_exp_f32_e32 v38, v38
	v_exp_f32_e32 v39, v39
	v_sub_f32_e32 v152, v154, v169
	v_sub_f32_e32 v32, v156, v169
	v_sub_f32_e32 v34, v157, v169
	v_exp_f32_e32 v156, v152
	v_sub_f32_e32 v152, v155, v169
	v_exp_f32_e32 v32, v32
	v_exp_f32_e32 v34, v34
	v_exp_f32_e32 v155, v152
	v_cvt_pk_bf16_f32 v153, v35, v37
	v_cvt_pk_bf16_f32 v154, v38, v39
	v_mov_b32_e32 v37, v36
	v_mov_b32_e32 v38, v36
	v_mov_b32_e32 v39, v36
	v_cvt_pk_bf16_f32 v152, v32, v34
	v_cvt_pk_bf16_f32 v155, v156, v155
	s_nop 1
	v_mfma_f32_16x16x32_bf16 v[104:107], v[0:3], v[152:155], v[104:107]
	v_mfma_f32_16x16x32_bf16 v[100:103], v[4:7], v[152:155], v[100:103]
	v_mfma_f32_16x16x32_bf16 v[96:99], v[8:11], v[152:155], v[96:99]
	v_mfma_f32_16x16x32_bf16 v[92:95], v[12:15], v[152:155], v[92:95]
	v_mfma_f32_16x16x32_bf16 v[108:111], v[36:39], v[152:155], v[108:111]
	ds_read_b128 v[152:155], v167 offset:26624
	s_waitcnt lgkmcnt(0)
	v_mfma_f32_16x16x32_bf16 v[20:23], v[20:23], v[152:155], 0
	v_mfma_f32_16x16x32_bf16 v[28:31], v[28:31], v[152:155], 0
	ds_read_b128 v[152:155], v167 offset:27648
	s_waitcnt lgkmcnt(0)
	v_mfma_f32_16x16x32_bf16 v[16:19], v[16:19], v[152:155], v[20:23]
	s_nop 7
	v_mfma_f32_16x16x32_bf16 v[20:23], v[24:27], v[152:155], v[28:31]
	s_nop 7
	v_max3_f32 v24, v16, v17, v18
	v_max3_f32 v25, v19, v20, v21
	v_max3_f32 v24, v24, v22, v23
	v_max_f32_e32 v24, v24, v25
	v_add_f32_e32 v25, 0x41000000, v168
	v_cmp_gt_f32_e32 vcc, v24, v25
	s_cbranch_vccz .LBB0_390
	v_mov_b32_e32 v25, v24
	s_nop 1
	v_permlane16_swap_b32 v24, v25
	s_nop 0
	v_max_f32_e32 v25, v25, v25
	v_max_f32_e32 v24, v24, v24
	v_max_f32_e32 v24, v24, v25
	v_mov_b32_e32 v25, v24
	s_nop 1
	v_permlane32_swap_b32 v24, v25
	s_nop 0
	v_max3_f32 v25, v168, v24, v25
	v_sub_f32_e32 v24, v168, v25
	v_exp_f32_e32 v24, v24
	v_mov_b32_e32 v168, v25
	v_pk_mul_f32 v[86:87], v[86:87], v[24:25] op_sel_hi:[1,0]
	v_pk_mul_f32 v[84:85], v[84:85], v[24:25] op_sel_hi:[1,0]
	v_pk_mul_f32 v[82:83], v[82:83], v[24:25] op_sel_hi:[1,0]
	v_pk_mul_f32 v[80:81], v[80:81], v[24:25] op_sel_hi:[1,0]
	v_pk_mul_f32 v[78:79], v[78:79], v[24:25] op_sel_hi:[1,0]
	v_pk_mul_f32 v[76:77], v[76:77], v[24:25] op_sel_hi:[1,0]
	v_pk_mul_f32 v[74:75], v[74:75], v[24:25] op_sel_hi:[1,0]
	v_pk_mul_f32 v[72:73], v[72:73], v[24:25] op_sel_hi:[1,0]
	v_pk_mul_f32 v[90:91], v[90:91], v[24:25] op_sel_hi:[1,0]
	v_pk_mul_f32 v[88:89], v[88:89], v[24:25] op_sel_hi:[1,0]
.LBB0_390:
	v_sub_f32_e32 v16, v16, v168
	v_sub_f32_e32 v17, v17, v168
	v_sub_f32_e32 v18, v18, v168
	v_sub_f32_e32 v19, v19, v168
	v_sub_f32_e32 v20, v20, v168
	v_sub_f32_e32 v21, v21, v168
	v_sub_f32_e32 v22, v22, v168
	v_sub_f32_e32 v23, v23, v168
	v_exp_f32_e32 v16, v16
	v_exp_f32_e32 v17, v17
	v_exp_f32_e32 v18, v18
	v_exp_f32_e32 v19, v19
	v_exp_f32_e32 v20, v20
	v_exp_f32_e32 v21, v21
	v_exp_f32_e32 v22, v22
	v_exp_f32_e32 v23, v23
	v_cvt_pk_bf16_f32 v16, v16, v17
	v_cvt_pk_bf16_f32 v17, v18, v19
	v_cvt_pk_bf16_f32 v18, v20, v21
	v_cvt_pk_bf16_f32 v19, v22, v23
	s_add_i32 s30, s25, -2
	s_nop 0
	v_mfma_f32_16x16x32_bf16 v[84:87], v[0:3], v[16:19], v[84:87]
	v_mfma_f32_16x16x32_bf16 v[80:83], v[4:7], v[16:19], v[80:83]
	v_mfma_f32_16x16x32_bf16 v[76:79], v[8:11], v[16:19], v[76:79]
	v_mfma_f32_16x16x32_bf16 v[72:75], v[12:15], v[16:19], v[72:75]
	v_mfma_f32_16x16x32_bf16 v[88:91], v[36:39], v[16:19], v[88:91]
	s_cmp_lt_u32 s30, 6
	s_cselect_b32 s0, s25, 0
	s_add_i32 s40, s0, s60
	ds_read_b128 v[8:11], v167 offset:20480
	s_lshl_b32 s0, s40, 1
	s_lshl_b64 s[42:43], s[0:1], 14
	v_lshl_add_u64 v[4:5], v[162:163], 0, s[42:43]
	global_load_dwordx4 v[20:23], v[4:5], off
	global_load_dwordx4 v[16:19], v[4:5], off offset:1024
	ds_read_b128 v[156:159], v167 offset:21504
	s_waitcnt vmcnt(9) lgkmcnt(1)
	v_mfma_f32_16x16x32_bf16 v[0:3], v[64:67], v[8:11], 0
	s_mov_b32 s41, s1
	v_add_co_u32_e32 v4, vcc, s72, v4
	s_lshl_b64 s[40:41], s[40:41], 15
	s_nop 0
	v_addc_co_u32_e32 v5, vcc, 0, v5, vcc
	v_lshl_add_u64 v[12:13], v[164:165], 0, s[40:41]
	s_waitcnt vmcnt(8) lgkmcnt(0)
	v_mfma_f32_16x16x32_bf16 v[152:155], v[60:63], v[156:159], v[0:3]
	global_load_dwordx4 v[28:31], v[4:5], off
	global_load_dwordx4 v[24:27], v[4:5], off offset:1024
	s_nop 0
	global_load_dwordx4 v[0:3], v[12:13], off
	global_load_dwordx4 v[4:7], v[12:13], off offset:1024
	s_nop 2
	s_waitcnt vmcnt(11)
	v_mfma_f32_16x16x32_bf16 v[172:175], v[68:71], v[8:11], 0
	global_load_dwordx4 v[8:11], v[12:13], off offset:2048
	s_nop 0
	global_load_dwordx4 v[12:15], v[12:13], off offset:3072
	s_waitcnt vmcnt(12)
	v_mfma_f32_16x16x32_bf16 v[156:159], v[56:59], v[156:159], v[172:175]
	s_nop 4
	v_max3_f32 v32, v152, v153, v154
	s_nop 1
	v_max3_f32 v35, v155, v156, v157
	v_max3_f32 v32, v32, v158, v159
	v_max_f32_e32 v32, v32, v35
	v_add_f32_e32 v34, 0x41000000, v171
	v_cmp_gt_f32_e32 vcc, v32, v34
	s_cbranch_vccz .LBB0_392
	v_mov_b32_e32 v34, v32
	s_nop 1
	v_permlane16_swap_b32 v32, v34
	s_nop 0
	v_max_f32_e32 v34, v34, v34
	v_max_f32_e32 v32, v32, v32
	v_max_f32_e32 v32, v32, v34
	v_mov_b32_e32 v34, v32
	s_nop 1
	v_permlane32_swap_b32 v32, v34
	s_nop 0
	v_max3_f32 v34, v171, v32, v34
	v_sub_f32_e32 v32, v171, v34
	v_exp_f32_e32 v32, v32
	v_mov_b32_e32 v171, v34
	v_pk_mul_f32 v[146:147], v[146:147], v[32:33] op_sel_hi:[1,0]
	v_pk_mul_f32 v[144:145], v[144:145], v[32:33] op_sel_hi:[1,0]
	v_pk_mul_f32 v[142:143], v[142:143], v[32:33] op_sel_hi:[1,0]
	v_pk_mul_f32 v[140:141], v[140:141], v[32:33] op_sel_hi:[1,0]
	v_pk_mul_f32 v[138:139], v[138:139], v[32:33] op_sel_hi:[1,0]
	v_pk_mul_f32 v[136:137], v[136:137], v[32:33] op_sel_hi:[1,0]
	v_pk_mul_f32 v[134:135], v[134:135], v[32:33] op_sel_hi:[1,0]
	v_pk_mul_f32 v[132:133], v[132:133], v[32:33] op_sel_hi:[1,0]
	v_pk_mul_f32 v[150:151], v[150:151], v[32:33] op_sel_hi:[1,0]
	v_pk_mul_f32 v[148:149], v[148:149], v[32:33] op_sel_hi:[1,0]
.LBB0_392:
	v_sub_f32_e32 v35, v154, v171
	v_sub_f32_e32 v37, v155, v171
	v_sub_f32_e32 v38, v156, v171
	v_sub_f32_e32 v39, v157, v171
	v_exp_f32_e32 v35, v35
	v_exp_f32_e32 v37, v37
	v_exp_f32_e32 v38, v38
	v_exp_f32_e32 v39, v39
	v_sub_f32_e32 v32, v152, v171
	v_sub_f32_e32 v152, v158, v171
	v_sub_f32_e32 v34, v153, v171
	v_exp_f32_e32 v155, v152
	v_sub_f32_e32 v152, v159, v171
	v_exp_f32_e32 v32, v32
	v_exp_f32_e32 v34, v34
	v_exp_f32_e32 v156, v152
	v_cvt_pk_bf16_f32 v153, v35, v37
	v_cvt_pk_bf16_f32 v154, v38, v39
	v_mov_b32_e32 v37, v36
	v_mov_b32_e32 v38, v36
	v_mov_b32_e32 v39, v36
	v_cvt_pk_bf16_f32 v152, v32, v34
	v_cvt_pk_bf16_f32 v155, v155, v156
	s_waitcnt vmcnt(11)
	s_nop 0
	v_mfma_f32_16x16x32_bf16 v[144:147], v[40:43], v[152:155], v[144:147]
	s_waitcnt vmcnt(10)
	v_mfma_f32_16x16x32_bf16 v[140:143], v[44:47], v[152:155], v[140:143]
	s_waitcnt vmcnt(9)
	v_mfma_f32_16x16x32_bf16 v[136:139], v[48:51], v[152:155], v[136:139]
	s_waitcnt vmcnt(8)
	v_mfma_f32_16x16x32_bf16 v[132:135], v[52:55], v[152:155], v[132:135]
	v_mfma_f32_16x16x32_bf16 v[148:151], v[36:39], v[152:155], v[148:151]
	ds_read_b128 v[152:155], v167 offset:22528
	ds_read_b128 v[172:175], v167 offset:23552
	s_waitcnt lgkmcnt(1)
	v_mfma_f32_16x16x32_bf16 v[156:159], v[64:67], v[152:155], 0
	v_mfma_f32_16x16x32_bf16 v[152:155], v[68:71], v[152:155], 0
	s_waitcnt lgkmcnt(0)
	v_mfma_f32_16x16x32_bf16 v[156:159], v[60:63], v[172:175], v[156:159]
	v_mfma_f32_16x16x32_bf16 v[152:155], v[56:59], v[172:175], v[152:155]
	s_nop 6
	v_max3_f32 v32, v156, v157, v158
	v_max3_f32 v35, v159, v152, v153
	v_max3_f32 v32, v32, v154, v155
	v_max_f32_e32 v32, v32, v35
	v_add_f32_e32 v34, 0x41000000, v170
	v_cmp_gt_f32_e32 vcc, v32, v34
	s_cbranch_vccz .LBB0_394
	v_mov_b32_e32 v34, v32
	s_nop 1
	v_permlane16_swap_b32 v32, v34
	s_nop 0
	v_max_f32_e32 v34, v34, v34
	v_max_f32_e32 v32, v32, v32
	v_max_f32_e32 v32, v32, v34
	v_mov_b32_e32 v34, v32
	s_nop 1
	v_permlane32_swap_b32 v32, v34
	s_nop 0
	v_max3_f32 v34, v170, v32, v34
	v_sub_f32_e32 v32, v170, v34
	v_exp_f32_e32 v32, v32
	v_mov_b32_e32 v170, v34
	v_pk_mul_f32 v[126:127], v[126:127], v[32:33] op_sel_hi:[1,0]
	v_pk_mul_f32 v[124:125], v[124:125], v[32:33] op_sel_hi:[1,0]
	v_pk_mul_f32 v[122:123], v[122:123], v[32:33] op_sel_hi:[1,0]
	v_pk_mul_f32 v[120:121], v[120:121], v[32:33] op_sel_hi:[1,0]
	v_pk_mul_f32 v[118:119], v[118:119], v[32:33] op_sel_hi:[1,0]
	v_pk_mul_f32 v[116:117], v[116:117], v[32:33] op_sel_hi:[1,0]
	v_pk_mul_f32 v[114:115], v[114:115], v[32:33] op_sel_hi:[1,0]
	v_pk_mul_f32 v[112:113], v[112:113], v[32:33] op_sel_hi:[1,0]
	v_pk_mul_f32 v[130:131], v[130:131], v[32:33] op_sel_hi:[1,0]
	v_pk_mul_f32 v[128:129], v[128:129], v[32:33] op_sel_hi:[1,0]
.LBB0_394:
	v_sub_f32_e32 v152, v152, v170
	v_sub_f32_e32 v34, v157, v170
	v_exp_f32_e32 v157, v152
	v_sub_f32_e32 v152, v153, v170
	v_sub_f32_e32 v35, v158, v170
	v_exp_f32_e32 v158, v152
	v_sub_f32_e32 v152, v154, v170
	v_sub_f32_e32 v32, v156, v170
	v_sub_f32_e32 v156, v159, v170
	v_exp_f32_e32 v159, v152
	v_sub_f32_e32 v152, v155, v170
	v_exp_f32_e32 v32, v32
	v_exp_f32_e32 v34, v34
	v_exp_f32_e32 v35, v35
	v_exp_f32_e32 v156, v156
	v_exp_f32_e32 v155, v152
	v_cvt_pk_bf16_f32 v152, v32, v34
	v_cvt_pk_bf16_f32 v154, v157, v158
	v_cvt_pk_bf16_f32 v153, v35, v156
	v_cvt_pk_bf16_f32 v155, v159, v155
	s_nop 1
	v_mfma_f32_16x16x32_bf16 v[124:127], v[40:43], v[152:155], v[124:127]
	v_mfma_f32_16x16x32_bf16 v[120:123], v[44:47], v[152:155], v[120:123]
	v_mfma_f32_16x16x32_bf16 v[116:119], v[48:51], v[152:155], v[116:119]
	v_mfma_f32_16x16x32_bf16 v[112:115], v[52:55], v[152:155], v[112:115]
	v_mfma_f32_16x16x32_bf16 v[128:131], v[36:39], v[152:155], v[128:131]
	ds_read_b128 v[152:155], v167 offset:24576
	ds_read_b128 v[172:175], v167 offset:25600
	s_waitcnt lgkmcnt(1)
	v_mfma_f32_16x16x32_bf16 v[156:159], v[64:67], v[152:155], 0
	v_mfma_f32_16x16x32_bf16 v[152:155], v[68:71], v[152:155], 0
	s_waitcnt lgkmcnt(0)
	v_mfma_f32_16x16x32_bf16 v[156:159], v[60:63], v[172:175], v[156:159]
	v_mfma_f32_16x16x32_bf16 v[152:155], v[56:59], v[172:175], v[152:155]
	s_nop 6
	v_max3_f32 v32, v156, v157, v158
	v_max3_f32 v35, v159, v152, v153
	v_max3_f32 v32, v32, v154, v155
	v_max_f32_e32 v32, v32, v35
	v_add_f32_e32 v34, 0x41000000, v169
	v_cmp_gt_f32_e32 vcc, v32, v34
	s_cbranch_vccz .LBB0_396
	v_mov_b32_e32 v34, v32
	s_nop 1
	v_permlane16_swap_b32 v32, v34
	s_nop 0
	v_max_f32_e32 v34, v34, v34
	v_max_f32_e32 v32, v32, v32
	v_max_f32_e32 v32, v32, v34
	v_mov_b32_e32 v34, v32
	s_nop 1
	v_permlane32_swap_b32 v34, v32
	s_nop 0
	v_max3_f32 v34, v169, v34, v32
	v_sub_f32_e32 v32, v169, v34
	v_exp_f32_e32 v32, v32
	v_mov_b32_e32 v169, v34
	v_pk_mul_f32 v[106:107], v[106:107], v[32:33] op_sel_hi:[1,0]
	v_pk_mul_f32 v[104:105], v[104:105], v[32:33] op_sel_hi:[1,0]
	v_pk_mul_f32 v[102:103], v[102:103], v[32:33] op_sel_hi:[1,0]
	v_pk_mul_f32 v[100:101], v[100:101], v[32:33] op_sel_hi:[1,0]
	v_pk_mul_f32 v[98:99], v[98:99], v[32:33] op_sel_hi:[1,0]
	v_pk_mul_f32 v[96:97], v[96:97], v[32:33] op_sel_hi:[1,0]
	v_pk_mul_f32 v[94:95], v[94:95], v[32:33] op_sel_hi:[1,0]
	v_pk_mul_f32 v[92:93], v[92:93], v[32:33] op_sel_hi:[1,0]
	v_pk_mul_f32 v[110:111], v[110:111], v[32:33] op_sel_hi:[1,0]
	v_pk_mul_f32 v[108:109], v[108:109], v[32:33] op_sel_hi:[1,0]
.LBB0_396:
	v_sub_f32_e32 v35, v158, v169
	v_sub_f32_e32 v37, v159, v169
	v_sub_f32_e32 v38, v152, v169
	v_sub_f32_e32 v39, v153, v169
	v_exp_f32_e32 v35, v35
	v_exp_f32_e32 v37, v37
	v_exp_f32_e32 v38, v38
	v_exp_f32_e32 v39, v39
	v_sub_f32_e32 v152, v154, v169
	v_sub_f32_e32 v32, v156, v169
	v_sub_f32_e32 v34, v157, v169
	v_exp_f32_e32 v156, v152
	v_sub_f32_e32 v152, v155, v169
	v_exp_f32_e32 v32, v32
	v_exp_f32_e32 v34, v34
	v_exp_f32_e32 v155, v152
	v_cvt_pk_bf16_f32 v153, v35, v37
	v_cvt_pk_bf16_f32 v154, v38, v39
	v_mov_b32_e32 v37, v36
	v_mov_b32_e32 v38, v36
	v_mov_b32_e32 v39, v36
	v_cvt_pk_bf16_f32 v152, v32, v34
	v_cvt_pk_bf16_f32 v155, v156, v155
	s_nop 1
	v_mfma_f32_16x16x32_bf16 v[104:107], v[40:43], v[152:155], v[104:107]
	v_mfma_f32_16x16x32_bf16 v[100:103], v[44:47], v[152:155], v[100:103]
	v_mfma_f32_16x16x32_bf16 v[96:99], v[48:51], v[152:155], v[96:99]
	v_mfma_f32_16x16x32_bf16 v[92:95], v[52:55], v[152:155], v[92:95]
	v_mfma_f32_16x16x32_bf16 v[108:111], v[36:39], v[152:155], v[108:111]
	ds_read_b128 v[152:155], v167 offset:26624
	s_waitcnt lgkmcnt(0)
	v_mfma_f32_16x16x32_bf16 v[64:67], v[64:67], v[152:155], 0
	v_mfma_f32_16x16x32_bf16 v[68:71], v[68:71], v[152:155], 0
	ds_read_b128 v[152:155], v167 offset:27648
	s_waitcnt lgkmcnt(0)
	v_mfma_f32_16x16x32_bf16 v[60:63], v[60:63], v[152:155], v[64:67]
	v_mfma_f32_16x16x32_bf16 v[56:59], v[56:59], v[152:155], v[68:71]
	s_nop 6
	v_max3_f32 v32, v60, v61, v62
	v_max3_f32 v35, v63, v56, v57
	v_max3_f32 v32, v32, v58, v59
	v_max_f32_e32 v32, v32, v35
	v_add_f32_e32 v34, 0x41000000, v168
	v_cmp_gt_f32_e32 vcc, v32, v34
	s_cbranch_vccz .LBB0_381
	v_mov_b32_e32 v34, v32
	s_nop 1
	v_permlane16_swap_b32 v32, v34
	s_nop 0
	v_max_f32_e32 v34, v34, v34
	v_max_f32_e32 v32, v32, v32
	v_max_f32_e32 v32, v32, v34
	v_mov_b32_e32 v34, v32
	s_nop 1
	v_permlane32_swap_b32 v32, v34
	s_nop 0
	v_max3_f32 v34, v168, v32, v34
	v_sub_f32_e32 v32, v168, v34
	v_exp_f32_e32 v32, v32
	v_mov_b32_e32 v168, v34
	v_pk_mul_f32 v[86:87], v[86:87], v[32:33] op_sel_hi:[1,0]
	v_pk_mul_f32 v[84:85], v[84:85], v[32:33] op_sel_hi:[1,0]
	v_pk_mul_f32 v[82:83], v[82:83], v[32:33] op_sel_hi:[1,0]
	v_pk_mul_f32 v[80:81], v[80:81], v[32:33] op_sel_hi:[1,0]
	v_pk_mul_f32 v[78:79], v[78:79], v[32:33] op_sel_hi:[1,0]
	v_pk_mul_f32 v[76:77], v[76:77], v[32:33] op_sel_hi:[1,0]
	v_pk_mul_f32 v[74:75], v[74:75], v[32:33] op_sel_hi:[1,0]
	v_pk_mul_f32 v[72:73], v[72:73], v[32:33] op_sel_hi:[1,0]
	v_pk_mul_f32 v[90:91], v[90:91], v[32:33] op_sel_hi:[1,0]
	v_pk_mul_f32 v[88:89], v[88:89], v[32:33] op_sel_hi:[1,0]
	s_branch .LBB0_381
